# hand-written staged epilogue for pool G1 phases (ph2, ph17): in-place silu, LDS transpose, row-contiguous stores
# speedup vs baseline: 1.0149x; 1.0149x over previous
.Lgm_ph2_loop:
	s_waitcnt lgkmcnt(1)
	v_mfma_f32_32x32x16_bf16 v[82:97], v[240:243], v[252:255], v[82:97]
	ds_read_b128 v[220:223], v210 offset:0
	s_add_u32 m0, s81, 0x5000
	s_nop 0
	global_load_lds_dwordx4 v202, s[70:71]
	v_mfma_f32_32x32x16_bf16 v[66:81], v[236:239], v[252:255], v[66:81]
	ds_read_b128 v[232:235], v214 offset:0
	s_add_u32 m0, s82, 0x0
	s_nop 0
	global_load_lds_dwordx4 v207, s[72:73]
	v_mfma_f32_32x32x16_bf16 v[50:65], v[240:243], v[248:251], v[50:65]
	ds_read_b128 v[216:219], v210 offset:4096
	s_add_u32 m0, s82, 0x1000
	s_nop 0
	global_load_lds_dwordx4 v206, s[72:73]
	v_mfma_f32_32x32x16_bf16 v[34:49], v[236:239], v[248:251], v[34:49]
	ds_read_b128 v[228:231], v214 offset:4096
	s_add_u32 m0, s82, 0x2000
	s_nop 0
	global_load_lds_dwordx4 v205, s[72:73]
	s_waitcnt lgkmcnt(4)
	v_mfma_f32_32x32x16_bf16 v[18:33], v[240:243], v[244:247], v[18:33]
	ds_read_b128 v[224:227], v214 offset:8192
	v_mfma_f32_32x32x16_bf16 v[2:17], v[236:239], v[244:247], v[2:17]
	s_add_u32 m0, s82, 0x3000
	s_nop 0
	global_load_lds_dwordx4 v204, s[72:73]
	s_waitcnt lgkmcnt(1)
	v_mfma_f32_32x32x16_bf16 v[82:97], v[220:223], v[232:235], v[82:97]
	ds_read_b128 v[240:243], v209 offset:0
	v_mfma_f32_32x32x16_bf16 v[66:81], v[216:219], v[232:235], v[66:81]
	ds_read_b128 v[252:255], v213 offset:0
	v_mfma_f32_32x32x16_bf16 v[50:65], v[220:223], v[228:231], v[50:65]
	ds_read_b128 v[236:239], v209 offset:4096
	v_mfma_f32_32x32x16_bf16 v[34:49], v[216:219], v[228:231], v[34:49]
	ds_read_b128 v[248:251], v213 offset:4096
	s_waitcnt lgkmcnt(4)
	v_mfma_f32_32x32x16_bf16 v[18:33], v[220:223], v[224:227], v[18:33]
	ds_read_b128 v[244:247], v213 offset:8192
	v_mfma_f32_32x32x16_bf16 v[2:17], v[216:219], v[224:227], v[2:17]
	s_waitcnt lgkmcnt(1)
	v_mfma_f32_32x32x16_bf16 v[82:97], v[240:243], v[252:255], v[82:97]
	ds_read_b128 v[220:223], v208 offset:0
	s_add_u32 s83, s79, s78
	s_add_u32 s83, s83, 2
	s_and_b32 s83, s83, 15
	v_mfma_f32_32x32x16_bf16 v[66:81], v[236:239], v[252:255], v[66:81]
	ds_read_b128 v[232:235], v212 offset:0
	s_lshl_b32 s83, s83, 7
	s_add_u32 s70, s66, s83
	v_mfma_f32_32x32x16_bf16 v[50:65], v[240:243], v[248:251], v[50:65]
	ds_read_b128 v[216:219], v208 offset:4096
	s_addc_u32 s71, s67, 0
	s_add_u32 s72, s68, s83
	v_mfma_f32_32x32x16_bf16 v[34:49], v[236:239], v[248:251], v[34:49]
	ds_read_b128 v[228:231], v212 offset:4096
	s_addc_u32 s73, s69, 0
	s_add_u32 s81, s80, 0x0
	s_add_u32 s82, s80, 0xc000
	s_waitcnt lgkmcnt(4)
	v_mfma_f32_32x32x16_bf16 v[18:33], v[240:243], v[244:247], v[18:33]
	ds_read_b128 v[224:227], v212 offset:8192
	v_mfma_f32_32x32x16_bf16 v[2:17], v[236:239], v[244:247], v[2:17]
	s_waitcnt vmcnt(0) lgkmcnt(0)
	s_barrier
	v_mfma_f32_32x32x16_bf16 v[82:97], v[220:223], v[232:235], v[82:97]
	s_add_u32 m0, s81, 0x0
	ds_read_b128 v[240:243], v211 offset:16384
	global_load_lds_dwordx4 v207, s[70:71]
	v_mfma_f32_32x32x16_bf16 v[66:81], v[216:219], v[232:235], v[66:81]
	s_add_u32 m0, s81, 0x1000
	ds_read_b128 v[252:255], v215 offset:24576
	global_load_lds_dwordx4 v206, s[70:71]
	v_mfma_f32_32x32x16_bf16 v[50:65], v[220:223], v[228:231], v[50:65]
	s_add_u32 m0, s81, 0x2000
	ds_read_b128 v[236:239], v211 offset:20480
	global_load_lds_dwordx4 v205, s[70:71]
	v_mfma_f32_32x32x16_bf16 v[34:49], v[216:219], v[228:231], v[34:49]
	s_add_u32 m0, s81, 0x3000
	ds_read_b128 v[248:251], v215 offset:28672
	global_load_lds_dwordx4 v204, s[70:71]
	v_mfma_f32_32x32x16_bf16 v[18:33], v[220:223], v[224:227], v[18:33]
	s_add_u32 m0, s81, 0x4000
	ds_read_b128 v[244:247], v215 offset:32768
	global_load_lds_dwordx4 v203, s[70:71]
	v_mfma_f32_32x32x16_bf16 v[2:17], v[216:219], v[224:227], v[2:17]
	s_waitcnt lgkmcnt(1)
	v_mfma_f32_32x32x16_bf16 v[82:97], v[240:243], v[252:255], v[82:97]
	ds_read_b128 v[220:223], v210 offset:16384
	s_add_u32 m0, s81, 0x5000
	s_nop 0
	global_load_lds_dwordx4 v202, s[70:71]
	v_mfma_f32_32x32x16_bf16 v[66:81], v[236:239], v[252:255], v[66:81]
	ds_read_b128 v[232:235], v214 offset:24576
	s_add_u32 m0, s82, 0x0
	s_nop 0
	global_load_lds_dwordx4 v207, s[72:73]
	v_mfma_f32_32x32x16_bf16 v[50:65], v[240:243], v[248:251], v[50:65]
	ds_read_b128 v[216:219], v210 offset:20480
	s_add_u32 m0, s82, 0x1000
	s_nop 0
	global_load_lds_dwordx4 v206, s[72:73]
	v_mfma_f32_32x32x16_bf16 v[34:49], v[236:239], v[248:251], v[34:49]
	ds_read_b128 v[228:231], v214 offset:28672
	s_add_u32 m0, s82, 0x2000
	s_nop 0
	global_load_lds_dwordx4 v205, s[72:73]
	s_waitcnt lgkmcnt(4)
	v_mfma_f32_32x32x16_bf16 v[18:33], v[240:243], v[244:247], v[18:33]
	ds_read_b128 v[224:227], v214 offset:32768
	v_mfma_f32_32x32x16_bf16 v[2:17], v[236:239], v[244:247], v[2:17]
	s_add_u32 m0, s82, 0x3000
	s_nop 0
	global_load_lds_dwordx4 v204, s[72:73]
	s_waitcnt lgkmcnt(1)
	v_mfma_f32_32x32x16_bf16 v[82:97], v[220:223], v[232:235], v[82:97]
	ds_read_b128 v[240:243], v209 offset:16384
	v_mfma_f32_32x32x16_bf16 v[66:81], v[216:219], v[232:235], v[66:81]
	ds_read_b128 v[252:255], v213 offset:24576
	v_mfma_f32_32x32x16_bf16 v[50:65], v[220:223], v[228:231], v[50:65]
	ds_read_b128 v[236:239], v209 offset:20480
	v_mfma_f32_32x32x16_bf16 v[34:49], v[216:219], v[228:231], v[34:49]
	ds_read_b128 v[248:251], v213 offset:28672
	s_waitcnt lgkmcnt(4)
	v_mfma_f32_32x32x16_bf16 v[18:33], v[220:223], v[224:227], v[18:33]
	ds_read_b128 v[244:247], v213 offset:32768
	v_mfma_f32_32x32x16_bf16 v[2:17], v[216:219], v[224:227], v[2:17]
	s_waitcnt lgkmcnt(1)
	v_mfma_f32_32x32x16_bf16 v[82:97], v[240:243], v[252:255], v[82:97]
	ds_read_b128 v[220:223], v208 offset:16384
	s_add_u32 s83, s79, s78
	s_add_u32 s83, s83, 3
	s_and_b32 s83, s83, 15
	v_mfma_f32_32x32x16_bf16 v[66:81], v[236:239], v[252:255], v[66:81]
	ds_read_b128 v[232:235], v212 offset:24576
	s_lshl_b32 s83, s83, 7
	s_add_u32 s70, s66, s83
	v_mfma_f32_32x32x16_bf16 v[50:65], v[240:243], v[248:251], v[50:65]
	ds_read_b128 v[216:219], v208 offset:20480
	s_addc_u32 s71, s67, 0
	s_add_u32 s72, s68, s83
	v_mfma_f32_32x32x16_bf16 v[34:49], v[236:239], v[248:251], v[34:49]
	ds_read_b128 v[228:231], v212 offset:28672
	s_addc_u32 s73, s69, 0
	s_add_u32 s81, s80, 0x6000
	s_add_u32 s82, s80, 0x10000
	s_waitcnt lgkmcnt(4)
	v_mfma_f32_32x32x16_bf16 v[18:33], v[240:243], v[244:247], v[18:33]
	ds_read_b128 v[224:227], v212 offset:32768
	v_mfma_f32_32x32x16_bf16 v[2:17], v[236:239], v[244:247], v[2:17]
	s_waitcnt vmcnt(0) lgkmcnt(0)
	s_barrier
	v_mfma_f32_32x32x16_bf16 v[82:97], v[220:223], v[232:235], v[82:97]
	s_add_u32 m0, s81, 0x0
	ds_read_b128 v[240:243], v211 offset:0
	global_load_lds_dwordx4 v207, s[70:71]
	v_mfma_f32_32x32x16_bf16 v[66:81], v[216:219], v[232:235], v[66:81]
	s_add_u32 m0, s81, 0x1000
	ds_read_b128 v[252:255], v215 offset:0
	global_load_lds_dwordx4 v206, s[70:71]
	v_mfma_f32_32x32x16_bf16 v[50:65], v[220:223], v[228:231], v[50:65]
	s_add_u32 m0, s81, 0x2000
	ds_read_b128 v[236:239], v211 offset:4096
	global_load_lds_dwordx4 v205, s[70:71]
	v_mfma_f32_32x32x16_bf16 v[34:49], v[216:219], v[228:231], v[34:49]
	s_add_u32 m0, s81, 0x3000
	ds_read_b128 v[248:251], v215 offset:4096
	global_load_lds_dwordx4 v204, s[70:71]
	v_mfma_f32_32x32x16_bf16 v[18:33], v[220:223], v[224:227], v[18:33]
	s_add_u32 m0, s81, 0x4000
	ds_read_b128 v[244:247], v215 offset:8192
	global_load_lds_dwordx4 v203, s[70:71]
	v_mfma_f32_32x32x16_bf16 v[2:17], v[216:219], v[224:227], v[2:17]
	s_add_u32 s78, s78, 2
	s_cmp_lt_u32 s78, 14
	s_cbranch_scc1 .Lgm_ph2_loop
	s_waitcnt lgkmcnt(1)
	v_mfma_f32_32x32x16_bf16 v[82:97], v[240:243], v[252:255], v[82:97]
	ds_read_b128 v[220:223], v210 offset:0
	s_add_u32 m0, s81, 0x5000
	s_nop 0
	global_load_lds_dwordx4 v202, s[70:71]
	v_mfma_f32_32x32x16_bf16 v[66:81], v[236:239], v[252:255], v[66:81]
	ds_read_b128 v[232:235], v214 offset:0
	s_add_u32 m0, s82, 0x0
	s_nop 0
	global_load_lds_dwordx4 v207, s[72:73]
	v_mfma_f32_32x32x16_bf16 v[50:65], v[240:243], v[248:251], v[50:65]
	ds_read_b128 v[216:219], v210 offset:4096
	s_add_u32 m0, s82, 0x1000
	s_nop 0
	global_load_lds_dwordx4 v206, s[72:73]
	v_mfma_f32_32x32x16_bf16 v[34:49], v[236:239], v[248:251], v[34:49]
	ds_read_b128 v[228:231], v214 offset:4096
	s_add_u32 m0, s82, 0x2000
	s_nop 0
	global_load_lds_dwordx4 v205, s[72:73]
	s_waitcnt lgkmcnt(4)
	v_mfma_f32_32x32x16_bf16 v[18:33], v[240:243], v[244:247], v[18:33]
	ds_read_b128 v[224:227], v214 offset:8192
	v_mfma_f32_32x32x16_bf16 v[2:17], v[236:239], v[244:247], v[2:17]
	s_add_u32 m0, s82, 0x3000
	s_nop 0
	global_load_lds_dwordx4 v204, s[72:73]
	s_waitcnt lgkmcnt(1)
	v_mfma_f32_32x32x16_bf16 v[82:97], v[220:223], v[232:235], v[82:97]
	ds_read_b128 v[240:243], v209 offset:0
	v_mfma_f32_32x32x16_bf16 v[66:81], v[216:219], v[232:235], v[66:81]
	ds_read_b128 v[252:255], v213 offset:0
	v_mfma_f32_32x32x16_bf16 v[50:65], v[220:223], v[228:231], v[50:65]
	ds_read_b128 v[236:239], v209 offset:4096
	v_mfma_f32_32x32x16_bf16 v[34:49], v[216:219], v[228:231], v[34:49]
	ds_read_b128 v[248:251], v213 offset:4096
	s_waitcnt lgkmcnt(4)
	v_mfma_f32_32x32x16_bf16 v[18:33], v[220:223], v[224:227], v[18:33]
	ds_read_b128 v[244:247], v213 offset:8192
	v_mfma_f32_32x32x16_bf16 v[2:17], v[216:219], v[224:227], v[2:17]
	s_waitcnt lgkmcnt(1)
	v_mfma_f32_32x32x16_bf16 v[82:97], v[240:243], v[252:255], v[82:97]
	ds_read_b128 v[220:223], v208 offset:0
	v_mfma_f32_32x32x16_bf16 v[66:81], v[236:239], v[252:255], v[66:81]
	ds_read_b128 v[232:235], v212 offset:0
	v_mfma_f32_32x32x16_bf16 v[50:65], v[240:243], v[248:251], v[50:65]
	ds_read_b128 v[216:219], v208 offset:4096
	v_mfma_f32_32x32x16_bf16 v[34:49], v[236:239], v[248:251], v[34:49]
	ds_read_b128 v[228:231], v212 offset:4096
	s_waitcnt lgkmcnt(4)
	v_mfma_f32_32x32x16_bf16 v[18:33], v[240:243], v[244:247], v[18:33]
	ds_read_b128 v[224:227], v212 offset:8192
	v_mfma_f32_32x32x16_bf16 v[2:17], v[236:239], v[244:247], v[2:17]
	s_waitcnt vmcnt(0) lgkmcnt(0)
	s_barrier
	v_mfma_f32_32x32x16_bf16 v[82:97], v[220:223], v[232:235], v[82:97]
	ds_read_b128 v[240:243], v211 offset:16384
	v_mfma_f32_32x32x16_bf16 v[66:81], v[216:219], v[232:235], v[66:81]
	ds_read_b128 v[252:255], v215 offset:24576
	v_mfma_f32_32x32x16_bf16 v[50:65], v[220:223], v[228:231], v[50:65]
	ds_read_b128 v[236:239], v211 offset:20480
	v_mfma_f32_32x32x16_bf16 v[34:49], v[216:219], v[228:231], v[34:49]
	ds_read_b128 v[248:251], v215 offset:28672
	v_mfma_f32_32x32x16_bf16 v[18:33], v[220:223], v[224:227], v[18:33]
	ds_read_b128 v[244:247], v215 offset:32768
	v_mfma_f32_32x32x16_bf16 v[2:17], v[216:219], v[224:227], v[2:17]
	s_waitcnt lgkmcnt(1)
	v_mfma_f32_32x32x16_bf16 v[82:97], v[240:243], v[252:255], v[82:97]
	ds_read_b128 v[220:223], v210 offset:16384
	v_mfma_f32_32x32x16_bf16 v[66:81], v[236:239], v[252:255], v[66:81]
	ds_read_b128 v[232:235], v214 offset:24576
	v_mfma_f32_32x32x16_bf16 v[50:65], v[240:243], v[248:251], v[50:65]
	ds_read_b128 v[216:219], v210 offset:20480
	v_mfma_f32_32x32x16_bf16 v[34:49], v[236:239], v[248:251], v[34:49]
	ds_read_b128 v[228:231], v214 offset:28672
	s_waitcnt lgkmcnt(4)
	v_mfma_f32_32x32x16_bf16 v[18:33], v[240:243], v[244:247], v[18:33]
	ds_read_b128 v[224:227], v214 offset:32768
	v_mfma_f32_32x32x16_bf16 v[2:17], v[236:239], v[244:247], v[2:17]
	s_waitcnt lgkmcnt(1)
	v_mfma_f32_32x32x16_bf16 v[82:97], v[220:223], v[232:235], v[82:97]
	ds_read_b128 v[240:243], v209 offset:16384
	v_mfma_f32_32x32x16_bf16 v[66:81], v[216:219], v[232:235], v[66:81]
	ds_read_b128 v[252:255], v213 offset:24576
	v_mfma_f32_32x32x16_bf16 v[50:65], v[220:223], v[228:231], v[50:65]
	ds_read_b128 v[236:239], v209 offset:20480
	v_mfma_f32_32x32x16_bf16 v[34:49], v[216:219], v[228:231], v[34:49]
	ds_read_b128 v[248:251], v213 offset:28672
	s_waitcnt lgkmcnt(4)
	v_mfma_f32_32x32x16_bf16 v[18:33], v[220:223], v[224:227], v[18:33]
	ds_read_b128 v[244:247], v213 offset:32768
	v_mfma_f32_32x32x16_bf16 v[2:17], v[216:219], v[224:227], v[2:17]
	s_waitcnt lgkmcnt(1)
	v_mfma_f32_32x32x16_bf16 v[82:97], v[240:243], v[252:255], v[82:97]
	ds_read_b128 v[220:223], v208 offset:16384
	v_mfma_f32_32x32x16_bf16 v[66:81], v[236:239], v[252:255], v[66:81]
	ds_read_b128 v[232:235], v212 offset:24576
	v_mfma_f32_32x32x16_bf16 v[50:65], v[240:243], v[248:251], v[50:65]
	ds_read_b128 v[216:219], v208 offset:20480
	v_mfma_f32_32x32x16_bf16 v[34:49], v[236:239], v[248:251], v[34:49]
	ds_read_b128 v[228:231], v212 offset:28672
	s_waitcnt lgkmcnt(4)
	v_mfma_f32_32x32x16_bf16 v[18:33], v[240:243], v[244:247], v[18:33]
	ds_read_b128 v[224:227], v212 offset:32768
	v_mfma_f32_32x32x16_bf16 v[2:17], v[236:239], v[244:247], v[2:17]
	s_waitcnt vmcnt(0) lgkmcnt(0)
	s_barrier
	v_mfma_f32_32x32x16_bf16 v[82:97], v[220:223], v[232:235], v[82:97]
	v_mfma_f32_32x32x16_bf16 v[66:81], v[216:219], v[232:235], v[66:81]
	v_mfma_f32_32x32x16_bf16 v[50:65], v[220:223], v[228:231], v[50:65]
	v_mfma_f32_32x32x16_bf16 v[34:49], v[216:219], v[228:231], v[34:49]
	v_mfma_f32_32x32x16_bf16 v[18:33], v[220:223], v[224:227], v[18:33]
	v_mfma_f32_32x32x16_bf16 v[2:17], v[216:219], v[224:227], v[2:17]
	s_nop 7
	s_nop 7
	s_setprio 0
	s_cmpk_lt_i32 s35, 0x200
	s_cbranch_scc1 G1E_ph2_U
	s_load_dwordx2 s[82:83], s[0:1], 0x98
	v_mul_f32_e32 v198, 0xbfb8aa3b, v2
	v_mul_f32_e32 v199, 0xbfb8aa3b, v3
	v_mul_f32_e32 v200, 0xbfb8aa3b, v4
	v_mul_f32_e32 v201, 0xbfb8aa3b, v5
	v_exp_f32_e32 v198, v198
	v_exp_f32_e32 v199, v199
	v_exp_f32_e32 v200, v200
	v_exp_f32_e32 v201, v201
	s_nop 0
	v_add_f32_e32 v198, 1.0, v198
	v_add_f32_e32 v199, 1.0, v199
	v_add_f32_e32 v200, 1.0, v200
	v_add_f32_e32 v201, 1.0, v201
	v_div_scale_f32 v202, s[84:85], v198, v198, v2
	v_div_scale_f32 v203, s[84:85], v199, v199, v3
	v_div_scale_f32 v204, s[84:85], v200, v200, v4
	v_div_scale_f32 v205, s[84:85], v201, v201, v5
	v_rcp_f32_e32 v206, v202
	v_rcp_f32_e32 v207, v203
	v_rcp_f32_e32 v208, v204
	v_rcp_f32_e32 v209, v205
	s_nop 0
	v_div_scale_f32 v210, vcc, v2, v198, v2
	v_fma_f32 v212, -v202, v206, 1.0
	v_fmac_f32_e32 v206, v212, v206
	v_mul_f32_e32 v211, v210, v206
	v_fma_f32 v212, -v202, v211, v210
	v_fmac_f32_e32 v211, v212, v206
	v_fma_f32 v212, -v202, v211, v210
	v_div_fmas_f32 v212, v212, v206, v211
	v_div_fixup_f32 v2, v212, v198, v2
	v_div_scale_f32 v210, vcc, v3, v199, v3
	v_fma_f32 v212, -v203, v207, 1.0
	v_fmac_f32_e32 v207, v212, v207
	v_mul_f32_e32 v211, v210, v207
	v_fma_f32 v212, -v203, v211, v210
	v_fmac_f32_e32 v211, v212, v207
	v_fma_f32 v212, -v203, v211, v210
	v_div_fmas_f32 v212, v212, v207, v211
	v_div_fixup_f32 v3, v212, v199, v3
	v_div_scale_f32 v210, vcc, v4, v200, v4
	v_fma_f32 v212, -v204, v208, 1.0
	v_fmac_f32_e32 v208, v212, v208
	v_mul_f32_e32 v211, v210, v208
	v_fma_f32 v212, -v204, v211, v210
	v_fmac_f32_e32 v211, v212, v208
	v_fma_f32 v212, -v204, v211, v210
	v_div_fmas_f32 v212, v212, v208, v211
	v_div_fixup_f32 v4, v212, v200, v4
	v_div_scale_f32 v210, vcc, v5, v201, v5
	v_fma_f32 v212, -v205, v209, 1.0
	v_fmac_f32_e32 v209, v212, v209
	v_mul_f32_e32 v211, v210, v209
	v_fma_f32 v212, -v205, v211, v210
	v_fmac_f32_e32 v211, v212, v209
	v_fma_f32 v212, -v205, v211, v210
	v_div_fmas_f32 v212, v212, v209, v211
	v_div_fixup_f32 v5, v212, v201, v5
	v_mul_f32_e32 v198, 0xbfb8aa3b, v6
	v_mul_f32_e32 v199, 0xbfb8aa3b, v7
	v_mul_f32_e32 v200, 0xbfb8aa3b, v8
	v_mul_f32_e32 v201, 0xbfb8aa3b, v9
	v_exp_f32_e32 v198, v198
	v_exp_f32_e32 v199, v199
	v_exp_f32_e32 v200, v200
	v_exp_f32_e32 v201, v201
	s_nop 0
	v_add_f32_e32 v198, 1.0, v198
	v_add_f32_e32 v199, 1.0, v199
	v_add_f32_e32 v200, 1.0, v200
	v_add_f32_e32 v201, 1.0, v201
	v_div_scale_f32 v202, s[84:85], v198, v198, v6
	v_div_scale_f32 v203, s[84:85], v199, v199, v7
	v_div_scale_f32 v204, s[84:85], v200, v200, v8
	v_div_scale_f32 v205, s[84:85], v201, v201, v9
	v_rcp_f32_e32 v206, v202
	v_rcp_f32_e32 v207, v203
	v_rcp_f32_e32 v208, v204
	v_rcp_f32_e32 v209, v205
	s_nop 0
	v_div_scale_f32 v210, vcc, v6, v198, v6
	v_fma_f32 v212, -v202, v206, 1.0
	v_fmac_f32_e32 v206, v212, v206
	v_mul_f32_e32 v211, v210, v206
	v_fma_f32 v212, -v202, v211, v210
	v_fmac_f32_e32 v211, v212, v206
	v_fma_f32 v212, -v202, v211, v210
	v_div_fmas_f32 v212, v212, v206, v211
	v_div_fixup_f32 v6, v212, v198, v6
	v_div_scale_f32 v210, vcc, v7, v199, v7
	v_fma_f32 v212, -v203, v207, 1.0
	v_fmac_f32_e32 v207, v212, v207
	v_mul_f32_e32 v211, v210, v207
	v_fma_f32 v212, -v203, v211, v210
	v_fmac_f32_e32 v211, v212, v207
	v_fma_f32 v212, -v203, v211, v210
	v_div_fmas_f32 v212, v212, v207, v211
	v_div_fixup_f32 v7, v212, v199, v7
	v_div_scale_f32 v210, vcc, v8, v200, v8
	v_fma_f32 v212, -v204, v208, 1.0
	v_fmac_f32_e32 v208, v212, v208
	v_mul_f32_e32 v211, v210, v208
	v_fma_f32 v212, -v204, v211, v210
	v_fmac_f32_e32 v211, v212, v208
	v_fma_f32 v212, -v204, v211, v210
	v_div_fmas_f32 v212, v212, v208, v211
	v_div_fixup_f32 v8, v212, v200, v8
	v_div_scale_f32 v210, vcc, v9, v201, v9
	v_fma_f32 v212, -v205, v209, 1.0
	v_fmac_f32_e32 v209, v212, v209
	v_mul_f32_e32 v211, v210, v209
	v_fma_f32 v212, -v205, v211, v210
	v_fmac_f32_e32 v211, v212, v209
	v_fma_f32 v212, -v205, v211, v210
	v_div_fmas_f32 v212, v212, v209, v211
	v_div_fixup_f32 v9, v212, v201, v9
	v_mul_f32_e32 v198, 0xbfb8aa3b, v10
	v_mul_f32_e32 v199, 0xbfb8aa3b, v11
	v_mul_f32_e32 v200, 0xbfb8aa3b, v12
	v_mul_f32_e32 v201, 0xbfb8aa3b, v13
	v_exp_f32_e32 v198, v198
	v_exp_f32_e32 v199, v199
	v_exp_f32_e32 v200, v200
	v_exp_f32_e32 v201, v201
	s_nop 0
	v_add_f32_e32 v198, 1.0, v198
	v_add_f32_e32 v199, 1.0, v199
	v_add_f32_e32 v200, 1.0, v200
	v_add_f32_e32 v201, 1.0, v201
	v_div_scale_f32 v202, s[84:85], v198, v198, v10
	v_div_scale_f32 v203, s[84:85], v199, v199, v11
	v_div_scale_f32 v204, s[84:85], v200, v200, v12
	v_div_scale_f32 v205, s[84:85], v201, v201, v13
	v_rcp_f32_e32 v206, v202
	v_rcp_f32_e32 v207, v203
	v_rcp_f32_e32 v208, v204
	v_rcp_f32_e32 v209, v205
	s_nop 0
	v_div_scale_f32 v210, vcc, v10, v198, v10
	v_fma_f32 v212, -v202, v206, 1.0
	v_fmac_f32_e32 v206, v212, v206
	v_mul_f32_e32 v211, v210, v206
	v_fma_f32 v212, -v202, v211, v210
	v_fmac_f32_e32 v211, v212, v206
	v_fma_f32 v212, -v202, v211, v210
	v_div_fmas_f32 v212, v212, v206, v211
	v_div_fixup_f32 v10, v212, v198, v10
	v_div_scale_f32 v210, vcc, v11, v199, v11
	v_fma_f32 v212, -v203, v207, 1.0
	v_fmac_f32_e32 v207, v212, v207
	v_mul_f32_e32 v211, v210, v207
	v_fma_f32 v212, -v203, v211, v210
	v_fmac_f32_e32 v211, v212, v207
	v_fma_f32 v212, -v203, v211, v210
	v_div_fmas_f32 v212, v212, v207, v211
	v_div_fixup_f32 v11, v212, v199, v11
	v_div_scale_f32 v210, vcc, v12, v200, v12
	v_fma_f32 v212, -v204, v208, 1.0
	v_fmac_f32_e32 v208, v212, v208
	v_mul_f32_e32 v211, v210, v208
	v_fma_f32 v212, -v204, v211, v210
	v_fmac_f32_e32 v211, v212, v208
	v_fma_f32 v212, -v204, v211, v210
	v_div_fmas_f32 v212, v212, v208, v211
	v_div_fixup_f32 v12, v212, v200, v12
	v_div_scale_f32 v210, vcc, v13, v201, v13
	v_fma_f32 v212, -v205, v209, 1.0
	v_fmac_f32_e32 v209, v212, v209
	v_mul_f32_e32 v211, v210, v209
	v_fma_f32 v212, -v205, v211, v210
	v_fmac_f32_e32 v211, v212, v209
	v_fma_f32 v212, -v205, v211, v210
	v_div_fmas_f32 v212, v212, v209, v211
	v_div_fixup_f32 v13, v212, v201, v13
	v_mul_f32_e32 v198, 0xbfb8aa3b, v14
	v_mul_f32_e32 v199, 0xbfb8aa3b, v15
	v_mul_f32_e32 v200, 0xbfb8aa3b, v16
	v_mul_f32_e32 v201, 0xbfb8aa3b, v17
	v_exp_f32_e32 v198, v198
	v_exp_f32_e32 v199, v199
	v_exp_f32_e32 v200, v200
	v_exp_f32_e32 v201, v201
	s_nop 0
	v_add_f32_e32 v198, 1.0, v198
	v_add_f32_e32 v199, 1.0, v199
	v_add_f32_e32 v200, 1.0, v200
	v_add_f32_e32 v201, 1.0, v201
	v_div_scale_f32 v202, s[84:85], v198, v198, v14
	v_div_scale_f32 v203, s[84:85], v199, v199, v15
	v_div_scale_f32 v204, s[84:85], v200, v200, v16
	v_div_scale_f32 v205, s[84:85], v201, v201, v17
	v_rcp_f32_e32 v206, v202
	v_rcp_f32_e32 v207, v203
	v_rcp_f32_e32 v208, v204
	v_rcp_f32_e32 v209, v205
	s_nop 0
	v_div_scale_f32 v210, vcc, v14, v198, v14
	v_fma_f32 v212, -v202, v206, 1.0
	v_fmac_f32_e32 v206, v212, v206
	v_mul_f32_e32 v211, v210, v206
	v_fma_f32 v212, -v202, v211, v210
	v_fmac_f32_e32 v211, v212, v206
	v_fma_f32 v212, -v202, v211, v210
	v_div_fmas_f32 v212, v212, v206, v211
	v_div_fixup_f32 v14, v212, v198, v14
	v_div_scale_f32 v210, vcc, v15, v199, v15
	v_fma_f32 v212, -v203, v207, 1.0
	v_fmac_f32_e32 v207, v212, v207
	v_mul_f32_e32 v211, v210, v207
	v_fma_f32 v212, -v203, v211, v210
	v_fmac_f32_e32 v211, v212, v207
	v_fma_f32 v212, -v203, v211, v210
	v_div_fmas_f32 v212, v212, v207, v211
	v_div_fixup_f32 v15, v212, v199, v15
	v_div_scale_f32 v210, vcc, v16, v200, v16
	v_fma_f32 v212, -v204, v208, 1.0
	v_fmac_f32_e32 v208, v212, v208
	v_mul_f32_e32 v211, v210, v208
	v_fma_f32 v212, -v204, v211, v210
	v_fmac_f32_e32 v211, v212, v208
	v_fma_f32 v212, -v204, v211, v210
	v_div_fmas_f32 v212, v212, v208, v211
	v_div_fixup_f32 v16, v212, v200, v16
	v_div_scale_f32 v210, vcc, v17, v201, v17
	v_fma_f32 v212, -v205, v209, 1.0
	v_fmac_f32_e32 v209, v212, v209
	v_mul_f32_e32 v211, v210, v209
	v_fma_f32 v212, -v205, v211, v210
	v_fmac_f32_e32 v211, v212, v209
	v_fma_f32 v212, -v205, v211, v210
	v_div_fmas_f32 v212, v212, v209, v211
	v_div_fixup_f32 v17, v212, v201, v17
	v_mul_f32_e32 v198, 0xbfb8aa3b, v18
	v_mul_f32_e32 v199, 0xbfb8aa3b, v19
	v_mul_f32_e32 v200, 0xbfb8aa3b, v20
	v_mul_f32_e32 v201, 0xbfb8aa3b, v21
	v_exp_f32_e32 v198, v198
	v_exp_f32_e32 v199, v199
	v_exp_f32_e32 v200, v200
	v_exp_f32_e32 v201, v201
	s_nop 0
	v_add_f32_e32 v198, 1.0, v198
	v_add_f32_e32 v199, 1.0, v199
	v_add_f32_e32 v200, 1.0, v200
	v_add_f32_e32 v201, 1.0, v201
	v_div_scale_f32 v202, s[84:85], v198, v198, v18
	v_div_scale_f32 v203, s[84:85], v199, v199, v19
	v_div_scale_f32 v204, s[84:85], v200, v200, v20
	v_div_scale_f32 v205, s[84:85], v201, v201, v21
	v_rcp_f32_e32 v206, v202
	v_rcp_f32_e32 v207, v203
	v_rcp_f32_e32 v208, v204
	v_rcp_f32_e32 v209, v205
	s_nop 0
	v_div_scale_f32 v210, vcc, v18, v198, v18
	v_fma_f32 v212, -v202, v206, 1.0
	v_fmac_f32_e32 v206, v212, v206
	v_mul_f32_e32 v211, v210, v206
	v_fma_f32 v212, -v202, v211, v210
	v_fmac_f32_e32 v211, v212, v206
	v_fma_f32 v212, -v202, v211, v210
	v_div_fmas_f32 v212, v212, v206, v211
	v_div_fixup_f32 v18, v212, v198, v18
	v_div_scale_f32 v210, vcc, v19, v199, v19
	v_fma_f32 v212, -v203, v207, 1.0
	v_fmac_f32_e32 v207, v212, v207
	v_mul_f32_e32 v211, v210, v207
	v_fma_f32 v212, -v203, v211, v210
	v_fmac_f32_e32 v211, v212, v207
	v_fma_f32 v212, -v203, v211, v210
	v_div_fmas_f32 v212, v212, v207, v211
	v_div_fixup_f32 v19, v212, v199, v19
	v_div_scale_f32 v210, vcc, v20, v200, v20
	v_fma_f32 v212, -v204, v208, 1.0
	v_fmac_f32_e32 v208, v212, v208
	v_mul_f32_e32 v211, v210, v208
	v_fma_f32 v212, -v204, v211, v210
	v_fmac_f32_e32 v211, v212, v208
	v_fma_f32 v212, -v204, v211, v210
	v_div_fmas_f32 v212, v212, v208, v211
	v_div_fixup_f32 v20, v212, v200, v20
	v_div_scale_f32 v210, vcc, v21, v201, v21
	v_fma_f32 v212, -v205, v209, 1.0
	v_fmac_f32_e32 v209, v212, v209
	v_mul_f32_e32 v211, v210, v209
	v_fma_f32 v212, -v205, v211, v210
	v_fmac_f32_e32 v211, v212, v209
	v_fma_f32 v212, -v205, v211, v210
	v_div_fmas_f32 v212, v212, v209, v211
	v_div_fixup_f32 v21, v212, v201, v21
	v_mul_f32_e32 v198, 0xbfb8aa3b, v22
	v_mul_f32_e32 v199, 0xbfb8aa3b, v23
	v_mul_f32_e32 v200, 0xbfb8aa3b, v24
	v_mul_f32_e32 v201, 0xbfb8aa3b, v25
	v_exp_f32_e32 v198, v198
	v_exp_f32_e32 v199, v199
	v_exp_f32_e32 v200, v200
	v_exp_f32_e32 v201, v201
	s_nop 0
	v_add_f32_e32 v198, 1.0, v198
	v_add_f32_e32 v199, 1.0, v199
	v_add_f32_e32 v200, 1.0, v200
	v_add_f32_e32 v201, 1.0, v201
	v_div_scale_f32 v202, s[84:85], v198, v198, v22
	v_div_scale_f32 v203, s[84:85], v199, v199, v23
	v_div_scale_f32 v204, s[84:85], v200, v200, v24
	v_div_scale_f32 v205, s[84:85], v201, v201, v25
	v_rcp_f32_e32 v206, v202
	v_rcp_f32_e32 v207, v203
	v_rcp_f32_e32 v208, v204
	v_rcp_f32_e32 v209, v205
	s_nop 0
	v_div_scale_f32 v210, vcc, v22, v198, v22
	v_fma_f32 v212, -v202, v206, 1.0
	v_fmac_f32_e32 v206, v212, v206
	v_mul_f32_e32 v211, v210, v206
	v_fma_f32 v212, -v202, v211, v210
	v_fmac_f32_e32 v211, v212, v206
	v_fma_f32 v212, -v202, v211, v210
	v_div_fmas_f32 v212, v212, v206, v211
	v_div_fixup_f32 v22, v212, v198, v22
	v_div_scale_f32 v210, vcc, v23, v199, v23
	v_fma_f32 v212, -v203, v207, 1.0
	v_fmac_f32_e32 v207, v212, v207
	v_mul_f32_e32 v211, v210, v207
	v_fma_f32 v212, -v203, v211, v210
	v_fmac_f32_e32 v211, v212, v207
	v_fma_f32 v212, -v203, v211, v210
	v_div_fmas_f32 v212, v212, v207, v211
	v_div_fixup_f32 v23, v212, v199, v23
	v_div_scale_f32 v210, vcc, v24, v200, v24
	v_fma_f32 v212, -v204, v208, 1.0
	v_fmac_f32_e32 v208, v212, v208
	v_mul_f32_e32 v211, v210, v208
	v_fma_f32 v212, -v204, v211, v210
	v_fmac_f32_e32 v211, v212, v208
	v_fma_f32 v212, -v204, v211, v210
	v_div_fmas_f32 v212, v212, v208, v211
	v_div_fixup_f32 v24, v212, v200, v24
	v_div_scale_f32 v210, vcc, v25, v201, v25
	v_fma_f32 v212, -v205, v209, 1.0
	v_fmac_f32_e32 v209, v212, v209
	v_mul_f32_e32 v211, v210, v209
	v_fma_f32 v212, -v205, v211, v210
	v_fmac_f32_e32 v211, v212, v209
	v_fma_f32 v212, -v205, v211, v210
	v_div_fmas_f32 v212, v212, v209, v211
	v_div_fixup_f32 v25, v212, v201, v25
	v_mul_f32_e32 v198, 0xbfb8aa3b, v26
	v_mul_f32_e32 v199, 0xbfb8aa3b, v27
	v_mul_f32_e32 v200, 0xbfb8aa3b, v28
	v_mul_f32_e32 v201, 0xbfb8aa3b, v29
	v_exp_f32_e32 v198, v198
	v_exp_f32_e32 v199, v199
	v_exp_f32_e32 v200, v200
	v_exp_f32_e32 v201, v201
	s_nop 0
	v_add_f32_e32 v198, 1.0, v198
	v_add_f32_e32 v199, 1.0, v199
	v_add_f32_e32 v200, 1.0, v200
	v_add_f32_e32 v201, 1.0, v201
	v_div_scale_f32 v202, s[84:85], v198, v198, v26
	v_div_scale_f32 v203, s[84:85], v199, v199, v27
	v_div_scale_f32 v204, s[84:85], v200, v200, v28
	v_div_scale_f32 v205, s[84:85], v201, v201, v29
	v_rcp_f32_e32 v206, v202
	v_rcp_f32_e32 v207, v203
	v_rcp_f32_e32 v208, v204
	v_rcp_f32_e32 v209, v205
	s_nop 0
	v_div_scale_f32 v210, vcc, v26, v198, v26
	v_fma_f32 v212, -v202, v206, 1.0
	v_fmac_f32_e32 v206, v212, v206
	v_mul_f32_e32 v211, v210, v206
	v_fma_f32 v212, -v202, v211, v210
	v_fmac_f32_e32 v211, v212, v206
	v_fma_f32 v212, -v202, v211, v210
	v_div_fmas_f32 v212, v212, v206, v211
	v_div_fixup_f32 v26, v212, v198, v26
	v_div_scale_f32 v210, vcc, v27, v199, v27
	v_fma_f32 v212, -v203, v207, 1.0
	v_fmac_f32_e32 v207, v212, v207
	v_mul_f32_e32 v211, v210, v207
	v_fma_f32 v212, -v203, v211, v210
	v_fmac_f32_e32 v211, v212, v207
	v_fma_f32 v212, -v203, v211, v210
	v_div_fmas_f32 v212, v212, v207, v211
	v_div_fixup_f32 v27, v212, v199, v27
	v_div_scale_f32 v210, vcc, v28, v200, v28
	v_fma_f32 v212, -v204, v208, 1.0
	v_fmac_f32_e32 v208, v212, v208
	v_mul_f32_e32 v211, v210, v208
	v_fma_f32 v212, -v204, v211, v210
	v_fmac_f32_e32 v211, v212, v208
	v_fma_f32 v212, -v204, v211, v210
	v_div_fmas_f32 v212, v212, v208, v211
	v_div_fixup_f32 v28, v212, v200, v28
	v_div_scale_f32 v210, vcc, v29, v201, v29
	v_fma_f32 v212, -v205, v209, 1.0
	v_fmac_f32_e32 v209, v212, v209
	v_mul_f32_e32 v211, v210, v209
	v_fma_f32 v212, -v205, v211, v210
	v_fmac_f32_e32 v211, v212, v209
	v_fma_f32 v212, -v205, v211, v210
	v_div_fmas_f32 v212, v212, v209, v211
	v_div_fixup_f32 v29, v212, v201, v29
	v_mul_f32_e32 v198, 0xbfb8aa3b, v30
	v_mul_f32_e32 v199, 0xbfb8aa3b, v31
	v_mul_f32_e32 v200, 0xbfb8aa3b, v32
	v_mul_f32_e32 v201, 0xbfb8aa3b, v33
	v_exp_f32_e32 v198, v198
	v_exp_f32_e32 v199, v199
	v_exp_f32_e32 v200, v200
	v_exp_f32_e32 v201, v201
	s_nop 0
	v_add_f32_e32 v198, 1.0, v198
	v_add_f32_e32 v199, 1.0, v199
	v_add_f32_e32 v200, 1.0, v200
	v_add_f32_e32 v201, 1.0, v201
	v_div_scale_f32 v202, s[84:85], v198, v198, v30
	v_div_scale_f32 v203, s[84:85], v199, v199, v31
	v_div_scale_f32 v204, s[84:85], v200, v200, v32
	v_div_scale_f32 v205, s[84:85], v201, v201, v33
	v_rcp_f32_e32 v206, v202
	v_rcp_f32_e32 v207, v203
	v_rcp_f32_e32 v208, v204
	v_rcp_f32_e32 v209, v205
	s_nop 0
	v_div_scale_f32 v210, vcc, v30, v198, v30
	v_fma_f32 v212, -v202, v206, 1.0
	v_fmac_f32_e32 v206, v212, v206
	v_mul_f32_e32 v211, v210, v206
	v_fma_f32 v212, -v202, v211, v210
	v_fmac_f32_e32 v211, v212, v206
	v_fma_f32 v212, -v202, v211, v210
	v_div_fmas_f32 v212, v212, v206, v211
	v_div_fixup_f32 v30, v212, v198, v30
	v_div_scale_f32 v210, vcc, v31, v199, v31
	v_fma_f32 v212, -v203, v207, 1.0
	v_fmac_f32_e32 v207, v212, v207
	v_mul_f32_e32 v211, v210, v207
	v_fma_f32 v212, -v203, v211, v210
	v_fmac_f32_e32 v211, v212, v207
	v_fma_f32 v212, -v203, v211, v210
	v_div_fmas_f32 v212, v212, v207, v211
	v_div_fixup_f32 v31, v212, v199, v31
	v_div_scale_f32 v210, vcc, v32, v200, v32
	v_fma_f32 v212, -v204, v208, 1.0
	v_fmac_f32_e32 v208, v212, v208
	v_mul_f32_e32 v211, v210, v208
	v_fma_f32 v212, -v204, v211, v210
	v_fmac_f32_e32 v211, v212, v208
	v_fma_f32 v212, -v204, v211, v210
	v_div_fmas_f32 v212, v212, v208, v211
	v_div_fixup_f32 v32, v212, v200, v32
	v_div_scale_f32 v210, vcc, v33, v201, v33
	v_fma_f32 v212, -v205, v209, 1.0
	v_fmac_f32_e32 v209, v212, v209
	v_mul_f32_e32 v211, v210, v209
	v_fma_f32 v212, -v205, v211, v210
	v_fmac_f32_e32 v211, v212, v209
	v_fma_f32 v212, -v205, v211, v210
	v_div_fmas_f32 v212, v212, v209, v211
	v_div_fixup_f32 v33, v212, v201, v33
	v_mul_f32_e32 v198, 0xbfb8aa3b, v34
	v_mul_f32_e32 v199, 0xbfb8aa3b, v35
	v_mul_f32_e32 v200, 0xbfb8aa3b, v36
	v_mul_f32_e32 v201, 0xbfb8aa3b, v37
	v_exp_f32_e32 v198, v198
	v_exp_f32_e32 v199, v199
	v_exp_f32_e32 v200, v200
	v_exp_f32_e32 v201, v201
	s_nop 0
	v_add_f32_e32 v198, 1.0, v198
	v_add_f32_e32 v199, 1.0, v199
	v_add_f32_e32 v200, 1.0, v200
	v_add_f32_e32 v201, 1.0, v201
	v_div_scale_f32 v202, s[84:85], v198, v198, v34
	v_div_scale_f32 v203, s[84:85], v199, v199, v35
	v_div_scale_f32 v204, s[84:85], v200, v200, v36
	v_div_scale_f32 v205, s[84:85], v201, v201, v37
	v_rcp_f32_e32 v206, v202
	v_rcp_f32_e32 v207, v203
	v_rcp_f32_e32 v208, v204
	v_rcp_f32_e32 v209, v205
	s_nop 0
	v_div_scale_f32 v210, vcc, v34, v198, v34
	v_fma_f32 v212, -v202, v206, 1.0
	v_fmac_f32_e32 v206, v212, v206
	v_mul_f32_e32 v211, v210, v206
	v_fma_f32 v212, -v202, v211, v210
	v_fmac_f32_e32 v211, v212, v206
	v_fma_f32 v212, -v202, v211, v210
	v_div_fmas_f32 v212, v212, v206, v211
	v_div_fixup_f32 v34, v212, v198, v34
	v_div_scale_f32 v210, vcc, v35, v199, v35
	v_fma_f32 v212, -v203, v207, 1.0
	v_fmac_f32_e32 v207, v212, v207
	v_mul_f32_e32 v211, v210, v207
	v_fma_f32 v212, -v203, v211, v210
	v_fmac_f32_e32 v211, v212, v207
	v_fma_f32 v212, -v203, v211, v210
	v_div_fmas_f32 v212, v212, v207, v211
	v_div_fixup_f32 v35, v212, v199, v35
	v_div_scale_f32 v210, vcc, v36, v200, v36
	v_fma_f32 v212, -v204, v208, 1.0
	v_fmac_f32_e32 v208, v212, v208
	v_mul_f32_e32 v211, v210, v208
	v_fma_f32 v212, -v204, v211, v210
	v_fmac_f32_e32 v211, v212, v208
	v_fma_f32 v212, -v204, v211, v210
	v_div_fmas_f32 v212, v212, v208, v211
	v_div_fixup_f32 v36, v212, v200, v36
	v_div_scale_f32 v210, vcc, v37, v201, v37
	v_fma_f32 v212, -v205, v209, 1.0
	v_fmac_f32_e32 v209, v212, v209
	v_mul_f32_e32 v211, v210, v209
	v_fma_f32 v212, -v205, v211, v210
	v_fmac_f32_e32 v211, v212, v209
	v_fma_f32 v212, -v205, v211, v210
	v_div_fmas_f32 v212, v212, v209, v211
	v_div_fixup_f32 v37, v212, v201, v37
	v_mul_f32_e32 v198, 0xbfb8aa3b, v38
	v_mul_f32_e32 v199, 0xbfb8aa3b, v39
	v_mul_f32_e32 v200, 0xbfb8aa3b, v40
	v_mul_f32_e32 v201, 0xbfb8aa3b, v41
	v_exp_f32_e32 v198, v198
	v_exp_f32_e32 v199, v199
	v_exp_f32_e32 v200, v200
	v_exp_f32_e32 v201, v201
	s_nop 0
	v_add_f32_e32 v198, 1.0, v198
	v_add_f32_e32 v199, 1.0, v199
	v_add_f32_e32 v200, 1.0, v200
	v_add_f32_e32 v201, 1.0, v201
	v_div_scale_f32 v202, s[84:85], v198, v198, v38
	v_div_scale_f32 v203, s[84:85], v199, v199, v39
	v_div_scale_f32 v204, s[84:85], v200, v200, v40
	v_div_scale_f32 v205, s[84:85], v201, v201, v41
	v_rcp_f32_e32 v206, v202
	v_rcp_f32_e32 v207, v203
	v_rcp_f32_e32 v208, v204
	v_rcp_f32_e32 v209, v205
	s_nop 0
	v_div_scale_f32 v210, vcc, v38, v198, v38
	v_fma_f32 v212, -v202, v206, 1.0
	v_fmac_f32_e32 v206, v212, v206
	v_mul_f32_e32 v211, v210, v206
	v_fma_f32 v212, -v202, v211, v210
	v_fmac_f32_e32 v211, v212, v206
	v_fma_f32 v212, -v202, v211, v210
	v_div_fmas_f32 v212, v212, v206, v211
	v_div_fixup_f32 v38, v212, v198, v38
	v_div_scale_f32 v210, vcc, v39, v199, v39
	v_fma_f32 v212, -v203, v207, 1.0
	v_fmac_f32_e32 v207, v212, v207
	v_mul_f32_e32 v211, v210, v207
	v_fma_f32 v212, -v203, v211, v210
	v_fmac_f32_e32 v211, v212, v207
	v_fma_f32 v212, -v203, v211, v210
	v_div_fmas_f32 v212, v212, v207, v211
	v_div_fixup_f32 v39, v212, v199, v39
	v_div_scale_f32 v210, vcc, v40, v200, v40
	v_fma_f32 v212, -v204, v208, 1.0
	v_fmac_f32_e32 v208, v212, v208
	v_mul_f32_e32 v211, v210, v208
	v_fma_f32 v212, -v204, v211, v210
	v_fmac_f32_e32 v211, v212, v208
	v_fma_f32 v212, -v204, v211, v210
	v_div_fmas_f32 v212, v212, v208, v211
	v_div_fixup_f32 v40, v212, v200, v40
	v_div_scale_f32 v210, vcc, v41, v201, v41
	v_fma_f32 v212, -v205, v209, 1.0
	v_fmac_f32_e32 v209, v212, v209
	v_mul_f32_e32 v211, v210, v209
	v_fma_f32 v212, -v205, v211, v210
	v_fmac_f32_e32 v211, v212, v209
	v_fma_f32 v212, -v205, v211, v210
	v_div_fmas_f32 v212, v212, v209, v211
	v_div_fixup_f32 v41, v212, v201, v41
	v_mul_f32_e32 v198, 0xbfb8aa3b, v42
	v_mul_f32_e32 v199, 0xbfb8aa3b, v43
	v_mul_f32_e32 v200, 0xbfb8aa3b, v44
	v_mul_f32_e32 v201, 0xbfb8aa3b, v45
	v_exp_f32_e32 v198, v198
	v_exp_f32_e32 v199, v199
	v_exp_f32_e32 v200, v200
	v_exp_f32_e32 v201, v201
	s_nop 0
	v_add_f32_e32 v198, 1.0, v198
	v_add_f32_e32 v199, 1.0, v199
	v_add_f32_e32 v200, 1.0, v200
	v_add_f32_e32 v201, 1.0, v201
	v_div_scale_f32 v202, s[84:85], v198, v198, v42
	v_div_scale_f32 v203, s[84:85], v199, v199, v43
	v_div_scale_f32 v204, s[84:85], v200, v200, v44
	v_div_scale_f32 v205, s[84:85], v201, v201, v45
	v_rcp_f32_e32 v206, v202
	v_rcp_f32_e32 v207, v203
	v_rcp_f32_e32 v208, v204
	v_rcp_f32_e32 v209, v205
	s_nop 0
	v_div_scale_f32 v210, vcc, v42, v198, v42
	v_fma_f32 v212, -v202, v206, 1.0
	v_fmac_f32_e32 v206, v212, v206
	v_mul_f32_e32 v211, v210, v206
	v_fma_f32 v212, -v202, v211, v210
	v_fmac_f32_e32 v211, v212, v206
	v_fma_f32 v212, -v202, v211, v210
	v_div_fmas_f32 v212, v212, v206, v211
	v_div_fixup_f32 v42, v212, v198, v42
	v_div_scale_f32 v210, vcc, v43, v199, v43
	v_fma_f32 v212, -v203, v207, 1.0
	v_fmac_f32_e32 v207, v212, v207
	v_mul_f32_e32 v211, v210, v207
	v_fma_f32 v212, -v203, v211, v210
	v_fmac_f32_e32 v211, v212, v207
	v_fma_f32 v212, -v203, v211, v210
	v_div_fmas_f32 v212, v212, v207, v211
	v_div_fixup_f32 v43, v212, v199, v43
	v_div_scale_f32 v210, vcc, v44, v200, v44
	v_fma_f32 v212, -v204, v208, 1.0
	v_fmac_f32_e32 v208, v212, v208
	v_mul_f32_e32 v211, v210, v208
	v_fma_f32 v212, -v204, v211, v210
	v_fmac_f32_e32 v211, v212, v208
	v_fma_f32 v212, -v204, v211, v210
	v_div_fmas_f32 v212, v212, v208, v211
	v_div_fixup_f32 v44, v212, v200, v44
	v_div_scale_f32 v210, vcc, v45, v201, v45
	v_fma_f32 v212, -v205, v209, 1.0
	v_fmac_f32_e32 v209, v212, v209
	v_mul_f32_e32 v211, v210, v209
	v_fma_f32 v212, -v205, v211, v210
	v_fmac_f32_e32 v211, v212, v209
	v_fma_f32 v212, -v205, v211, v210
	v_div_fmas_f32 v212, v212, v209, v211
	v_div_fixup_f32 v45, v212, v201, v45
	v_mul_f32_e32 v198, 0xbfb8aa3b, v46
	v_mul_f32_e32 v199, 0xbfb8aa3b, v47
	v_mul_f32_e32 v200, 0xbfb8aa3b, v48
	v_mul_f32_e32 v201, 0xbfb8aa3b, v49
	v_exp_f32_e32 v198, v198
	v_exp_f32_e32 v199, v199
	v_exp_f32_e32 v200, v200
	v_exp_f32_e32 v201, v201
	s_nop 0
	v_add_f32_e32 v198, 1.0, v198
	v_add_f32_e32 v199, 1.0, v199
	v_add_f32_e32 v200, 1.0, v200
	v_add_f32_e32 v201, 1.0, v201
	v_div_scale_f32 v202, s[84:85], v198, v198, v46
	v_div_scale_f32 v203, s[84:85], v199, v199, v47
	v_div_scale_f32 v204, s[84:85], v200, v200, v48
	v_div_scale_f32 v205, s[84:85], v201, v201, v49
	v_rcp_f32_e32 v206, v202
	v_rcp_f32_e32 v207, v203
	v_rcp_f32_e32 v208, v204
	v_rcp_f32_e32 v209, v205
	s_nop 0
	v_div_scale_f32 v210, vcc, v46, v198, v46
	v_fma_f32 v212, -v202, v206, 1.0
	v_fmac_f32_e32 v206, v212, v206
	v_mul_f32_e32 v211, v210, v206
	v_fma_f32 v212, -v202, v211, v210
	v_fmac_f32_e32 v211, v212, v206
	v_fma_f32 v212, -v202, v211, v210
	v_div_fmas_f32 v212, v212, v206, v211
	v_div_fixup_f32 v46, v212, v198, v46
	v_div_scale_f32 v210, vcc, v47, v199, v47
	v_fma_f32 v212, -v203, v207, 1.0
	v_fmac_f32_e32 v207, v212, v207
	v_mul_f32_e32 v211, v210, v207
	v_fma_f32 v212, -v203, v211, v210
	v_fmac_f32_e32 v211, v212, v207
	v_fma_f32 v212, -v203, v211, v210
	v_div_fmas_f32 v212, v212, v207, v211
	v_div_fixup_f32 v47, v212, v199, v47
	v_div_scale_f32 v210, vcc, v48, v200, v48
	v_fma_f32 v212, -v204, v208, 1.0
	v_fmac_f32_e32 v208, v212, v208
	v_mul_f32_e32 v211, v210, v208
	v_fma_f32 v212, -v204, v211, v210
	v_fmac_f32_e32 v211, v212, v208
	v_fma_f32 v212, -v204, v211, v210
	v_div_fmas_f32 v212, v212, v208, v211
	v_div_fixup_f32 v48, v212, v200, v48
	v_div_scale_f32 v210, vcc, v49, v201, v49
	v_fma_f32 v212, -v205, v209, 1.0
	v_fmac_f32_e32 v209, v212, v209
	v_mul_f32_e32 v211, v210, v209
	v_fma_f32 v212, -v205, v211, v210
	v_fmac_f32_e32 v211, v212, v209
	v_fma_f32 v212, -v205, v211, v210
	v_div_fmas_f32 v212, v212, v209, v211
	v_div_fixup_f32 v49, v212, v201, v49
	v_mul_f32_e32 v198, 0xbfb8aa3b, v50
	v_mul_f32_e32 v199, 0xbfb8aa3b, v51
	v_mul_f32_e32 v200, 0xbfb8aa3b, v52
	v_mul_f32_e32 v201, 0xbfb8aa3b, v53
	v_exp_f32_e32 v198, v198
	v_exp_f32_e32 v199, v199
	v_exp_f32_e32 v200, v200
	v_exp_f32_e32 v201, v201
	s_nop 0
	v_add_f32_e32 v198, 1.0, v198
	v_add_f32_e32 v199, 1.0, v199
	v_add_f32_e32 v200, 1.0, v200
	v_add_f32_e32 v201, 1.0, v201
	v_div_scale_f32 v202, s[84:85], v198, v198, v50
	v_div_scale_f32 v203, s[84:85], v199, v199, v51
	v_div_scale_f32 v204, s[84:85], v200, v200, v52
	v_div_scale_f32 v205, s[84:85], v201, v201, v53
	v_rcp_f32_e32 v206, v202
	v_rcp_f32_e32 v207, v203
	v_rcp_f32_e32 v208, v204
	v_rcp_f32_e32 v209, v205
	s_nop 0
	v_div_scale_f32 v210, vcc, v50, v198, v50
	v_fma_f32 v212, -v202, v206, 1.0
	v_fmac_f32_e32 v206, v212, v206
	v_mul_f32_e32 v211, v210, v206
	v_fma_f32 v212, -v202, v211, v210
	v_fmac_f32_e32 v211, v212, v206
	v_fma_f32 v212, -v202, v211, v210
	v_div_fmas_f32 v212, v212, v206, v211
	v_div_fixup_f32 v50, v212, v198, v50
	v_div_scale_f32 v210, vcc, v51, v199, v51
	v_fma_f32 v212, -v203, v207, 1.0
	v_fmac_f32_e32 v207, v212, v207
	v_mul_f32_e32 v211, v210, v207
	v_fma_f32 v212, -v203, v211, v210
	v_fmac_f32_e32 v211, v212, v207
	v_fma_f32 v212, -v203, v211, v210
	v_div_fmas_f32 v212, v212, v207, v211
	v_div_fixup_f32 v51, v212, v199, v51
	v_div_scale_f32 v210, vcc, v52, v200, v52
	v_fma_f32 v212, -v204, v208, 1.0
	v_fmac_f32_e32 v208, v212, v208
	v_mul_f32_e32 v211, v210, v208
	v_fma_f32 v212, -v204, v211, v210
	v_fmac_f32_e32 v211, v212, v208
	v_fma_f32 v212, -v204, v211, v210
	v_div_fmas_f32 v212, v212, v208, v211
	v_div_fixup_f32 v52, v212, v200, v52
	v_div_scale_f32 v210, vcc, v53, v201, v53
	v_fma_f32 v212, -v205, v209, 1.0
	v_fmac_f32_e32 v209, v212, v209
	v_mul_f32_e32 v211, v210, v209
	v_fma_f32 v212, -v205, v211, v210
	v_fmac_f32_e32 v211, v212, v209
	v_fma_f32 v212, -v205, v211, v210
	v_div_fmas_f32 v212, v212, v209, v211
	v_div_fixup_f32 v53, v212, v201, v53
	v_mul_f32_e32 v198, 0xbfb8aa3b, v54
	v_mul_f32_e32 v199, 0xbfb8aa3b, v55
	v_mul_f32_e32 v200, 0xbfb8aa3b, v56
	v_mul_f32_e32 v201, 0xbfb8aa3b, v57
	v_exp_f32_e32 v198, v198
	v_exp_f32_e32 v199, v199
	v_exp_f32_e32 v200, v200
	v_exp_f32_e32 v201, v201
	s_nop 0
	v_add_f32_e32 v198, 1.0, v198
	v_add_f32_e32 v199, 1.0, v199
	v_add_f32_e32 v200, 1.0, v200
	v_add_f32_e32 v201, 1.0, v201
	v_div_scale_f32 v202, s[84:85], v198, v198, v54
	v_div_scale_f32 v203, s[84:85], v199, v199, v55
	v_div_scale_f32 v204, s[84:85], v200, v200, v56
	v_div_scale_f32 v205, s[84:85], v201, v201, v57
	v_rcp_f32_e32 v206, v202
	v_rcp_f32_e32 v207, v203
	v_rcp_f32_e32 v208, v204
	v_rcp_f32_e32 v209, v205
	s_nop 0
	v_div_scale_f32 v210, vcc, v54, v198, v54
	v_fma_f32 v212, -v202, v206, 1.0
	v_fmac_f32_e32 v206, v212, v206
	v_mul_f32_e32 v211, v210, v206
	v_fma_f32 v212, -v202, v211, v210
	v_fmac_f32_e32 v211, v212, v206
	v_fma_f32 v212, -v202, v211, v210
	v_div_fmas_f32 v212, v212, v206, v211
	v_div_fixup_f32 v54, v212, v198, v54
	v_div_scale_f32 v210, vcc, v55, v199, v55
	v_fma_f32 v212, -v203, v207, 1.0
	v_fmac_f32_e32 v207, v212, v207
	v_mul_f32_e32 v211, v210, v207
	v_fma_f32 v212, -v203, v211, v210
	v_fmac_f32_e32 v211, v212, v207
	v_fma_f32 v212, -v203, v211, v210
	v_div_fmas_f32 v212, v212, v207, v211
	v_div_fixup_f32 v55, v212, v199, v55
	v_div_scale_f32 v210, vcc, v56, v200, v56
	v_fma_f32 v212, -v204, v208, 1.0
	v_fmac_f32_e32 v208, v212, v208
	v_mul_f32_e32 v211, v210, v208
	v_fma_f32 v212, -v204, v211, v210
	v_fmac_f32_e32 v211, v212, v208
	v_fma_f32 v212, -v204, v211, v210
	v_div_fmas_f32 v212, v212, v208, v211
	v_div_fixup_f32 v56, v212, v200, v56
	v_div_scale_f32 v210, vcc, v57, v201, v57
	v_fma_f32 v212, -v205, v209, 1.0
	v_fmac_f32_e32 v209, v212, v209
	v_mul_f32_e32 v211, v210, v209
	v_fma_f32 v212, -v205, v211, v210
	v_fmac_f32_e32 v211, v212, v209
	v_fma_f32 v212, -v205, v211, v210
	v_div_fmas_f32 v212, v212, v209, v211
	v_div_fixup_f32 v57, v212, v201, v57
	v_mul_f32_e32 v198, 0xbfb8aa3b, v58
	v_mul_f32_e32 v199, 0xbfb8aa3b, v59
	v_mul_f32_e32 v200, 0xbfb8aa3b, v60
	v_mul_f32_e32 v201, 0xbfb8aa3b, v61
	v_exp_f32_e32 v198, v198
	v_exp_f32_e32 v199, v199
	v_exp_f32_e32 v200, v200
	v_exp_f32_e32 v201, v201
	s_nop 0
	v_add_f32_e32 v198, 1.0, v198
	v_add_f32_e32 v199, 1.0, v199
	v_add_f32_e32 v200, 1.0, v200
	v_add_f32_e32 v201, 1.0, v201
	v_div_scale_f32 v202, s[84:85], v198, v198, v58
	v_div_scale_f32 v203, s[84:85], v199, v199, v59
	v_div_scale_f32 v204, s[84:85], v200, v200, v60
	v_div_scale_f32 v205, s[84:85], v201, v201, v61
	v_rcp_f32_e32 v206, v202
	v_rcp_f32_e32 v207, v203
	v_rcp_f32_e32 v208, v204
	v_rcp_f32_e32 v209, v205
	s_nop 0
	v_div_scale_f32 v210, vcc, v58, v198, v58
	v_fma_f32 v212, -v202, v206, 1.0
	v_fmac_f32_e32 v206, v212, v206
	v_mul_f32_e32 v211, v210, v206
	v_fma_f32 v212, -v202, v211, v210
	v_fmac_f32_e32 v211, v212, v206
	v_fma_f32 v212, -v202, v211, v210
	v_div_fmas_f32 v212, v212, v206, v211
	v_div_fixup_f32 v58, v212, v198, v58
	v_div_scale_f32 v210, vcc, v59, v199, v59
	v_fma_f32 v212, -v203, v207, 1.0
	v_fmac_f32_e32 v207, v212, v207
	v_mul_f32_e32 v211, v210, v207
	v_fma_f32 v212, -v203, v211, v210
	v_fmac_f32_e32 v211, v212, v207
	v_fma_f32 v212, -v203, v211, v210
	v_div_fmas_f32 v212, v212, v207, v211
	v_div_fixup_f32 v59, v212, v199, v59
	v_div_scale_f32 v210, vcc, v60, v200, v60
	v_fma_f32 v212, -v204, v208, 1.0
	v_fmac_f32_e32 v208, v212, v208
	v_mul_f32_e32 v211, v210, v208
	v_fma_f32 v212, -v204, v211, v210
	v_fmac_f32_e32 v211, v212, v208
	v_fma_f32 v212, -v204, v211, v210
	v_div_fmas_f32 v212, v212, v208, v211
	v_div_fixup_f32 v60, v212, v200, v60
	v_div_scale_f32 v210, vcc, v61, v201, v61
	v_fma_f32 v212, -v205, v209, 1.0
	v_fmac_f32_e32 v209, v212, v209
	v_mul_f32_e32 v211, v210, v209
	v_fma_f32 v212, -v205, v211, v210
	v_fmac_f32_e32 v211, v212, v209
	v_fma_f32 v212, -v205, v211, v210
	v_div_fmas_f32 v212, v212, v209, v211
	v_div_fixup_f32 v61, v212, v201, v61
	v_mul_f32_e32 v198, 0xbfb8aa3b, v62
	v_mul_f32_e32 v199, 0xbfb8aa3b, v63
	v_mul_f32_e32 v200, 0xbfb8aa3b, v64
	v_mul_f32_e32 v201, 0xbfb8aa3b, v65
	v_exp_f32_e32 v198, v198
	v_exp_f32_e32 v199, v199
	v_exp_f32_e32 v200, v200
	v_exp_f32_e32 v201, v201
	s_nop 0
	v_add_f32_e32 v198, 1.0, v198
	v_add_f32_e32 v199, 1.0, v199
	v_add_f32_e32 v200, 1.0, v200
	v_add_f32_e32 v201, 1.0, v201
	v_div_scale_f32 v202, s[84:85], v198, v198, v62
	v_div_scale_f32 v203, s[84:85], v199, v199, v63
	v_div_scale_f32 v204, s[84:85], v200, v200, v64
	v_div_scale_f32 v205, s[84:85], v201, v201, v65
	v_rcp_f32_e32 v206, v202
	v_rcp_f32_e32 v207, v203
	v_rcp_f32_e32 v208, v204
	v_rcp_f32_e32 v209, v205
	s_nop 0
	v_div_scale_f32 v210, vcc, v62, v198, v62
	v_fma_f32 v212, -v202, v206, 1.0
	v_fmac_f32_e32 v206, v212, v206
	v_mul_f32_e32 v211, v210, v206
	v_fma_f32 v212, -v202, v211, v210
	v_fmac_f32_e32 v211, v212, v206
	v_fma_f32 v212, -v202, v211, v210
	v_div_fmas_f32 v212, v212, v206, v211
	v_div_fixup_f32 v62, v212, v198, v62
	v_div_scale_f32 v210, vcc, v63, v199, v63
	v_fma_f32 v212, -v203, v207, 1.0
	v_fmac_f32_e32 v207, v212, v207
	v_mul_f32_e32 v211, v210, v207
	v_fma_f32 v212, -v203, v211, v210
	v_fmac_f32_e32 v211, v212, v207
	v_fma_f32 v212, -v203, v211, v210
	v_div_fmas_f32 v212, v212, v207, v211
	v_div_fixup_f32 v63, v212, v199, v63
	v_div_scale_f32 v210, vcc, v64, v200, v64
	v_fma_f32 v212, -v204, v208, 1.0
	v_fmac_f32_e32 v208, v212, v208
	v_mul_f32_e32 v211, v210, v208
	v_fma_f32 v212, -v204, v211, v210
	v_fmac_f32_e32 v211, v212, v208
	v_fma_f32 v212, -v204, v211, v210
	v_div_fmas_f32 v212, v212, v208, v211
	v_div_fixup_f32 v64, v212, v200, v64
	v_div_scale_f32 v210, vcc, v65, v201, v65
	v_fma_f32 v212, -v205, v209, 1.0
	v_fmac_f32_e32 v209, v212, v209
	v_mul_f32_e32 v211, v210, v209
	v_fma_f32 v212, -v205, v211, v210
	v_fmac_f32_e32 v211, v212, v209
	v_fma_f32 v212, -v205, v211, v210
	v_div_fmas_f32 v212, v212, v209, v211
	v_div_fixup_f32 v65, v212, v201, v65
	v_mul_f32_e32 v198, 0xbfb8aa3b, v66
	v_mul_f32_e32 v199, 0xbfb8aa3b, v67
	v_mul_f32_e32 v200, 0xbfb8aa3b, v68
	v_mul_f32_e32 v201, 0xbfb8aa3b, v69
	v_exp_f32_e32 v198, v198
	v_exp_f32_e32 v199, v199
	v_exp_f32_e32 v200, v200
	v_exp_f32_e32 v201, v201
	s_nop 0
	v_add_f32_e32 v198, 1.0, v198
	v_add_f32_e32 v199, 1.0, v199
	v_add_f32_e32 v200, 1.0, v200
	v_add_f32_e32 v201, 1.0, v201
	v_div_scale_f32 v202, s[84:85], v198, v198, v66
	v_div_scale_f32 v203, s[84:85], v199, v199, v67
	v_div_scale_f32 v204, s[84:85], v200, v200, v68
	v_div_scale_f32 v205, s[84:85], v201, v201, v69
	v_rcp_f32_e32 v206, v202
	v_rcp_f32_e32 v207, v203
	v_rcp_f32_e32 v208, v204
	v_rcp_f32_e32 v209, v205
	s_nop 0
	v_div_scale_f32 v210, vcc, v66, v198, v66
	v_fma_f32 v212, -v202, v206, 1.0
	v_fmac_f32_e32 v206, v212, v206
	v_mul_f32_e32 v211, v210, v206
	v_fma_f32 v212, -v202, v211, v210
	v_fmac_f32_e32 v211, v212, v206
	v_fma_f32 v212, -v202, v211, v210
	v_div_fmas_f32 v212, v212, v206, v211
	v_div_fixup_f32 v66, v212, v198, v66
	v_div_scale_f32 v210, vcc, v67, v199, v67
	v_fma_f32 v212, -v203, v207, 1.0
	v_fmac_f32_e32 v207, v212, v207
	v_mul_f32_e32 v211, v210, v207
	v_fma_f32 v212, -v203, v211, v210
	v_fmac_f32_e32 v211, v212, v207
	v_fma_f32 v212, -v203, v211, v210
	v_div_fmas_f32 v212, v212, v207, v211
	v_div_fixup_f32 v67, v212, v199, v67
	v_div_scale_f32 v210, vcc, v68, v200, v68
	v_fma_f32 v212, -v204, v208, 1.0
	v_fmac_f32_e32 v208, v212, v208
	v_mul_f32_e32 v211, v210, v208
	v_fma_f32 v212, -v204, v211, v210
	v_fmac_f32_e32 v211, v212, v208
	v_fma_f32 v212, -v204, v211, v210
	v_div_fmas_f32 v212, v212, v208, v211
	v_div_fixup_f32 v68, v212, v200, v68
	v_div_scale_f32 v210, vcc, v69, v201, v69
	v_fma_f32 v212, -v205, v209, 1.0
	v_fmac_f32_e32 v209, v212, v209
	v_mul_f32_e32 v211, v210, v209
	v_fma_f32 v212, -v205, v211, v210
	v_fmac_f32_e32 v211, v212, v209
	v_fma_f32 v212, -v205, v211, v210
	v_div_fmas_f32 v212, v212, v209, v211
	v_div_fixup_f32 v69, v212, v201, v69
	v_mul_f32_e32 v198, 0xbfb8aa3b, v70
	v_mul_f32_e32 v199, 0xbfb8aa3b, v71
	v_mul_f32_e32 v200, 0xbfb8aa3b, v72
	v_mul_f32_e32 v201, 0xbfb8aa3b, v73
	v_exp_f32_e32 v198, v198
	v_exp_f32_e32 v199, v199
	v_exp_f32_e32 v200, v200
	v_exp_f32_e32 v201, v201
	s_nop 0
	v_add_f32_e32 v198, 1.0, v198
	v_add_f32_e32 v199, 1.0, v199
	v_add_f32_e32 v200, 1.0, v200
	v_add_f32_e32 v201, 1.0, v201
	v_div_scale_f32 v202, s[84:85], v198, v198, v70
	v_div_scale_f32 v203, s[84:85], v199, v199, v71
	v_div_scale_f32 v204, s[84:85], v200, v200, v72
	v_div_scale_f32 v205, s[84:85], v201, v201, v73
	v_rcp_f32_e32 v206, v202
	v_rcp_f32_e32 v207, v203
	v_rcp_f32_e32 v208, v204
	v_rcp_f32_e32 v209, v205
	s_nop 0
	v_div_scale_f32 v210, vcc, v70, v198, v70
	v_fma_f32 v212, -v202, v206, 1.0
	v_fmac_f32_e32 v206, v212, v206
	v_mul_f32_e32 v211, v210, v206
	v_fma_f32 v212, -v202, v211, v210
	v_fmac_f32_e32 v211, v212, v206
	v_fma_f32 v212, -v202, v211, v210
	v_div_fmas_f32 v212, v212, v206, v211
	v_div_fixup_f32 v70, v212, v198, v70
	v_div_scale_f32 v210, vcc, v71, v199, v71
	v_fma_f32 v212, -v203, v207, 1.0
	v_fmac_f32_e32 v207, v212, v207
	v_mul_f32_e32 v211, v210, v207
	v_fma_f32 v212, -v203, v211, v210
	v_fmac_f32_e32 v211, v212, v207
	v_fma_f32 v212, -v203, v211, v210
	v_div_fmas_f32 v212, v212, v207, v211
	v_div_fixup_f32 v71, v212, v199, v71
	v_div_scale_f32 v210, vcc, v72, v200, v72
	v_fma_f32 v212, -v204, v208, 1.0
	v_fmac_f32_e32 v208, v212, v208
	v_mul_f32_e32 v211, v210, v208
	v_fma_f32 v212, -v204, v211, v210
	v_fmac_f32_e32 v211, v212, v208
	v_fma_f32 v212, -v204, v211, v210
	v_div_fmas_f32 v212, v212, v208, v211
	v_div_fixup_f32 v72, v212, v200, v72
	v_div_scale_f32 v210, vcc, v73, v201, v73
	v_fma_f32 v212, -v205, v209, 1.0
	v_fmac_f32_e32 v209, v212, v209
	v_mul_f32_e32 v211, v210, v209
	v_fma_f32 v212, -v205, v211, v210
	v_fmac_f32_e32 v211, v212, v209
	v_fma_f32 v212, -v205, v211, v210
	v_div_fmas_f32 v212, v212, v209, v211
	v_div_fixup_f32 v73, v212, v201, v73
	v_mul_f32_e32 v198, 0xbfb8aa3b, v74
	v_mul_f32_e32 v199, 0xbfb8aa3b, v75
	v_mul_f32_e32 v200, 0xbfb8aa3b, v76
	v_mul_f32_e32 v201, 0xbfb8aa3b, v77
	v_exp_f32_e32 v198, v198
	v_exp_f32_e32 v199, v199
	v_exp_f32_e32 v200, v200
	v_exp_f32_e32 v201, v201
	s_nop 0
	v_add_f32_e32 v198, 1.0, v198
	v_add_f32_e32 v199, 1.0, v199
	v_add_f32_e32 v200, 1.0, v200
	v_add_f32_e32 v201, 1.0, v201
	v_div_scale_f32 v202, s[84:85], v198, v198, v74
	v_div_scale_f32 v203, s[84:85], v199, v199, v75
	v_div_scale_f32 v204, s[84:85], v200, v200, v76
	v_div_scale_f32 v205, s[84:85], v201, v201, v77
	v_rcp_f32_e32 v206, v202
	v_rcp_f32_e32 v207, v203
	v_rcp_f32_e32 v208, v204
	v_rcp_f32_e32 v209, v205
	s_nop 0
	v_div_scale_f32 v210, vcc, v74, v198, v74
	v_fma_f32 v212, -v202, v206, 1.0
	v_fmac_f32_e32 v206, v212, v206
	v_mul_f32_e32 v211, v210, v206
	v_fma_f32 v212, -v202, v211, v210
	v_fmac_f32_e32 v211, v212, v206
	v_fma_f32 v212, -v202, v211, v210
	v_div_fmas_f32 v212, v212, v206, v211
	v_div_fixup_f32 v74, v212, v198, v74
	v_div_scale_f32 v210, vcc, v75, v199, v75
	v_fma_f32 v212, -v203, v207, 1.0
	v_fmac_f32_e32 v207, v212, v207
	v_mul_f32_e32 v211, v210, v207
	v_fma_f32 v212, -v203, v211, v210
	v_fmac_f32_e32 v211, v212, v207
	v_fma_f32 v212, -v203, v211, v210
	v_div_fmas_f32 v212, v212, v207, v211
	v_div_fixup_f32 v75, v212, v199, v75
	v_div_scale_f32 v210, vcc, v76, v200, v76
	v_fma_f32 v212, -v204, v208, 1.0
	v_fmac_f32_e32 v208, v212, v208
	v_mul_f32_e32 v211, v210, v208
	v_fma_f32 v212, -v204, v211, v210
	v_fmac_f32_e32 v211, v212, v208
	v_fma_f32 v212, -v204, v211, v210
	v_div_fmas_f32 v212, v212, v208, v211
	v_div_fixup_f32 v76, v212, v200, v76
	v_div_scale_f32 v210, vcc, v77, v201, v77
	v_fma_f32 v212, -v205, v209, 1.0
	v_fmac_f32_e32 v209, v212, v209
	v_mul_f32_e32 v211, v210, v209
	v_fma_f32 v212, -v205, v211, v210
	v_fmac_f32_e32 v211, v212, v209
	v_fma_f32 v212, -v205, v211, v210
	v_div_fmas_f32 v212, v212, v209, v211
	v_div_fixup_f32 v77, v212, v201, v77
	v_mul_f32_e32 v198, 0xbfb8aa3b, v78
	v_mul_f32_e32 v199, 0xbfb8aa3b, v79
	v_mul_f32_e32 v200, 0xbfb8aa3b, v80
	v_mul_f32_e32 v201, 0xbfb8aa3b, v81
	v_exp_f32_e32 v198, v198
	v_exp_f32_e32 v199, v199
	v_exp_f32_e32 v200, v200
	v_exp_f32_e32 v201, v201
	s_nop 0
	v_add_f32_e32 v198, 1.0, v198
	v_add_f32_e32 v199, 1.0, v199
	v_add_f32_e32 v200, 1.0, v200
	v_add_f32_e32 v201, 1.0, v201
	v_div_scale_f32 v202, s[84:85], v198, v198, v78
	v_div_scale_f32 v203, s[84:85], v199, v199, v79
	v_div_scale_f32 v204, s[84:85], v200, v200, v80
	v_div_scale_f32 v205, s[84:85], v201, v201, v81
	v_rcp_f32_e32 v206, v202
	v_rcp_f32_e32 v207, v203
	v_rcp_f32_e32 v208, v204
	v_rcp_f32_e32 v209, v205
	s_nop 0
	v_div_scale_f32 v210, vcc, v78, v198, v78
	v_fma_f32 v212, -v202, v206, 1.0
	v_fmac_f32_e32 v206, v212, v206
	v_mul_f32_e32 v211, v210, v206
	v_fma_f32 v212, -v202, v211, v210
	v_fmac_f32_e32 v211, v212, v206
	v_fma_f32 v212, -v202, v211, v210
	v_div_fmas_f32 v212, v212, v206, v211
	v_div_fixup_f32 v78, v212, v198, v78
	v_div_scale_f32 v210, vcc, v79, v199, v79
	v_fma_f32 v212, -v203, v207, 1.0
	v_fmac_f32_e32 v207, v212, v207
	v_mul_f32_e32 v211, v210, v207
	v_fma_f32 v212, -v203, v211, v210
	v_fmac_f32_e32 v211, v212, v207
	v_fma_f32 v212, -v203, v211, v210
	v_div_fmas_f32 v212, v212, v207, v211
	v_div_fixup_f32 v79, v212, v199, v79
	v_div_scale_f32 v210, vcc, v80, v200, v80
	v_fma_f32 v212, -v204, v208, 1.0
	v_fmac_f32_e32 v208, v212, v208
	v_mul_f32_e32 v211, v210, v208
	v_fma_f32 v212, -v204, v211, v210
	v_fmac_f32_e32 v211, v212, v208
	v_fma_f32 v212, -v204, v211, v210
	v_div_fmas_f32 v212, v212, v208, v211
	v_div_fixup_f32 v80, v212, v200, v80
	v_div_scale_f32 v210, vcc, v81, v201, v81
	v_fma_f32 v212, -v205, v209, 1.0
	v_fmac_f32_e32 v209, v212, v209
	v_mul_f32_e32 v211, v210, v209
	v_fma_f32 v212, -v205, v211, v210
	v_fmac_f32_e32 v211, v212, v209
	v_fma_f32 v212, -v205, v211, v210
	v_div_fmas_f32 v212, v212, v209, v211
	v_div_fixup_f32 v81, v212, v201, v81
	v_mul_f32_e32 v198, 0xbfb8aa3b, v82
	v_mul_f32_e32 v199, 0xbfb8aa3b, v83
	v_mul_f32_e32 v200, 0xbfb8aa3b, v84
	v_mul_f32_e32 v201, 0xbfb8aa3b, v85
	v_exp_f32_e32 v198, v198
	v_exp_f32_e32 v199, v199
	v_exp_f32_e32 v200, v200
	v_exp_f32_e32 v201, v201
	s_nop 0
	v_add_f32_e32 v198, 1.0, v198
	v_add_f32_e32 v199, 1.0, v199
	v_add_f32_e32 v200, 1.0, v200
	v_add_f32_e32 v201, 1.0, v201
	v_div_scale_f32 v202, s[84:85], v198, v198, v82
	v_div_scale_f32 v203, s[84:85], v199, v199, v83
	v_div_scale_f32 v204, s[84:85], v200, v200, v84
	v_div_scale_f32 v205, s[84:85], v201, v201, v85
	v_rcp_f32_e32 v206, v202
	v_rcp_f32_e32 v207, v203
	v_rcp_f32_e32 v208, v204
	v_rcp_f32_e32 v209, v205
	s_nop 0
	v_div_scale_f32 v210, vcc, v82, v198, v82
	v_fma_f32 v212, -v202, v206, 1.0
	v_fmac_f32_e32 v206, v212, v206
	v_mul_f32_e32 v211, v210, v206
	v_fma_f32 v212, -v202, v211, v210
	v_fmac_f32_e32 v211, v212, v206
	v_fma_f32 v212, -v202, v211, v210
	v_div_fmas_f32 v212, v212, v206, v211
	v_div_fixup_f32 v82, v212, v198, v82
	v_div_scale_f32 v210, vcc, v83, v199, v83
	v_fma_f32 v212, -v203, v207, 1.0
	v_fmac_f32_e32 v207, v212, v207
	v_mul_f32_e32 v211, v210, v207
	v_fma_f32 v212, -v203, v211, v210
	v_fmac_f32_e32 v211, v212, v207
	v_fma_f32 v212, -v203, v211, v210
	v_div_fmas_f32 v212, v212, v207, v211
	v_div_fixup_f32 v83, v212, v199, v83
	v_div_scale_f32 v210, vcc, v84, v200, v84
	v_fma_f32 v212, -v204, v208, 1.0
	v_fmac_f32_e32 v208, v212, v208
	v_mul_f32_e32 v211, v210, v208
	v_fma_f32 v212, -v204, v211, v210
	v_fmac_f32_e32 v211, v212, v208
	v_fma_f32 v212, -v204, v211, v210
	v_div_fmas_f32 v212, v212, v208, v211
	v_div_fixup_f32 v84, v212, v200, v84
	v_div_scale_f32 v210, vcc, v85, v201, v85
	v_fma_f32 v212, -v205, v209, 1.0
	v_fmac_f32_e32 v209, v212, v209
	v_mul_f32_e32 v211, v210, v209
	v_fma_f32 v212, -v205, v211, v210
	v_fmac_f32_e32 v211, v212, v209
	v_fma_f32 v212, -v205, v211, v210
	v_div_fmas_f32 v212, v212, v209, v211
	v_div_fixup_f32 v85, v212, v201, v85
	v_mul_f32_e32 v198, 0xbfb8aa3b, v86
	v_mul_f32_e32 v199, 0xbfb8aa3b, v87
	v_mul_f32_e32 v200, 0xbfb8aa3b, v88
	v_mul_f32_e32 v201, 0xbfb8aa3b, v89
	v_exp_f32_e32 v198, v198
	v_exp_f32_e32 v199, v199
	v_exp_f32_e32 v200, v200
	v_exp_f32_e32 v201, v201
	s_nop 0
	v_add_f32_e32 v198, 1.0, v198
	v_add_f32_e32 v199, 1.0, v199
	v_add_f32_e32 v200, 1.0, v200
	v_add_f32_e32 v201, 1.0, v201
	v_div_scale_f32 v202, s[84:85], v198, v198, v86
	v_div_scale_f32 v203, s[84:85], v199, v199, v87
	v_div_scale_f32 v204, s[84:85], v200, v200, v88
	v_div_scale_f32 v205, s[84:85], v201, v201, v89
	v_rcp_f32_e32 v206, v202
	v_rcp_f32_e32 v207, v203
	v_rcp_f32_e32 v208, v204
	v_rcp_f32_e32 v209, v205
	s_nop 0
	v_div_scale_f32 v210, vcc, v86, v198, v86
	v_fma_f32 v212, -v202, v206, 1.0
	v_fmac_f32_e32 v206, v212, v206
	v_mul_f32_e32 v211, v210, v206
	v_fma_f32 v212, -v202, v211, v210
	v_fmac_f32_e32 v211, v212, v206
	v_fma_f32 v212, -v202, v211, v210
	v_div_fmas_f32 v212, v212, v206, v211
	v_div_fixup_f32 v86, v212, v198, v86
	v_div_scale_f32 v210, vcc, v87, v199, v87
	v_fma_f32 v212, -v203, v207, 1.0
	v_fmac_f32_e32 v207, v212, v207
	v_mul_f32_e32 v211, v210, v207
	v_fma_f32 v212, -v203, v211, v210
	v_fmac_f32_e32 v211, v212, v207
	v_fma_f32 v212, -v203, v211, v210
	v_div_fmas_f32 v212, v212, v207, v211
	v_div_fixup_f32 v87, v212, v199, v87
	v_div_scale_f32 v210, vcc, v88, v200, v88
	v_fma_f32 v212, -v204, v208, 1.0
	v_fmac_f32_e32 v208, v212, v208
	v_mul_f32_e32 v211, v210, v208
	v_fma_f32 v212, -v204, v211, v210
	v_fmac_f32_e32 v211, v212, v208
	v_fma_f32 v212, -v204, v211, v210
	v_div_fmas_f32 v212, v212, v208, v211
	v_div_fixup_f32 v88, v212, v200, v88
	v_div_scale_f32 v210, vcc, v89, v201, v89
	v_fma_f32 v212, -v205, v209, 1.0
	v_fmac_f32_e32 v209, v212, v209
	v_mul_f32_e32 v211, v210, v209
	v_fma_f32 v212, -v205, v211, v210
	v_fmac_f32_e32 v211, v212, v209
	v_fma_f32 v212, -v205, v211, v210
	v_div_fmas_f32 v212, v212, v209, v211
	v_div_fixup_f32 v89, v212, v201, v89
	v_mul_f32_e32 v198, 0xbfb8aa3b, v90
	v_mul_f32_e32 v199, 0xbfb8aa3b, v91
	v_mul_f32_e32 v200, 0xbfb8aa3b, v92
	v_mul_f32_e32 v201, 0xbfb8aa3b, v93
	v_exp_f32_e32 v198, v198
	v_exp_f32_e32 v199, v199
	v_exp_f32_e32 v200, v200
	v_exp_f32_e32 v201, v201
	s_nop 0
	v_add_f32_e32 v198, 1.0, v198
	v_add_f32_e32 v199, 1.0, v199
	v_add_f32_e32 v200, 1.0, v200
	v_add_f32_e32 v201, 1.0, v201
	v_div_scale_f32 v202, s[84:85], v198, v198, v90
	v_div_scale_f32 v203, s[84:85], v199, v199, v91
	v_div_scale_f32 v204, s[84:85], v200, v200, v92
	v_div_scale_f32 v205, s[84:85], v201, v201, v93
	v_rcp_f32_e32 v206, v202
	v_rcp_f32_e32 v207, v203
	v_rcp_f32_e32 v208, v204
	v_rcp_f32_e32 v209, v205
	s_nop 0
	v_div_scale_f32 v210, vcc, v90, v198, v90
	v_fma_f32 v212, -v202, v206, 1.0
	v_fmac_f32_e32 v206, v212, v206
	v_mul_f32_e32 v211, v210, v206
	v_fma_f32 v212, -v202, v211, v210
	v_fmac_f32_e32 v211, v212, v206
	v_fma_f32 v212, -v202, v211, v210
	v_div_fmas_f32 v212, v212, v206, v211
	v_div_fixup_f32 v90, v212, v198, v90
	v_div_scale_f32 v210, vcc, v91, v199, v91
	v_fma_f32 v212, -v203, v207, 1.0
	v_fmac_f32_e32 v207, v212, v207
	v_mul_f32_e32 v211, v210, v207
	v_fma_f32 v212, -v203, v211, v210
	v_fmac_f32_e32 v211, v212, v207
	v_fma_f32 v212, -v203, v211, v210
	v_div_fmas_f32 v212, v212, v207, v211
	v_div_fixup_f32 v91, v212, v199, v91
	v_div_scale_f32 v210, vcc, v92, v200, v92
	v_fma_f32 v212, -v204, v208, 1.0
	v_fmac_f32_e32 v208, v212, v208
	v_mul_f32_e32 v211, v210, v208
	v_fma_f32 v212, -v204, v211, v210
	v_fmac_f32_e32 v211, v212, v208
	v_fma_f32 v212, -v204, v211, v210
	v_div_fmas_f32 v212, v212, v208, v211
	v_div_fixup_f32 v92, v212, v200, v92
	v_div_scale_f32 v210, vcc, v93, v201, v93
	v_fma_f32 v212, -v205, v209, 1.0
	v_fmac_f32_e32 v209, v212, v209
	v_mul_f32_e32 v211, v210, v209
	v_fma_f32 v212, -v205, v211, v210
	v_fmac_f32_e32 v211, v212, v209
	v_fma_f32 v212, -v205, v211, v210
	v_div_fmas_f32 v212, v212, v209, v211
	v_div_fixup_f32 v93, v212, v201, v93
	v_mul_f32_e32 v198, 0xbfb8aa3b, v94
	v_mul_f32_e32 v199, 0xbfb8aa3b, v95
	v_mul_f32_e32 v200, 0xbfb8aa3b, v96
	v_mul_f32_e32 v201, 0xbfb8aa3b, v97
	v_exp_f32_e32 v198, v198
	v_exp_f32_e32 v199, v199
	v_exp_f32_e32 v200, v200
	v_exp_f32_e32 v201, v201
	s_nop 0
	v_add_f32_e32 v198, 1.0, v198
	v_add_f32_e32 v199, 1.0, v199
	v_add_f32_e32 v200, 1.0, v200
	v_add_f32_e32 v201, 1.0, v201
	v_div_scale_f32 v202, s[84:85], v198, v198, v94
	v_div_scale_f32 v203, s[84:85], v199, v199, v95
	v_div_scale_f32 v204, s[84:85], v200, v200, v96
	v_div_scale_f32 v205, s[84:85], v201, v201, v97
	v_rcp_f32_e32 v206, v202
	v_rcp_f32_e32 v207, v203
	v_rcp_f32_e32 v208, v204
	v_rcp_f32_e32 v209, v205
	s_nop 0
	v_div_scale_f32 v210, vcc, v94, v198, v94
	v_fma_f32 v212, -v202, v206, 1.0
	v_fmac_f32_e32 v206, v212, v206
	v_mul_f32_e32 v211, v210, v206
	v_fma_f32 v212, -v202, v211, v210
	v_fmac_f32_e32 v211, v212, v206
	v_fma_f32 v212, -v202, v211, v210
	v_div_fmas_f32 v212, v212, v206, v211
	v_div_fixup_f32 v94, v212, v198, v94
	v_div_scale_f32 v210, vcc, v95, v199, v95
	v_fma_f32 v212, -v203, v207, 1.0
	v_fmac_f32_e32 v207, v212, v207
	v_mul_f32_e32 v211, v210, v207
	v_fma_f32 v212, -v203, v211, v210
	v_fmac_f32_e32 v211, v212, v207
	v_fma_f32 v212, -v203, v211, v210
	v_div_fmas_f32 v212, v212, v207, v211
	v_div_fixup_f32 v95, v212, v199, v95
	v_div_scale_f32 v210, vcc, v96, v200, v96
	v_fma_f32 v212, -v204, v208, 1.0
	v_fmac_f32_e32 v208, v212, v208
	v_mul_f32_e32 v211, v210, v208
	v_fma_f32 v212, -v204, v211, v210
	v_fmac_f32_e32 v211, v212, v208
	v_fma_f32 v212, -v204, v211, v210
	v_div_fmas_f32 v212, v212, v208, v211
	v_div_fixup_f32 v96, v212, v200, v96
	v_div_scale_f32 v210, vcc, v97, v201, v97
	v_fma_f32 v212, -v205, v209, 1.0
	v_fmac_f32_e32 v209, v212, v209
	v_mul_f32_e32 v211, v210, v209
	v_fma_f32 v212, -v205, v211, v210
	v_fmac_f32_e32 v211, v212, v209
	v_fma_f32 v212, -v205, v211, v210
	v_div_fmas_f32 v212, v212, v209, v211
	v_div_fixup_f32 v97, v212, v201, v97
	s_branch G1E_ph2_ST
G1E_ph2_U:
	s_load_dwordx2 s[82:83], s[0:1], 0x108
G1E_ph2_ST:
	v_and_b32_e32 v223, 31, v0
	v_mul_u32_u24_e32 v220, 0x110, v223
	v_bfe_u32 v223, v0, 5, 1
	v_lshl_add_u32 v220, v223, 4, v220
	v_bfe_u32 v224, v0, 6, 2
	v_mul_u32_u24_e32 v223, 0x2200, v224
	v_add_u32_e32 v220, v220, v223
	v_bfe_u32 v222, v0, 4, 2
	v_mul_u32_u24_e32 v221, 0x110, v222
	v_add_u32_e32 v221, v221, v223
	v_and_b32_e32 v223, 15, v0
	v_lshl_add_u32 v221, v223, 4, v221
	s_and_b32 s84, s35, 63
	s_mulk_i32 s84, 0xc0
	s_lshr_b32 s85, s35, 6
	s_and_b32 s85, s85, 7
	s_lshl_b32 s85, s85, 8
	v_lshrrev_b32_e32 v224, 1, v224
	v_mul_u32_u24_e32 v224, 0x60, v224
	v_add3_u32 v222, v222, v224, s84
	v_lshlrev_b32_e32 v222, 11, v222
	v_lshl_add_u32 v222, v223, 3, v222
	v_bfe_u32 v223, v0, 6, 1
	v_lshl_add_u32 v222, v223, 7, v222
	v_add_u32_e32 v222, s85, v222
	ds_write_b128 v220, v[82:85]
	ds_write_b128 v220, v[86:89] offset:32
	ds_write_b128 v220, v[90:93] offset:64
	ds_write_b128 v220, v[94:97] offset:96
	ds_write_b128 v220, v[66:69] offset:128
	ds_write_b128 v220, v[70:73] offset:160
	ds_write_b128 v220, v[74:77] offset:192
	ds_write_b128 v220, v[78:81] offset:224
	v_mov_b32_e32 v230, v222
	v_add_u32_e32 v231, 0x2000, v222
	v_add_u32_e32 v232, 0x4000, v222
	v_add_u32_e32 v233, 0x6000, v222
	v_add_u32_e32 v234, 0x8000, v222
	v_add_u32_e32 v235, 0xa000, v222
	v_add_u32_e32 v236, 0xc000, v222
	v_add_u32_e32 v237, 0xe000, v222
	s_waitcnt lgkmcnt(0)
	ds_read_b128 v[82:85], v221
	ds_read_b128 v[86:89], v221 offset:1088
	ds_read_b128 v[90:93], v221 offset:2176
	ds_read_b128 v[94:97], v221 offset:3264
	ds_read_b128 v[66:69], v221 offset:4352
	ds_read_b128 v[70:73], v221 offset:5440
	ds_read_b128 v[74:77], v221 offset:6528
	ds_read_b128 v[78:81], v221 offset:7616
	s_waitcnt lgkmcnt(7)
	v_cvt_pk_bf16_f32 v82, v82, v83
	v_cvt_pk_bf16_f32 v83, v84, v85
	global_store_dwordx2 v230, v[82:83], s[82:83]
	s_waitcnt lgkmcnt(6)
	v_cvt_pk_bf16_f32 v86, v86, v87
	v_cvt_pk_bf16_f32 v87, v88, v89
	global_store_dwordx2 v231, v[86:87], s[82:83]
	s_waitcnt lgkmcnt(5)
	v_cvt_pk_bf16_f32 v90, v90, v91
	v_cvt_pk_bf16_f32 v91, v92, v93
	global_store_dwordx2 v232, v[90:91], s[82:83]
	s_waitcnt lgkmcnt(4)
	v_cvt_pk_bf16_f32 v94, v94, v95
	v_cvt_pk_bf16_f32 v95, v96, v97
	global_store_dwordx2 v233, v[94:95], s[82:83]
	s_waitcnt lgkmcnt(3)
	v_cvt_pk_bf16_f32 v66, v66, v67
	v_cvt_pk_bf16_f32 v67, v68, v69
	global_store_dwordx2 v234, v[66:67], s[82:83]
	s_waitcnt lgkmcnt(2)
	v_cvt_pk_bf16_f32 v70, v70, v71
	v_cvt_pk_bf16_f32 v71, v72, v73
	global_store_dwordx2 v235, v[70:71], s[82:83]
	s_waitcnt lgkmcnt(1)
	v_cvt_pk_bf16_f32 v74, v74, v75
	v_cvt_pk_bf16_f32 v75, v76, v77
	global_store_dwordx2 v236, v[74:75], s[82:83]
	s_waitcnt lgkmcnt(0)
	v_cvt_pk_bf16_f32 v78, v78, v79
	v_cvt_pk_bf16_f32 v79, v80, v81
	global_store_dwordx2 v237, v[78:79], s[82:83]
	ds_write_b128 v220, v[50:53]
	ds_write_b128 v220, v[54:57] offset:32
	ds_write_b128 v220, v[58:61] offset:64
	ds_write_b128 v220, v[62:65] offset:96
	ds_write_b128 v220, v[34:37] offset:128
	ds_write_b128 v220, v[38:41] offset:160
	ds_write_b128 v220, v[42:45] offset:192
	ds_write_b128 v220, v[46:49] offset:224
	v_add_u32_e32 v230, 0x10000, v222
	v_add_u32_e32 v231, 0x12000, v222
	v_add_u32_e32 v232, 0x14000, v222
	v_add_u32_e32 v233, 0x16000, v222
	v_add_u32_e32 v234, 0x18000, v222
	v_add_u32_e32 v235, 0x1a000, v222
	v_add_u32_e32 v236, 0x1c000, v222
	v_add_u32_e32 v237, 0x1e000, v222
	s_waitcnt lgkmcnt(0)
	ds_read_b128 v[50:53], v221
	ds_read_b128 v[54:57], v221 offset:1088
	ds_read_b128 v[58:61], v221 offset:2176
	ds_read_b128 v[62:65], v221 offset:3264
	ds_read_b128 v[34:37], v221 offset:4352
	ds_read_b128 v[38:41], v221 offset:5440
	ds_read_b128 v[42:45], v221 offset:6528
	ds_read_b128 v[46:49], v221 offset:7616
	s_waitcnt lgkmcnt(7)
	v_cvt_pk_bf16_f32 v50, v50, v51
	v_cvt_pk_bf16_f32 v51, v52, v53
	global_store_dwordx2 v230, v[50:51], s[82:83]
	s_waitcnt lgkmcnt(6)
	v_cvt_pk_bf16_f32 v54, v54, v55
	v_cvt_pk_bf16_f32 v55, v56, v57
	global_store_dwordx2 v231, v[54:55], s[82:83]
	s_waitcnt lgkmcnt(5)
	v_cvt_pk_bf16_f32 v58, v58, v59
	v_cvt_pk_bf16_f32 v59, v60, v61
	global_store_dwordx2 v232, v[58:59], s[82:83]
	s_waitcnt lgkmcnt(4)
	v_cvt_pk_bf16_f32 v62, v62, v63
	v_cvt_pk_bf16_f32 v63, v64, v65
	global_store_dwordx2 v233, v[62:63], s[82:83]
	s_waitcnt lgkmcnt(3)
	v_cvt_pk_bf16_f32 v34, v34, v35
	v_cvt_pk_bf16_f32 v35, v36, v37
	global_store_dwordx2 v234, v[34:35], s[82:83]
	s_waitcnt lgkmcnt(2)
	v_cvt_pk_bf16_f32 v38, v38, v39
	v_cvt_pk_bf16_f32 v39, v40, v41
	global_store_dwordx2 v235, v[38:39], s[82:83]
	s_waitcnt lgkmcnt(1)
	v_cvt_pk_bf16_f32 v42, v42, v43
	v_cvt_pk_bf16_f32 v43, v44, v45
	global_store_dwordx2 v236, v[42:43], s[82:83]
	s_waitcnt lgkmcnt(0)
	v_cvt_pk_bf16_f32 v46, v46, v47
	v_cvt_pk_bf16_f32 v47, v48, v49
	global_store_dwordx2 v237, v[46:47], s[82:83]
	ds_write_b128 v220, v[18:21]
	ds_write_b128 v220, v[22:25] offset:32
	ds_write_b128 v220, v[26:29] offset:64
	ds_write_b128 v220, v[30:33] offset:96
	ds_write_b128 v220, v[2:5] offset:128
	ds_write_b128 v220, v[6:9] offset:160
	ds_write_b128 v220, v[10:13] offset:192
	ds_write_b128 v220, v[14:17] offset:224
	v_add_u32_e32 v230, 0x20000, v222
	v_add_u32_e32 v231, 0x22000, v222
	v_add_u32_e32 v232, 0x24000, v222
	v_add_u32_e32 v233, 0x26000, v222
	v_add_u32_e32 v234, 0x28000, v222
	v_add_u32_e32 v235, 0x2a000, v222
	v_add_u32_e32 v236, 0x2c000, v222
	v_add_u32_e32 v237, 0x2e000, v222
	s_waitcnt lgkmcnt(0)
	ds_read_b128 v[18:21], v221
	ds_read_b128 v[22:25], v221 offset:1088
	ds_read_b128 v[26:29], v221 offset:2176
	ds_read_b128 v[30:33], v221 offset:3264
	ds_read_b128 v[2:5], v221 offset:4352
	ds_read_b128 v[6:9], v221 offset:5440
	ds_read_b128 v[10:13], v221 offset:6528
	ds_read_b128 v[14:17], v221 offset:7616
	s_waitcnt lgkmcnt(7)
	v_cvt_pk_bf16_f32 v18, v18, v19
	v_cvt_pk_bf16_f32 v19, v20, v21
	global_store_dwordx2 v230, v[18:19], s[82:83]
	s_waitcnt lgkmcnt(6)
	v_cvt_pk_bf16_f32 v22, v22, v23
	v_cvt_pk_bf16_f32 v23, v24, v25
	global_store_dwordx2 v231, v[22:23], s[82:83]
	s_waitcnt lgkmcnt(5)
	v_cvt_pk_bf16_f32 v26, v26, v27
	v_cvt_pk_bf16_f32 v27, v28, v29
	global_store_dwordx2 v232, v[26:27], s[82:83]
	s_waitcnt lgkmcnt(4)
	v_cvt_pk_bf16_f32 v30, v30, v31
	v_cvt_pk_bf16_f32 v31, v32, v33
	global_store_dwordx2 v233, v[30:31], s[82:83]
	s_waitcnt lgkmcnt(3)
	v_cvt_pk_bf16_f32 v2, v2, v3
	v_cvt_pk_bf16_f32 v3, v4, v5
	global_store_dwordx2 v234, v[2:3], s[82:83]
	s_waitcnt lgkmcnt(2)
	v_cvt_pk_bf16_f32 v6, v6, v7
	v_cvt_pk_bf16_f32 v7, v8, v9
	global_store_dwordx2 v235, v[6:7], s[82:83]
	s_waitcnt lgkmcnt(1)
	v_cvt_pk_bf16_f32 v10, v10, v11
	v_cvt_pk_bf16_f32 v11, v12, v13
	global_store_dwordx2 v236, v[10:11], s[82:83]
	s_waitcnt lgkmcnt(0)
	v_cvt_pk_bf16_f32 v14, v14, v15
	v_cvt_pk_bf16_f32 v15, v16, v17
	global_store_dwordx2 v237, v[14:15], s[82:83]
	s_barrier
	s_mov_b64 s[4:5], exec
	s_branch .LBB0_149

.Lgm_ph17_loop:
	s_waitcnt lgkmcnt(1)
	v_mfma_f32_32x32x16_bf16 v[82:97], v[240:243], v[252:255], v[82:97]
	ds_read_b128 v[220:223], v210 offset:0
	s_add_u32 m0, s81, 0x5000
	s_nop 0
	global_load_lds_dwordx4 v202, s[70:71]
	v_mfma_f32_32x32x16_bf16 v[66:81], v[236:239], v[252:255], v[66:81]
	ds_read_b128 v[232:235], v214 offset:0
	s_add_u32 m0, s82, 0x0
	s_nop 0
	global_load_lds_dwordx4 v207, s[72:73]
	v_mfma_f32_32x32x16_bf16 v[50:65], v[240:243], v[248:251], v[50:65]
	ds_read_b128 v[216:219], v210 offset:4096
	s_add_u32 m0, s82, 0x1000
	s_nop 0
	global_load_lds_dwordx4 v206, s[72:73]
	v_mfma_f32_32x32x16_bf16 v[34:49], v[236:239], v[248:251], v[34:49]
	ds_read_b128 v[228:231], v214 offset:4096
	s_add_u32 m0, s82, 0x2000
	s_nop 0
	global_load_lds_dwordx4 v205, s[72:73]
	s_waitcnt lgkmcnt(4)
	v_mfma_f32_32x32x16_bf16 v[18:33], v[240:243], v[244:247], v[18:33]
	ds_read_b128 v[224:227], v214 offset:8192
	v_mfma_f32_32x32x16_bf16 v[2:17], v[236:239], v[244:247], v[2:17]
	s_add_u32 m0, s82, 0x3000
	s_nop 0
	global_load_lds_dwordx4 v204, s[72:73]
	s_waitcnt lgkmcnt(1)
	v_mfma_f32_32x32x16_bf16 v[82:97], v[220:223], v[232:235], v[82:97]
	ds_read_b128 v[240:243], v209 offset:0
	v_mfma_f32_32x32x16_bf16 v[66:81], v[216:219], v[232:235], v[66:81]
	ds_read_b128 v[252:255], v213 offset:0
	v_mfma_f32_32x32x16_bf16 v[50:65], v[220:223], v[228:231], v[50:65]
	ds_read_b128 v[236:239], v209 offset:4096
	v_mfma_f32_32x32x16_bf16 v[34:49], v[216:219], v[228:231], v[34:49]
	ds_read_b128 v[248:251], v213 offset:4096
	s_waitcnt lgkmcnt(4)
	v_mfma_f32_32x32x16_bf16 v[18:33], v[220:223], v[224:227], v[18:33]
	ds_read_b128 v[244:247], v213 offset:8192
	v_mfma_f32_32x32x16_bf16 v[2:17], v[216:219], v[224:227], v[2:17]
	s_waitcnt lgkmcnt(1)
	v_mfma_f32_32x32x16_bf16 v[82:97], v[240:243], v[252:255], v[82:97]
	ds_read_b128 v[220:223], v208 offset:0
	s_add_u32 s83, s79, s78
	s_add_u32 s83, s83, 2
	s_and_b32 s83, s83, 15
	v_mfma_f32_32x32x16_bf16 v[66:81], v[236:239], v[252:255], v[66:81]
	ds_read_b128 v[232:235], v212 offset:0
	s_lshl_b32 s83, s83, 7
	s_add_u32 s70, s66, s83
	v_mfma_f32_32x32x16_bf16 v[50:65], v[240:243], v[248:251], v[50:65]
	ds_read_b128 v[216:219], v208 offset:4096
	s_addc_u32 s71, s67, 0
	s_add_u32 s72, s68, s83
	v_mfma_f32_32x32x16_bf16 v[34:49], v[236:239], v[248:251], v[34:49]
	ds_read_b128 v[228:231], v212 offset:4096
	s_addc_u32 s73, s69, 0
	s_add_u32 s81, s80, 0x0
	s_add_u32 s82, s80, 0xc000
	s_waitcnt lgkmcnt(4)
	v_mfma_f32_32x32x16_bf16 v[18:33], v[240:243], v[244:247], v[18:33]
	ds_read_b128 v[224:227], v212 offset:8192
	v_mfma_f32_32x32x16_bf16 v[2:17], v[236:239], v[244:247], v[2:17]
	s_waitcnt vmcnt(0) lgkmcnt(0)
	s_barrier
	v_mfma_f32_32x32x16_bf16 v[82:97], v[220:223], v[232:235], v[82:97]
	s_add_u32 m0, s81, 0x0
	ds_read_b128 v[240:243], v211 offset:16384
	global_load_lds_dwordx4 v207, s[70:71]
	v_mfma_f32_32x32x16_bf16 v[66:81], v[216:219], v[232:235], v[66:81]
	s_add_u32 m0, s81, 0x1000
	ds_read_b128 v[252:255], v215 offset:24576
	global_load_lds_dwordx4 v206, s[70:71]
	v_mfma_f32_32x32x16_bf16 v[50:65], v[220:223], v[228:231], v[50:65]
	s_add_u32 m0, s81, 0x2000
	ds_read_b128 v[236:239], v211 offset:20480
	global_load_lds_dwordx4 v205, s[70:71]
	v_mfma_f32_32x32x16_bf16 v[34:49], v[216:219], v[228:231], v[34:49]
	s_add_u32 m0, s81, 0x3000
	ds_read_b128 v[248:251], v215 offset:28672
	global_load_lds_dwordx4 v204, s[70:71]
	v_mfma_f32_32x32x16_bf16 v[18:33], v[220:223], v[224:227], v[18:33]
	s_add_u32 m0, s81, 0x4000
	ds_read_b128 v[244:247], v215 offset:32768
	global_load_lds_dwordx4 v203, s[70:71]
	v_mfma_f32_32x32x16_bf16 v[2:17], v[216:219], v[224:227], v[2:17]
	s_waitcnt lgkmcnt(1)
	v_mfma_f32_32x32x16_bf16 v[82:97], v[240:243], v[252:255], v[82:97]
	ds_read_b128 v[220:223], v210 offset:16384
	s_add_u32 m0, s81, 0x5000
	s_nop 0
	global_load_lds_dwordx4 v202, s[70:71]
	v_mfma_f32_32x32x16_bf16 v[66:81], v[236:239], v[252:255], v[66:81]
	ds_read_b128 v[232:235], v214 offset:24576
	s_add_u32 m0, s82, 0x0
	s_nop 0
	global_load_lds_dwordx4 v207, s[72:73]
	v_mfma_f32_32x32x16_bf16 v[50:65], v[240:243], v[248:251], v[50:65]
	ds_read_b128 v[216:219], v210 offset:20480
	s_add_u32 m0, s82, 0x1000
	s_nop 0
	global_load_lds_dwordx4 v206, s[72:73]
	v_mfma_f32_32x32x16_bf16 v[34:49], v[236:239], v[248:251], v[34:49]
	ds_read_b128 v[228:231], v214 offset:28672
	s_add_u32 m0, s82, 0x2000
	s_nop 0
	global_load_lds_dwordx4 v205, s[72:73]
	s_waitcnt lgkmcnt(4)
	v_mfma_f32_32x32x16_bf16 v[18:33], v[240:243], v[244:247], v[18:33]
	ds_read_b128 v[224:227], v214 offset:32768
	v_mfma_f32_32x32x16_bf16 v[2:17], v[236:239], v[244:247], v[2:17]
	s_add_u32 m0, s82, 0x3000
	s_nop 0
	global_load_lds_dwordx4 v204, s[72:73]
	s_waitcnt lgkmcnt(1)
	v_mfma_f32_32x32x16_bf16 v[82:97], v[220:223], v[232:235], v[82:97]
	ds_read_b128 v[240:243], v209 offset:16384
	v_mfma_f32_32x32x16_bf16 v[66:81], v[216:219], v[232:235], v[66:81]
	ds_read_b128 v[252:255], v213 offset:24576
	v_mfma_f32_32x32x16_bf16 v[50:65], v[220:223], v[228:231], v[50:65]
	ds_read_b128 v[236:239], v209 offset:20480
	v_mfma_f32_32x32x16_bf16 v[34:49], v[216:219], v[228:231], v[34:49]
	ds_read_b128 v[248:251], v213 offset:28672
	s_waitcnt lgkmcnt(4)
	v_mfma_f32_32x32x16_bf16 v[18:33], v[220:223], v[224:227], v[18:33]
	ds_read_b128 v[244:247], v213 offset:32768
	v_mfma_f32_32x32x16_bf16 v[2:17], v[216:219], v[224:227], v[2:17]
	s_waitcnt lgkmcnt(1)
	v_mfma_f32_32x32x16_bf16 v[82:97], v[240:243], v[252:255], v[82:97]
	ds_read_b128 v[220:223], v208 offset:16384
	s_add_u32 s83, s79, s78
	s_add_u32 s83, s83, 3
	s_and_b32 s83, s83, 15
	v_mfma_f32_32x32x16_bf16 v[66:81], v[236:239], v[252:255], v[66:81]
	ds_read_b128 v[232:235], v212 offset:24576
	s_lshl_b32 s83, s83, 7
	s_add_u32 s70, s66, s83
	v_mfma_f32_32x32x16_bf16 v[50:65], v[240:243], v[248:251], v[50:65]
	ds_read_b128 v[216:219], v208 offset:20480
	s_addc_u32 s71, s67, 0
	s_add_u32 s72, s68, s83
	v_mfma_f32_32x32x16_bf16 v[34:49], v[236:239], v[248:251], v[34:49]
	ds_read_b128 v[228:231], v212 offset:28672
	s_addc_u32 s73, s69, 0
	s_add_u32 s81, s80, 0x6000
	s_add_u32 s82, s80, 0x10000
	s_waitcnt lgkmcnt(4)
	v_mfma_f32_32x32x16_bf16 v[18:33], v[240:243], v[244:247], v[18:33]
	ds_read_b128 v[224:227], v212 offset:32768
	v_mfma_f32_32x32x16_bf16 v[2:17], v[236:239], v[244:247], v[2:17]
	s_waitcnt vmcnt(0) lgkmcnt(0)
	s_barrier
	v_mfma_f32_32x32x16_bf16 v[82:97], v[220:223], v[232:235], v[82:97]
	s_add_u32 m0, s81, 0x0
	ds_read_b128 v[240:243], v211 offset:0
	global_load_lds_dwordx4 v207, s[70:71]
	v_mfma_f32_32x32x16_bf16 v[66:81], v[216:219], v[232:235], v[66:81]
	s_add_u32 m0, s81, 0x1000
	ds_read_b128 v[252:255], v215 offset:0
	global_load_lds_dwordx4 v206, s[70:71]
	v_mfma_f32_32x32x16_bf16 v[50:65], v[220:223], v[228:231], v[50:65]
	s_add_u32 m0, s81, 0x2000
	ds_read_b128 v[236:239], v211 offset:4096
	global_load_lds_dwordx4 v205, s[70:71]
	v_mfma_f32_32x32x16_bf16 v[34:49], v[216:219], v[228:231], v[34:49]
	s_add_u32 m0, s81, 0x3000
	ds_read_b128 v[248:251], v215 offset:4096
	global_load_lds_dwordx4 v204, s[70:71]
	v_mfma_f32_32x32x16_bf16 v[18:33], v[220:223], v[224:227], v[18:33]
	s_add_u32 m0, s81, 0x4000
	ds_read_b128 v[244:247], v215 offset:8192
	global_load_lds_dwordx4 v203, s[70:71]
	v_mfma_f32_32x32x16_bf16 v[2:17], v[216:219], v[224:227], v[2:17]
	s_add_u32 s78, s78, 2
	s_cmp_lt_u32 s78, 14
	s_cbranch_scc1 .Lgm_ph17_loop
	s_waitcnt lgkmcnt(1)
	v_mfma_f32_32x32x16_bf16 v[82:97], v[240:243], v[252:255], v[82:97]
	ds_read_b128 v[220:223], v210 offset:0
	s_add_u32 m0, s81, 0x5000
	s_nop 0
	global_load_lds_dwordx4 v202, s[70:71]
	v_mfma_f32_32x32x16_bf16 v[66:81], v[236:239], v[252:255], v[66:81]
	ds_read_b128 v[232:235], v214 offset:0
	s_add_u32 m0, s82, 0x0
	s_nop 0
	global_load_lds_dwordx4 v207, s[72:73]
	v_mfma_f32_32x32x16_bf16 v[50:65], v[240:243], v[248:251], v[50:65]
	ds_read_b128 v[216:219], v210 offset:4096
	s_add_u32 m0, s82, 0x1000
	s_nop 0
	global_load_lds_dwordx4 v206, s[72:73]
	v_mfma_f32_32x32x16_bf16 v[34:49], v[236:239], v[248:251], v[34:49]
	ds_read_b128 v[228:231], v214 offset:4096
	s_add_u32 m0, s82, 0x2000
	s_nop 0
	global_load_lds_dwordx4 v205, s[72:73]
	s_waitcnt lgkmcnt(4)
	v_mfma_f32_32x32x16_bf16 v[18:33], v[240:243], v[244:247], v[18:33]
	ds_read_b128 v[224:227], v214 offset:8192
	v_mfma_f32_32x32x16_bf16 v[2:17], v[236:239], v[244:247], v[2:17]
	s_add_u32 m0, s82, 0x3000
	s_nop 0
	global_load_lds_dwordx4 v204, s[72:73]
	s_waitcnt lgkmcnt(1)
	v_mfma_f32_32x32x16_bf16 v[82:97], v[220:223], v[232:235], v[82:97]
	ds_read_b128 v[240:243], v209 offset:0
	v_mfma_f32_32x32x16_bf16 v[66:81], v[216:219], v[232:235], v[66:81]
	ds_read_b128 v[252:255], v213 offset:0
	v_mfma_f32_32x32x16_bf16 v[50:65], v[220:223], v[228:231], v[50:65]
	ds_read_b128 v[236:239], v209 offset:4096
	v_mfma_f32_32x32x16_bf16 v[34:49], v[216:219], v[228:231], v[34:49]
	ds_read_b128 v[248:251], v213 offset:4096
	s_waitcnt lgkmcnt(4)
	v_mfma_f32_32x32x16_bf16 v[18:33], v[220:223], v[224:227], v[18:33]
	ds_read_b128 v[244:247], v213 offset:8192
	v_mfma_f32_32x32x16_bf16 v[2:17], v[216:219], v[224:227], v[2:17]
	s_waitcnt lgkmcnt(1)
	v_mfma_f32_32x32x16_bf16 v[82:97], v[240:243], v[252:255], v[82:97]
	ds_read_b128 v[220:223], v208 offset:0
	v_mfma_f32_32x32x16_bf16 v[66:81], v[236:239], v[252:255], v[66:81]
	ds_read_b128 v[232:235], v212 offset:0
	v_mfma_f32_32x32x16_bf16 v[50:65], v[240:243], v[248:251], v[50:65]
	ds_read_b128 v[216:219], v208 offset:4096
	v_mfma_f32_32x32x16_bf16 v[34:49], v[236:239], v[248:251], v[34:49]
	ds_read_b128 v[228:231], v212 offset:4096
	s_waitcnt lgkmcnt(4)
	v_mfma_f32_32x32x16_bf16 v[18:33], v[240:243], v[244:247], v[18:33]
	ds_read_b128 v[224:227], v212 offset:8192
	v_mfma_f32_32x32x16_bf16 v[2:17], v[236:239], v[244:247], v[2:17]
	s_waitcnt vmcnt(0) lgkmcnt(0)
	s_barrier
	v_mfma_f32_32x32x16_bf16 v[82:97], v[220:223], v[232:235], v[82:97]
	ds_read_b128 v[240:243], v211 offset:16384
	v_mfma_f32_32x32x16_bf16 v[66:81], v[216:219], v[232:235], v[66:81]
	ds_read_b128 v[252:255], v215 offset:24576
	v_mfma_f32_32x32x16_bf16 v[50:65], v[220:223], v[228:231], v[50:65]
	ds_read_b128 v[236:239], v211 offset:20480
	v_mfma_f32_32x32x16_bf16 v[34:49], v[216:219], v[228:231], v[34:49]
	ds_read_b128 v[248:251], v215 offset:28672
	v_mfma_f32_32x32x16_bf16 v[18:33], v[220:223], v[224:227], v[18:33]
	ds_read_b128 v[244:247], v215 offset:32768
	v_mfma_f32_32x32x16_bf16 v[2:17], v[216:219], v[224:227], v[2:17]
	s_waitcnt lgkmcnt(1)
	v_mfma_f32_32x32x16_bf16 v[82:97], v[240:243], v[252:255], v[82:97]
	ds_read_b128 v[220:223], v210 offset:16384
	v_mfma_f32_32x32x16_bf16 v[66:81], v[236:239], v[252:255], v[66:81]
	ds_read_b128 v[232:235], v214 offset:24576
	v_mfma_f32_32x32x16_bf16 v[50:65], v[240:243], v[248:251], v[50:65]
	ds_read_b128 v[216:219], v210 offset:20480
	v_mfma_f32_32x32x16_bf16 v[34:49], v[236:239], v[248:251], v[34:49]
	ds_read_b128 v[228:231], v214 offset:28672
	s_waitcnt lgkmcnt(4)
	v_mfma_f32_32x32x16_bf16 v[18:33], v[240:243], v[244:247], v[18:33]
	ds_read_b128 v[224:227], v214 offset:32768
	v_mfma_f32_32x32x16_bf16 v[2:17], v[236:239], v[244:247], v[2:17]
	s_waitcnt lgkmcnt(1)
	v_mfma_f32_32x32x16_bf16 v[82:97], v[220:223], v[232:235], v[82:97]
	ds_read_b128 v[240:243], v209 offset:16384
	v_mfma_f32_32x32x16_bf16 v[66:81], v[216:219], v[232:235], v[66:81]
	ds_read_b128 v[252:255], v213 offset:24576
	v_mfma_f32_32x32x16_bf16 v[50:65], v[220:223], v[228:231], v[50:65]
	ds_read_b128 v[236:239], v209 offset:20480
	v_mfma_f32_32x32x16_bf16 v[34:49], v[216:219], v[228:231], v[34:49]
	ds_read_b128 v[248:251], v213 offset:28672
	s_waitcnt lgkmcnt(4)
	v_mfma_f32_32x32x16_bf16 v[18:33], v[220:223], v[224:227], v[18:33]
	ds_read_b128 v[244:247], v213 offset:32768
	v_mfma_f32_32x32x16_bf16 v[2:17], v[216:219], v[224:227], v[2:17]
	s_waitcnt lgkmcnt(1)
	v_mfma_f32_32x32x16_bf16 v[82:97], v[240:243], v[252:255], v[82:97]
	ds_read_b128 v[220:223], v208 offset:16384
	v_mfma_f32_32x32x16_bf16 v[66:81], v[236:239], v[252:255], v[66:81]
	ds_read_b128 v[232:235], v212 offset:24576
	v_mfma_f32_32x32x16_bf16 v[50:65], v[240:243], v[248:251], v[50:65]
	ds_read_b128 v[216:219], v208 offset:20480
	v_mfma_f32_32x32x16_bf16 v[34:49], v[236:239], v[248:251], v[34:49]
	ds_read_b128 v[228:231], v212 offset:28672
	s_waitcnt lgkmcnt(4)
	v_mfma_f32_32x32x16_bf16 v[18:33], v[240:243], v[244:247], v[18:33]
	ds_read_b128 v[224:227], v212 offset:32768
	v_mfma_f32_32x32x16_bf16 v[2:17], v[236:239], v[244:247], v[2:17]
	s_waitcnt vmcnt(0) lgkmcnt(0)
	s_barrier
	v_mfma_f32_32x32x16_bf16 v[82:97], v[220:223], v[232:235], v[82:97]
	v_mfma_f32_32x32x16_bf16 v[66:81], v[216:219], v[232:235], v[66:81]
	v_mfma_f32_32x32x16_bf16 v[50:65], v[220:223], v[228:231], v[50:65]
	v_mfma_f32_32x32x16_bf16 v[34:49], v[216:219], v[228:231], v[34:49]
	v_mfma_f32_32x32x16_bf16 v[18:33], v[220:223], v[224:227], v[18:33]
	v_mfma_f32_32x32x16_bf16 v[2:17], v[216:219], v[224:227], v[2:17]
	s_nop 7
	s_nop 7
	s_setprio 0
	s_cmpk_lt_i32 s35, 0x200
	s_cbranch_scc1 G1E_ph17_U
	s_load_dwordx2 s[82:83], s[0:1], 0x98
	v_mul_f32_e32 v198, 0xbfb8aa3b, v2
	v_mul_f32_e32 v199, 0xbfb8aa3b, v3
	v_mul_f32_e32 v200, 0xbfb8aa3b, v4
	v_mul_f32_e32 v201, 0xbfb8aa3b, v5
	v_exp_f32_e32 v198, v198
	v_exp_f32_e32 v199, v199
	v_exp_f32_e32 v200, v200
	v_exp_f32_e32 v201, v201
	s_nop 0
	v_add_f32_e32 v198, 1.0, v198
	v_add_f32_e32 v199, 1.0, v199
	v_add_f32_e32 v200, 1.0, v200
	v_add_f32_e32 v201, 1.0, v201
	v_div_scale_f32 v202, s[84:85], v198, v198, v2
	v_div_scale_f32 v203, s[84:85], v199, v199, v3
	v_div_scale_f32 v204, s[84:85], v200, v200, v4
	v_div_scale_f32 v205, s[84:85], v201, v201, v5
	v_rcp_f32_e32 v206, v202
	v_rcp_f32_e32 v207, v203
	v_rcp_f32_e32 v208, v204
	v_rcp_f32_e32 v209, v205
	s_nop 0
	v_div_scale_f32 v210, vcc, v2, v198, v2
	v_fma_f32 v212, -v202, v206, 1.0
	v_fmac_f32_e32 v206, v212, v206
	v_mul_f32_e32 v211, v210, v206
	v_fma_f32 v212, -v202, v211, v210
	v_fmac_f32_e32 v211, v212, v206
	v_fma_f32 v212, -v202, v211, v210
	v_div_fmas_f32 v212, v212, v206, v211
	v_div_fixup_f32 v2, v212, v198, v2
	v_div_scale_f32 v210, vcc, v3, v199, v3
	v_fma_f32 v212, -v203, v207, 1.0
	v_fmac_f32_e32 v207, v212, v207
	v_mul_f32_e32 v211, v210, v207
	v_fma_f32 v212, -v203, v211, v210
	v_fmac_f32_e32 v211, v212, v207
	v_fma_f32 v212, -v203, v211, v210
	v_div_fmas_f32 v212, v212, v207, v211
	v_div_fixup_f32 v3, v212, v199, v3
	v_div_scale_f32 v210, vcc, v4, v200, v4
	v_fma_f32 v212, -v204, v208, 1.0
	v_fmac_f32_e32 v208, v212, v208
	v_mul_f32_e32 v211, v210, v208
	v_fma_f32 v212, -v204, v211, v210
	v_fmac_f32_e32 v211, v212, v208
	v_fma_f32 v212, -v204, v211, v210
	v_div_fmas_f32 v212, v212, v208, v211
	v_div_fixup_f32 v4, v212, v200, v4
	v_div_scale_f32 v210, vcc, v5, v201, v5
	v_fma_f32 v212, -v205, v209, 1.0
	v_fmac_f32_e32 v209, v212, v209
	v_mul_f32_e32 v211, v210, v209
	v_fma_f32 v212, -v205, v211, v210
	v_fmac_f32_e32 v211, v212, v209
	v_fma_f32 v212, -v205, v211, v210
	v_div_fmas_f32 v212, v212, v209, v211
	v_div_fixup_f32 v5, v212, v201, v5
	v_mul_f32_e32 v198, 0xbfb8aa3b, v6
	v_mul_f32_e32 v199, 0xbfb8aa3b, v7
	v_mul_f32_e32 v200, 0xbfb8aa3b, v8
	v_mul_f32_e32 v201, 0xbfb8aa3b, v9
	v_exp_f32_e32 v198, v198
	v_exp_f32_e32 v199, v199
	v_exp_f32_e32 v200, v200
	v_exp_f32_e32 v201, v201
	s_nop 0
	v_add_f32_e32 v198, 1.0, v198
	v_add_f32_e32 v199, 1.0, v199
	v_add_f32_e32 v200, 1.0, v200
	v_add_f32_e32 v201, 1.0, v201
	v_div_scale_f32 v202, s[84:85], v198, v198, v6
	v_div_scale_f32 v203, s[84:85], v199, v199, v7
	v_div_scale_f32 v204, s[84:85], v200, v200, v8
	v_div_scale_f32 v205, s[84:85], v201, v201, v9
	v_rcp_f32_e32 v206, v202
	v_rcp_f32_e32 v207, v203
	v_rcp_f32_e32 v208, v204
	v_rcp_f32_e32 v209, v205
	s_nop 0
	v_div_scale_f32 v210, vcc, v6, v198, v6
	v_fma_f32 v212, -v202, v206, 1.0
	v_fmac_f32_e32 v206, v212, v206
	v_mul_f32_e32 v211, v210, v206
	v_fma_f32 v212, -v202, v211, v210
	v_fmac_f32_e32 v211, v212, v206
	v_fma_f32 v212, -v202, v211, v210
	v_div_fmas_f32 v212, v212, v206, v211
	v_div_fixup_f32 v6, v212, v198, v6
	v_div_scale_f32 v210, vcc, v7, v199, v7
	v_fma_f32 v212, -v203, v207, 1.0
	v_fmac_f32_e32 v207, v212, v207
	v_mul_f32_e32 v211, v210, v207
	v_fma_f32 v212, -v203, v211, v210
	v_fmac_f32_e32 v211, v212, v207
	v_fma_f32 v212, -v203, v211, v210
	v_div_fmas_f32 v212, v212, v207, v211
	v_div_fixup_f32 v7, v212, v199, v7
	v_div_scale_f32 v210, vcc, v8, v200, v8
	v_fma_f32 v212, -v204, v208, 1.0
	v_fmac_f32_e32 v208, v212, v208
	v_mul_f32_e32 v211, v210, v208
	v_fma_f32 v212, -v204, v211, v210
	v_fmac_f32_e32 v211, v212, v208
	v_fma_f32 v212, -v204, v211, v210
	v_div_fmas_f32 v212, v212, v208, v211
	v_div_fixup_f32 v8, v212, v200, v8
	v_div_scale_f32 v210, vcc, v9, v201, v9
	v_fma_f32 v212, -v205, v209, 1.0
	v_fmac_f32_e32 v209, v212, v209
	v_mul_f32_e32 v211, v210, v209
	v_fma_f32 v212, -v205, v211, v210
	v_fmac_f32_e32 v211, v212, v209
	v_fma_f32 v212, -v205, v211, v210
	v_div_fmas_f32 v212, v212, v209, v211
	v_div_fixup_f32 v9, v212, v201, v9
	v_mul_f32_e32 v198, 0xbfb8aa3b, v10
	v_mul_f32_e32 v199, 0xbfb8aa3b, v11
	v_mul_f32_e32 v200, 0xbfb8aa3b, v12
	v_mul_f32_e32 v201, 0xbfb8aa3b, v13
	v_exp_f32_e32 v198, v198
	v_exp_f32_e32 v199, v199
	v_exp_f32_e32 v200, v200
	v_exp_f32_e32 v201, v201
	s_nop 0
	v_add_f32_e32 v198, 1.0, v198
	v_add_f32_e32 v199, 1.0, v199
	v_add_f32_e32 v200, 1.0, v200
	v_add_f32_e32 v201, 1.0, v201
	v_div_scale_f32 v202, s[84:85], v198, v198, v10
	v_div_scale_f32 v203, s[84:85], v199, v199, v11
	v_div_scale_f32 v204, s[84:85], v200, v200, v12
	v_div_scale_f32 v205, s[84:85], v201, v201, v13
	v_rcp_f32_e32 v206, v202
	v_rcp_f32_e32 v207, v203
	v_rcp_f32_e32 v208, v204
	v_rcp_f32_e32 v209, v205
	s_nop 0
	v_div_scale_f32 v210, vcc, v10, v198, v10
	v_fma_f32 v212, -v202, v206, 1.0
	v_fmac_f32_e32 v206, v212, v206
	v_mul_f32_e32 v211, v210, v206
	v_fma_f32 v212, -v202, v211, v210
	v_fmac_f32_e32 v211, v212, v206
	v_fma_f32 v212, -v202, v211, v210
	v_div_fmas_f32 v212, v212, v206, v211
	v_div_fixup_f32 v10, v212, v198, v10
	v_div_scale_f32 v210, vcc, v11, v199, v11
	v_fma_f32 v212, -v203, v207, 1.0
	v_fmac_f32_e32 v207, v212, v207
	v_mul_f32_e32 v211, v210, v207
	v_fma_f32 v212, -v203, v211, v210
	v_fmac_f32_e32 v211, v212, v207
	v_fma_f32 v212, -v203, v211, v210
	v_div_fmas_f32 v212, v212, v207, v211
	v_div_fixup_f32 v11, v212, v199, v11
	v_div_scale_f32 v210, vcc, v12, v200, v12
	v_fma_f32 v212, -v204, v208, 1.0
	v_fmac_f32_e32 v208, v212, v208
	v_mul_f32_e32 v211, v210, v208
	v_fma_f32 v212, -v204, v211, v210
	v_fmac_f32_e32 v211, v212, v208
	v_fma_f32 v212, -v204, v211, v210
	v_div_fmas_f32 v212, v212, v208, v211
	v_div_fixup_f32 v12, v212, v200, v12
	v_div_scale_f32 v210, vcc, v13, v201, v13
	v_fma_f32 v212, -v205, v209, 1.0
	v_fmac_f32_e32 v209, v212, v209
	v_mul_f32_e32 v211, v210, v209
	v_fma_f32 v212, -v205, v211, v210
	v_fmac_f32_e32 v211, v212, v209
	v_fma_f32 v212, -v205, v211, v210
	v_div_fmas_f32 v212, v212, v209, v211
	v_div_fixup_f32 v13, v212, v201, v13
	v_mul_f32_e32 v198, 0xbfb8aa3b, v14
	v_mul_f32_e32 v199, 0xbfb8aa3b, v15
	v_mul_f32_e32 v200, 0xbfb8aa3b, v16
	v_mul_f32_e32 v201, 0xbfb8aa3b, v17
	v_exp_f32_e32 v198, v198
	v_exp_f32_e32 v199, v199
	v_exp_f32_e32 v200, v200
	v_exp_f32_e32 v201, v201
	s_nop 0
	v_add_f32_e32 v198, 1.0, v198
	v_add_f32_e32 v199, 1.0, v199
	v_add_f32_e32 v200, 1.0, v200
	v_add_f32_e32 v201, 1.0, v201
	v_div_scale_f32 v202, s[84:85], v198, v198, v14
	v_div_scale_f32 v203, s[84:85], v199, v199, v15
	v_div_scale_f32 v204, s[84:85], v200, v200, v16
	v_div_scale_f32 v205, s[84:85], v201, v201, v17
	v_rcp_f32_e32 v206, v202
	v_rcp_f32_e32 v207, v203
	v_rcp_f32_e32 v208, v204
	v_rcp_f32_e32 v209, v205
	s_nop 0
	v_div_scale_f32 v210, vcc, v14, v198, v14
	v_fma_f32 v212, -v202, v206, 1.0
	v_fmac_f32_e32 v206, v212, v206
	v_mul_f32_e32 v211, v210, v206
	v_fma_f32 v212, -v202, v211, v210
	v_fmac_f32_e32 v211, v212, v206
	v_fma_f32 v212, -v202, v211, v210
	v_div_fmas_f32 v212, v212, v206, v211
	v_div_fixup_f32 v14, v212, v198, v14
	v_div_scale_f32 v210, vcc, v15, v199, v15
	v_fma_f32 v212, -v203, v207, 1.0
	v_fmac_f32_e32 v207, v212, v207
	v_mul_f32_e32 v211, v210, v207
	v_fma_f32 v212, -v203, v211, v210
	v_fmac_f32_e32 v211, v212, v207
	v_fma_f32 v212, -v203, v211, v210
	v_div_fmas_f32 v212, v212, v207, v211
	v_div_fixup_f32 v15, v212, v199, v15
	v_div_scale_f32 v210, vcc, v16, v200, v16
	v_fma_f32 v212, -v204, v208, 1.0
	v_fmac_f32_e32 v208, v212, v208
	v_mul_f32_e32 v211, v210, v208
	v_fma_f32 v212, -v204, v211, v210
	v_fmac_f32_e32 v211, v212, v208
	v_fma_f32 v212, -v204, v211, v210
	v_div_fmas_f32 v212, v212, v208, v211
	v_div_fixup_f32 v16, v212, v200, v16
	v_div_scale_f32 v210, vcc, v17, v201, v17
	v_fma_f32 v212, -v205, v209, 1.0
	v_fmac_f32_e32 v209, v212, v209
	v_mul_f32_e32 v211, v210, v209
	v_fma_f32 v212, -v205, v211, v210
	v_fmac_f32_e32 v211, v212, v209
	v_fma_f32 v212, -v205, v211, v210
	v_div_fmas_f32 v212, v212, v209, v211
	v_div_fixup_f32 v17, v212, v201, v17
	v_mul_f32_e32 v198, 0xbfb8aa3b, v18
	v_mul_f32_e32 v199, 0xbfb8aa3b, v19
	v_mul_f32_e32 v200, 0xbfb8aa3b, v20
	v_mul_f32_e32 v201, 0xbfb8aa3b, v21
	v_exp_f32_e32 v198, v198
	v_exp_f32_e32 v199, v199
	v_exp_f32_e32 v200, v200
	v_exp_f32_e32 v201, v201
	s_nop 0
	v_add_f32_e32 v198, 1.0, v198
	v_add_f32_e32 v199, 1.0, v199
	v_add_f32_e32 v200, 1.0, v200
	v_add_f32_e32 v201, 1.0, v201
	v_div_scale_f32 v202, s[84:85], v198, v198, v18
	v_div_scale_f32 v203, s[84:85], v199, v199, v19
	v_div_scale_f32 v204, s[84:85], v200, v200, v20
	v_div_scale_f32 v205, s[84:85], v201, v201, v21
	v_rcp_f32_e32 v206, v202
	v_rcp_f32_e32 v207, v203
	v_rcp_f32_e32 v208, v204
	v_rcp_f32_e32 v209, v205
	s_nop 0
	v_div_scale_f32 v210, vcc, v18, v198, v18
	v_fma_f32 v212, -v202, v206, 1.0
	v_fmac_f32_e32 v206, v212, v206
	v_mul_f32_e32 v211, v210, v206
	v_fma_f32 v212, -v202, v211, v210
	v_fmac_f32_e32 v211, v212, v206
	v_fma_f32 v212, -v202, v211, v210
	v_div_fmas_f32 v212, v212, v206, v211
	v_div_fixup_f32 v18, v212, v198, v18
	v_div_scale_f32 v210, vcc, v19, v199, v19
	v_fma_f32 v212, -v203, v207, 1.0
	v_fmac_f32_e32 v207, v212, v207
	v_mul_f32_e32 v211, v210, v207
	v_fma_f32 v212, -v203, v211, v210
	v_fmac_f32_e32 v211, v212, v207
	v_fma_f32 v212, -v203, v211, v210
	v_div_fmas_f32 v212, v212, v207, v211
	v_div_fixup_f32 v19, v212, v199, v19
	v_div_scale_f32 v210, vcc, v20, v200, v20
	v_fma_f32 v212, -v204, v208, 1.0
	v_fmac_f32_e32 v208, v212, v208
	v_mul_f32_e32 v211, v210, v208
	v_fma_f32 v212, -v204, v211, v210
	v_fmac_f32_e32 v211, v212, v208
	v_fma_f32 v212, -v204, v211, v210
	v_div_fmas_f32 v212, v212, v208, v211
	v_div_fixup_f32 v20, v212, v200, v20
	v_div_scale_f32 v210, vcc, v21, v201, v21
	v_fma_f32 v212, -v205, v209, 1.0
	v_fmac_f32_e32 v209, v212, v209
	v_mul_f32_e32 v211, v210, v209
	v_fma_f32 v212, -v205, v211, v210
	v_fmac_f32_e32 v211, v212, v209
	v_fma_f32 v212, -v205, v211, v210
	v_div_fmas_f32 v212, v212, v209, v211
	v_div_fixup_f32 v21, v212, v201, v21
	v_mul_f32_e32 v198, 0xbfb8aa3b, v22
	v_mul_f32_e32 v199, 0xbfb8aa3b, v23
	v_mul_f32_e32 v200, 0xbfb8aa3b, v24
	v_mul_f32_e32 v201, 0xbfb8aa3b, v25
	v_exp_f32_e32 v198, v198
	v_exp_f32_e32 v199, v199
	v_exp_f32_e32 v200, v200
	v_exp_f32_e32 v201, v201
	s_nop 0
	v_add_f32_e32 v198, 1.0, v198
	v_add_f32_e32 v199, 1.0, v199
	v_add_f32_e32 v200, 1.0, v200
	v_add_f32_e32 v201, 1.0, v201
	v_div_scale_f32 v202, s[84:85], v198, v198, v22
	v_div_scale_f32 v203, s[84:85], v199, v199, v23
	v_div_scale_f32 v204, s[84:85], v200, v200, v24
	v_div_scale_f32 v205, s[84:85], v201, v201, v25
	v_rcp_f32_e32 v206, v202
	v_rcp_f32_e32 v207, v203
	v_rcp_f32_e32 v208, v204
	v_rcp_f32_e32 v209, v205
	s_nop 0
	v_div_scale_f32 v210, vcc, v22, v198, v22
	v_fma_f32 v212, -v202, v206, 1.0
	v_fmac_f32_e32 v206, v212, v206
	v_mul_f32_e32 v211, v210, v206
	v_fma_f32 v212, -v202, v211, v210
	v_fmac_f32_e32 v211, v212, v206
	v_fma_f32 v212, -v202, v211, v210
	v_div_fmas_f32 v212, v212, v206, v211
	v_div_fixup_f32 v22, v212, v198, v22
	v_div_scale_f32 v210, vcc, v23, v199, v23
	v_fma_f32 v212, -v203, v207, 1.0
	v_fmac_f32_e32 v207, v212, v207
	v_mul_f32_e32 v211, v210, v207
	v_fma_f32 v212, -v203, v211, v210
	v_fmac_f32_e32 v211, v212, v207
	v_fma_f32 v212, -v203, v211, v210
	v_div_fmas_f32 v212, v212, v207, v211
	v_div_fixup_f32 v23, v212, v199, v23
	v_div_scale_f32 v210, vcc, v24, v200, v24
	v_fma_f32 v212, -v204, v208, 1.0
	v_fmac_f32_e32 v208, v212, v208
	v_mul_f32_e32 v211, v210, v208
	v_fma_f32 v212, -v204, v211, v210
	v_fmac_f32_e32 v211, v212, v208
	v_fma_f32 v212, -v204, v211, v210
	v_div_fmas_f32 v212, v212, v208, v211
	v_div_fixup_f32 v24, v212, v200, v24
	v_div_scale_f32 v210, vcc, v25, v201, v25
	v_fma_f32 v212, -v205, v209, 1.0
	v_fmac_f32_e32 v209, v212, v209
	v_mul_f32_e32 v211, v210, v209
	v_fma_f32 v212, -v205, v211, v210
	v_fmac_f32_e32 v211, v212, v209
	v_fma_f32 v212, -v205, v211, v210
	v_div_fmas_f32 v212, v212, v209, v211
	v_div_fixup_f32 v25, v212, v201, v25
	v_mul_f32_e32 v198, 0xbfb8aa3b, v26
	v_mul_f32_e32 v199, 0xbfb8aa3b, v27
	v_mul_f32_e32 v200, 0xbfb8aa3b, v28
	v_mul_f32_e32 v201, 0xbfb8aa3b, v29
	v_exp_f32_e32 v198, v198
	v_exp_f32_e32 v199, v199
	v_exp_f32_e32 v200, v200
	v_exp_f32_e32 v201, v201
	s_nop 0
	v_add_f32_e32 v198, 1.0, v198
	v_add_f32_e32 v199, 1.0, v199
	v_add_f32_e32 v200, 1.0, v200
	v_add_f32_e32 v201, 1.0, v201
	v_div_scale_f32 v202, s[84:85], v198, v198, v26
	v_div_scale_f32 v203, s[84:85], v199, v199, v27
	v_div_scale_f32 v204, s[84:85], v200, v200, v28
	v_div_scale_f32 v205, s[84:85], v201, v201, v29
	v_rcp_f32_e32 v206, v202
	v_rcp_f32_e32 v207, v203
	v_rcp_f32_e32 v208, v204
	v_rcp_f32_e32 v209, v205
	s_nop 0
	v_div_scale_f32 v210, vcc, v26, v198, v26
	v_fma_f32 v212, -v202, v206, 1.0
	v_fmac_f32_e32 v206, v212, v206
	v_mul_f32_e32 v211, v210, v206
	v_fma_f32 v212, -v202, v211, v210
	v_fmac_f32_e32 v211, v212, v206
	v_fma_f32 v212, -v202, v211, v210
	v_div_fmas_f32 v212, v212, v206, v211
	v_div_fixup_f32 v26, v212, v198, v26
	v_div_scale_f32 v210, vcc, v27, v199, v27
	v_fma_f32 v212, -v203, v207, 1.0
	v_fmac_f32_e32 v207, v212, v207
	v_mul_f32_e32 v211, v210, v207
	v_fma_f32 v212, -v203, v211, v210
	v_fmac_f32_e32 v211, v212, v207
	v_fma_f32 v212, -v203, v211, v210
	v_div_fmas_f32 v212, v212, v207, v211
	v_div_fixup_f32 v27, v212, v199, v27
	v_div_scale_f32 v210, vcc, v28, v200, v28
	v_fma_f32 v212, -v204, v208, 1.0
	v_fmac_f32_e32 v208, v212, v208
	v_mul_f32_e32 v211, v210, v208
	v_fma_f32 v212, -v204, v211, v210
	v_fmac_f32_e32 v211, v212, v208
	v_fma_f32 v212, -v204, v211, v210
	v_div_fmas_f32 v212, v212, v208, v211
	v_div_fixup_f32 v28, v212, v200, v28
	v_div_scale_f32 v210, vcc, v29, v201, v29
	v_fma_f32 v212, -v205, v209, 1.0
	v_fmac_f32_e32 v209, v212, v209
	v_mul_f32_e32 v211, v210, v209
	v_fma_f32 v212, -v205, v211, v210
	v_fmac_f32_e32 v211, v212, v209
	v_fma_f32 v212, -v205, v211, v210
	v_div_fmas_f32 v212, v212, v209, v211
	v_div_fixup_f32 v29, v212, v201, v29
	v_mul_f32_e32 v198, 0xbfb8aa3b, v30
	v_mul_f32_e32 v199, 0xbfb8aa3b, v31
	v_mul_f32_e32 v200, 0xbfb8aa3b, v32
	v_mul_f32_e32 v201, 0xbfb8aa3b, v33
	v_exp_f32_e32 v198, v198
	v_exp_f32_e32 v199, v199
	v_exp_f32_e32 v200, v200
	v_exp_f32_e32 v201, v201
	s_nop 0
	v_add_f32_e32 v198, 1.0, v198
	v_add_f32_e32 v199, 1.0, v199
	v_add_f32_e32 v200, 1.0, v200
	v_add_f32_e32 v201, 1.0, v201
	v_div_scale_f32 v202, s[84:85], v198, v198, v30
	v_div_scale_f32 v203, s[84:85], v199, v199, v31
	v_div_scale_f32 v204, s[84:85], v200, v200, v32
	v_div_scale_f32 v205, s[84:85], v201, v201, v33
	v_rcp_f32_e32 v206, v202
	v_rcp_f32_e32 v207, v203
	v_rcp_f32_e32 v208, v204
	v_rcp_f32_e32 v209, v205
	s_nop 0
	v_div_scale_f32 v210, vcc, v30, v198, v30
	v_fma_f32 v212, -v202, v206, 1.0
	v_fmac_f32_e32 v206, v212, v206
	v_mul_f32_e32 v211, v210, v206
	v_fma_f32 v212, -v202, v211, v210
	v_fmac_f32_e32 v211, v212, v206
	v_fma_f32 v212, -v202, v211, v210
	v_div_fmas_f32 v212, v212, v206, v211
	v_div_fixup_f32 v30, v212, v198, v30
	v_div_scale_f32 v210, vcc, v31, v199, v31
	v_fma_f32 v212, -v203, v207, 1.0
	v_fmac_f32_e32 v207, v212, v207
	v_mul_f32_e32 v211, v210, v207
	v_fma_f32 v212, -v203, v211, v210
	v_fmac_f32_e32 v211, v212, v207
	v_fma_f32 v212, -v203, v211, v210
	v_div_fmas_f32 v212, v212, v207, v211
	v_div_fixup_f32 v31, v212, v199, v31
	v_div_scale_f32 v210, vcc, v32, v200, v32
	v_fma_f32 v212, -v204, v208, 1.0
	v_fmac_f32_e32 v208, v212, v208
	v_mul_f32_e32 v211, v210, v208
	v_fma_f32 v212, -v204, v211, v210
	v_fmac_f32_e32 v211, v212, v208
	v_fma_f32 v212, -v204, v211, v210
	v_div_fmas_f32 v212, v212, v208, v211
	v_div_fixup_f32 v32, v212, v200, v32
	v_div_scale_f32 v210, vcc, v33, v201, v33
	v_fma_f32 v212, -v205, v209, 1.0
	v_fmac_f32_e32 v209, v212, v209
	v_mul_f32_e32 v211, v210, v209
	v_fma_f32 v212, -v205, v211, v210
	v_fmac_f32_e32 v211, v212, v209
	v_fma_f32 v212, -v205, v211, v210
	v_div_fmas_f32 v212, v212, v209, v211
	v_div_fixup_f32 v33, v212, v201, v33
	v_mul_f32_e32 v198, 0xbfb8aa3b, v34
	v_mul_f32_e32 v199, 0xbfb8aa3b, v35
	v_mul_f32_e32 v200, 0xbfb8aa3b, v36
	v_mul_f32_e32 v201, 0xbfb8aa3b, v37
	v_exp_f32_e32 v198, v198
	v_exp_f32_e32 v199, v199
	v_exp_f32_e32 v200, v200
	v_exp_f32_e32 v201, v201
	s_nop 0
	v_add_f32_e32 v198, 1.0, v198
	v_add_f32_e32 v199, 1.0, v199
	v_add_f32_e32 v200, 1.0, v200
	v_add_f32_e32 v201, 1.0, v201
	v_div_scale_f32 v202, s[84:85], v198, v198, v34
	v_div_scale_f32 v203, s[84:85], v199, v199, v35
	v_div_scale_f32 v204, s[84:85], v200, v200, v36
	v_div_scale_f32 v205, s[84:85], v201, v201, v37
	v_rcp_f32_e32 v206, v202
	v_rcp_f32_e32 v207, v203
	v_rcp_f32_e32 v208, v204
	v_rcp_f32_e32 v209, v205
	s_nop 0
	v_div_scale_f32 v210, vcc, v34, v198, v34
	v_fma_f32 v212, -v202, v206, 1.0
	v_fmac_f32_e32 v206, v212, v206
	v_mul_f32_e32 v211, v210, v206
	v_fma_f32 v212, -v202, v211, v210
	v_fmac_f32_e32 v211, v212, v206
	v_fma_f32 v212, -v202, v211, v210
	v_div_fmas_f32 v212, v212, v206, v211
	v_div_fixup_f32 v34, v212, v198, v34
	v_div_scale_f32 v210, vcc, v35, v199, v35
	v_fma_f32 v212, -v203, v207, 1.0
	v_fmac_f32_e32 v207, v212, v207
	v_mul_f32_e32 v211, v210, v207
	v_fma_f32 v212, -v203, v211, v210
	v_fmac_f32_e32 v211, v212, v207
	v_fma_f32 v212, -v203, v211, v210
	v_div_fmas_f32 v212, v212, v207, v211
	v_div_fixup_f32 v35, v212, v199, v35
	v_div_scale_f32 v210, vcc, v36, v200, v36
	v_fma_f32 v212, -v204, v208, 1.0
	v_fmac_f32_e32 v208, v212, v208
	v_mul_f32_e32 v211, v210, v208
	v_fma_f32 v212, -v204, v211, v210
	v_fmac_f32_e32 v211, v212, v208
	v_fma_f32 v212, -v204, v211, v210
	v_div_fmas_f32 v212, v212, v208, v211
	v_div_fixup_f32 v36, v212, v200, v36
	v_div_scale_f32 v210, vcc, v37, v201, v37
	v_fma_f32 v212, -v205, v209, 1.0
	v_fmac_f32_e32 v209, v212, v209
	v_mul_f32_e32 v211, v210, v209
	v_fma_f32 v212, -v205, v211, v210
	v_fmac_f32_e32 v211, v212, v209
	v_fma_f32 v212, -v205, v211, v210
	v_div_fmas_f32 v212, v212, v209, v211
	v_div_fixup_f32 v37, v212, v201, v37
	v_mul_f32_e32 v198, 0xbfb8aa3b, v38
	v_mul_f32_e32 v199, 0xbfb8aa3b, v39
	v_mul_f32_e32 v200, 0xbfb8aa3b, v40
	v_mul_f32_e32 v201, 0xbfb8aa3b, v41
	v_exp_f32_e32 v198, v198
	v_exp_f32_e32 v199, v199
	v_exp_f32_e32 v200, v200
	v_exp_f32_e32 v201, v201
	s_nop 0
	v_add_f32_e32 v198, 1.0, v198
	v_add_f32_e32 v199, 1.0, v199
	v_add_f32_e32 v200, 1.0, v200
	v_add_f32_e32 v201, 1.0, v201
	v_div_scale_f32 v202, s[84:85], v198, v198, v38
	v_div_scale_f32 v203, s[84:85], v199, v199, v39
	v_div_scale_f32 v204, s[84:85], v200, v200, v40
	v_div_scale_f32 v205, s[84:85], v201, v201, v41
	v_rcp_f32_e32 v206, v202
	v_rcp_f32_e32 v207, v203
	v_rcp_f32_e32 v208, v204
	v_rcp_f32_e32 v209, v205
	s_nop 0
	v_div_scale_f32 v210, vcc, v38, v198, v38
	v_fma_f32 v212, -v202, v206, 1.0
	v_fmac_f32_e32 v206, v212, v206
	v_mul_f32_e32 v211, v210, v206
	v_fma_f32 v212, -v202, v211, v210
	v_fmac_f32_e32 v211, v212, v206
	v_fma_f32 v212, -v202, v211, v210
	v_div_fmas_f32 v212, v212, v206, v211
	v_div_fixup_f32 v38, v212, v198, v38
	v_div_scale_f32 v210, vcc, v39, v199, v39
	v_fma_f32 v212, -v203, v207, 1.0
	v_fmac_f32_e32 v207, v212, v207
	v_mul_f32_e32 v211, v210, v207
	v_fma_f32 v212, -v203, v211, v210
	v_fmac_f32_e32 v211, v212, v207
	v_fma_f32 v212, -v203, v211, v210
	v_div_fmas_f32 v212, v212, v207, v211
	v_div_fixup_f32 v39, v212, v199, v39
	v_div_scale_f32 v210, vcc, v40, v200, v40
	v_fma_f32 v212, -v204, v208, 1.0
	v_fmac_f32_e32 v208, v212, v208
	v_mul_f32_e32 v211, v210, v208
	v_fma_f32 v212, -v204, v211, v210
	v_fmac_f32_e32 v211, v212, v208
	v_fma_f32 v212, -v204, v211, v210
	v_div_fmas_f32 v212, v212, v208, v211
	v_div_fixup_f32 v40, v212, v200, v40
	v_div_scale_f32 v210, vcc, v41, v201, v41
	v_fma_f32 v212, -v205, v209, 1.0
	v_fmac_f32_e32 v209, v212, v209
	v_mul_f32_e32 v211, v210, v209
	v_fma_f32 v212, -v205, v211, v210
	v_fmac_f32_e32 v211, v212, v209
	v_fma_f32 v212, -v205, v211, v210
	v_div_fmas_f32 v212, v212, v209, v211
	v_div_fixup_f32 v41, v212, v201, v41
	v_mul_f32_e32 v198, 0xbfb8aa3b, v42
	v_mul_f32_e32 v199, 0xbfb8aa3b, v43
	v_mul_f32_e32 v200, 0xbfb8aa3b, v44
	v_mul_f32_e32 v201, 0xbfb8aa3b, v45
	v_exp_f32_e32 v198, v198
	v_exp_f32_e32 v199, v199
	v_exp_f32_e32 v200, v200
	v_exp_f32_e32 v201, v201
	s_nop 0
	v_add_f32_e32 v198, 1.0, v198
	v_add_f32_e32 v199, 1.0, v199
	v_add_f32_e32 v200, 1.0, v200
	v_add_f32_e32 v201, 1.0, v201
	v_div_scale_f32 v202, s[84:85], v198, v198, v42
	v_div_scale_f32 v203, s[84:85], v199, v199, v43
	v_div_scale_f32 v204, s[84:85], v200, v200, v44
	v_div_scale_f32 v205, s[84:85], v201, v201, v45
	v_rcp_f32_e32 v206, v202
	v_rcp_f32_e32 v207, v203
	v_rcp_f32_e32 v208, v204
	v_rcp_f32_e32 v209, v205
	s_nop 0
	v_div_scale_f32 v210, vcc, v42, v198, v42
	v_fma_f32 v212, -v202, v206, 1.0
	v_fmac_f32_e32 v206, v212, v206
	v_mul_f32_e32 v211, v210, v206
	v_fma_f32 v212, -v202, v211, v210
	v_fmac_f32_e32 v211, v212, v206
	v_fma_f32 v212, -v202, v211, v210
	v_div_fmas_f32 v212, v212, v206, v211
	v_div_fixup_f32 v42, v212, v198, v42
	v_div_scale_f32 v210, vcc, v43, v199, v43
	v_fma_f32 v212, -v203, v207, 1.0
	v_fmac_f32_e32 v207, v212, v207
	v_mul_f32_e32 v211, v210, v207
	v_fma_f32 v212, -v203, v211, v210
	v_fmac_f32_e32 v211, v212, v207
	v_fma_f32 v212, -v203, v211, v210
	v_div_fmas_f32 v212, v212, v207, v211
	v_div_fixup_f32 v43, v212, v199, v43
	v_div_scale_f32 v210, vcc, v44, v200, v44
	v_fma_f32 v212, -v204, v208, 1.0
	v_fmac_f32_e32 v208, v212, v208
	v_mul_f32_e32 v211, v210, v208
	v_fma_f32 v212, -v204, v211, v210
	v_fmac_f32_e32 v211, v212, v208
	v_fma_f32 v212, -v204, v211, v210
	v_div_fmas_f32 v212, v212, v208, v211
	v_div_fixup_f32 v44, v212, v200, v44
	v_div_scale_f32 v210, vcc, v45, v201, v45
	v_fma_f32 v212, -v205, v209, 1.0
	v_fmac_f32_e32 v209, v212, v209
	v_mul_f32_e32 v211, v210, v209
	v_fma_f32 v212, -v205, v211, v210
	v_fmac_f32_e32 v211, v212, v209
	v_fma_f32 v212, -v205, v211, v210
	v_div_fmas_f32 v212, v212, v209, v211
	v_div_fixup_f32 v45, v212, v201, v45
	v_mul_f32_e32 v198, 0xbfb8aa3b, v46
	v_mul_f32_e32 v199, 0xbfb8aa3b, v47
	v_mul_f32_e32 v200, 0xbfb8aa3b, v48
	v_mul_f32_e32 v201, 0xbfb8aa3b, v49
	v_exp_f32_e32 v198, v198
	v_exp_f32_e32 v199, v199
	v_exp_f32_e32 v200, v200
	v_exp_f32_e32 v201, v201
	s_nop 0
	v_add_f32_e32 v198, 1.0, v198
	v_add_f32_e32 v199, 1.0, v199
	v_add_f32_e32 v200, 1.0, v200
	v_add_f32_e32 v201, 1.0, v201
	v_div_scale_f32 v202, s[84:85], v198, v198, v46
	v_div_scale_f32 v203, s[84:85], v199, v199, v47
	v_div_scale_f32 v204, s[84:85], v200, v200, v48
	v_div_scale_f32 v205, s[84:85], v201, v201, v49
	v_rcp_f32_e32 v206, v202
	v_rcp_f32_e32 v207, v203
	v_rcp_f32_e32 v208, v204
	v_rcp_f32_e32 v209, v205
	s_nop 0
	v_div_scale_f32 v210, vcc, v46, v198, v46
	v_fma_f32 v212, -v202, v206, 1.0
	v_fmac_f32_e32 v206, v212, v206
	v_mul_f32_e32 v211, v210, v206
	v_fma_f32 v212, -v202, v211, v210
	v_fmac_f32_e32 v211, v212, v206
	v_fma_f32 v212, -v202, v211, v210
	v_div_fmas_f32 v212, v212, v206, v211
	v_div_fixup_f32 v46, v212, v198, v46
	v_div_scale_f32 v210, vcc, v47, v199, v47
	v_fma_f32 v212, -v203, v207, 1.0
	v_fmac_f32_e32 v207, v212, v207
	v_mul_f32_e32 v211, v210, v207
	v_fma_f32 v212, -v203, v211, v210
	v_fmac_f32_e32 v211, v212, v207
	v_fma_f32 v212, -v203, v211, v210
	v_div_fmas_f32 v212, v212, v207, v211
	v_div_fixup_f32 v47, v212, v199, v47
	v_div_scale_f32 v210, vcc, v48, v200, v48
	v_fma_f32 v212, -v204, v208, 1.0
	v_fmac_f32_e32 v208, v212, v208
	v_mul_f32_e32 v211, v210, v208
	v_fma_f32 v212, -v204, v211, v210
	v_fmac_f32_e32 v211, v212, v208
	v_fma_f32 v212, -v204, v211, v210
	v_div_fmas_f32 v212, v212, v208, v211
	v_div_fixup_f32 v48, v212, v200, v48
	v_div_scale_f32 v210, vcc, v49, v201, v49
	v_fma_f32 v212, -v205, v209, 1.0
	v_fmac_f32_e32 v209, v212, v209
	v_mul_f32_e32 v211, v210, v209
	v_fma_f32 v212, -v205, v211, v210
	v_fmac_f32_e32 v211, v212, v209
	v_fma_f32 v212, -v205, v211, v210
	v_div_fmas_f32 v212, v212, v209, v211
	v_div_fixup_f32 v49, v212, v201, v49
	v_mul_f32_e32 v198, 0xbfb8aa3b, v50
	v_mul_f32_e32 v199, 0xbfb8aa3b, v51
	v_mul_f32_e32 v200, 0xbfb8aa3b, v52
	v_mul_f32_e32 v201, 0xbfb8aa3b, v53
	v_exp_f32_e32 v198, v198
	v_exp_f32_e32 v199, v199
	v_exp_f32_e32 v200, v200
	v_exp_f32_e32 v201, v201
	s_nop 0
	v_add_f32_e32 v198, 1.0, v198
	v_add_f32_e32 v199, 1.0, v199
	v_add_f32_e32 v200, 1.0, v200
	v_add_f32_e32 v201, 1.0, v201
	v_div_scale_f32 v202, s[84:85], v198, v198, v50
	v_div_scale_f32 v203, s[84:85], v199, v199, v51
	v_div_scale_f32 v204, s[84:85], v200, v200, v52
	v_div_scale_f32 v205, s[84:85], v201, v201, v53
	v_rcp_f32_e32 v206, v202
	v_rcp_f32_e32 v207, v203
	v_rcp_f32_e32 v208, v204
	v_rcp_f32_e32 v209, v205
	s_nop 0
	v_div_scale_f32 v210, vcc, v50, v198, v50
	v_fma_f32 v212, -v202, v206, 1.0
	v_fmac_f32_e32 v206, v212, v206
	v_mul_f32_e32 v211, v210, v206
	v_fma_f32 v212, -v202, v211, v210
	v_fmac_f32_e32 v211, v212, v206
	v_fma_f32 v212, -v202, v211, v210
	v_div_fmas_f32 v212, v212, v206, v211
	v_div_fixup_f32 v50, v212, v198, v50
	v_div_scale_f32 v210, vcc, v51, v199, v51
	v_fma_f32 v212, -v203, v207, 1.0
	v_fmac_f32_e32 v207, v212, v207
	v_mul_f32_e32 v211, v210, v207
	v_fma_f32 v212, -v203, v211, v210
	v_fmac_f32_e32 v211, v212, v207
	v_fma_f32 v212, -v203, v211, v210
	v_div_fmas_f32 v212, v212, v207, v211
	v_div_fixup_f32 v51, v212, v199, v51
	v_div_scale_f32 v210, vcc, v52, v200, v52
	v_fma_f32 v212, -v204, v208, 1.0
	v_fmac_f32_e32 v208, v212, v208
	v_mul_f32_e32 v211, v210, v208
	v_fma_f32 v212, -v204, v211, v210
	v_fmac_f32_e32 v211, v212, v208
	v_fma_f32 v212, -v204, v211, v210
	v_div_fmas_f32 v212, v212, v208, v211
	v_div_fixup_f32 v52, v212, v200, v52
	v_div_scale_f32 v210, vcc, v53, v201, v53
	v_fma_f32 v212, -v205, v209, 1.0
	v_fmac_f32_e32 v209, v212, v209
	v_mul_f32_e32 v211, v210, v209
	v_fma_f32 v212, -v205, v211, v210
	v_fmac_f32_e32 v211, v212, v209
	v_fma_f32 v212, -v205, v211, v210
	v_div_fmas_f32 v212, v212, v209, v211
	v_div_fixup_f32 v53, v212, v201, v53
	v_mul_f32_e32 v198, 0xbfb8aa3b, v54
	v_mul_f32_e32 v199, 0xbfb8aa3b, v55
	v_mul_f32_e32 v200, 0xbfb8aa3b, v56
	v_mul_f32_e32 v201, 0xbfb8aa3b, v57
	v_exp_f32_e32 v198, v198
	v_exp_f32_e32 v199, v199
	v_exp_f32_e32 v200, v200
	v_exp_f32_e32 v201, v201
	s_nop 0
	v_add_f32_e32 v198, 1.0, v198
	v_add_f32_e32 v199, 1.0, v199
	v_add_f32_e32 v200, 1.0, v200
	v_add_f32_e32 v201, 1.0, v201
	v_div_scale_f32 v202, s[84:85], v198, v198, v54
	v_div_scale_f32 v203, s[84:85], v199, v199, v55
	v_div_scale_f32 v204, s[84:85], v200, v200, v56
	v_div_scale_f32 v205, s[84:85], v201, v201, v57
	v_rcp_f32_e32 v206, v202
	v_rcp_f32_e32 v207, v203
	v_rcp_f32_e32 v208, v204
	v_rcp_f32_e32 v209, v205
	s_nop 0
	v_div_scale_f32 v210, vcc, v54, v198, v54
	v_fma_f32 v212, -v202, v206, 1.0
	v_fmac_f32_e32 v206, v212, v206
	v_mul_f32_e32 v211, v210, v206
	v_fma_f32 v212, -v202, v211, v210
	v_fmac_f32_e32 v211, v212, v206
	v_fma_f32 v212, -v202, v211, v210
	v_div_fmas_f32 v212, v212, v206, v211
	v_div_fixup_f32 v54, v212, v198, v54
	v_div_scale_f32 v210, vcc, v55, v199, v55
	v_fma_f32 v212, -v203, v207, 1.0
	v_fmac_f32_e32 v207, v212, v207
	v_mul_f32_e32 v211, v210, v207
	v_fma_f32 v212, -v203, v211, v210
	v_fmac_f32_e32 v211, v212, v207
	v_fma_f32 v212, -v203, v211, v210
	v_div_fmas_f32 v212, v212, v207, v211
	v_div_fixup_f32 v55, v212, v199, v55
	v_div_scale_f32 v210, vcc, v56, v200, v56
	v_fma_f32 v212, -v204, v208, 1.0
	v_fmac_f32_e32 v208, v212, v208
	v_mul_f32_e32 v211, v210, v208
	v_fma_f32 v212, -v204, v211, v210
	v_fmac_f32_e32 v211, v212, v208
	v_fma_f32 v212, -v204, v211, v210
	v_div_fmas_f32 v212, v212, v208, v211
	v_div_fixup_f32 v56, v212, v200, v56
	v_div_scale_f32 v210, vcc, v57, v201, v57
	v_fma_f32 v212, -v205, v209, 1.0
	v_fmac_f32_e32 v209, v212, v209
	v_mul_f32_e32 v211, v210, v209
	v_fma_f32 v212, -v205, v211, v210
	v_fmac_f32_e32 v211, v212, v209
	v_fma_f32 v212, -v205, v211, v210
	v_div_fmas_f32 v212, v212, v209, v211
	v_div_fixup_f32 v57, v212, v201, v57
	v_mul_f32_e32 v198, 0xbfb8aa3b, v58
	v_mul_f32_e32 v199, 0xbfb8aa3b, v59
	v_mul_f32_e32 v200, 0xbfb8aa3b, v60
	v_mul_f32_e32 v201, 0xbfb8aa3b, v61
	v_exp_f32_e32 v198, v198
	v_exp_f32_e32 v199, v199
	v_exp_f32_e32 v200, v200
	v_exp_f32_e32 v201, v201
	s_nop 0
	v_add_f32_e32 v198, 1.0, v198
	v_add_f32_e32 v199, 1.0, v199
	v_add_f32_e32 v200, 1.0, v200
	v_add_f32_e32 v201, 1.0, v201
	v_div_scale_f32 v202, s[84:85], v198, v198, v58
	v_div_scale_f32 v203, s[84:85], v199, v199, v59
	v_div_scale_f32 v204, s[84:85], v200, v200, v60
	v_div_scale_f32 v205, s[84:85], v201, v201, v61
	v_rcp_f32_e32 v206, v202
	v_rcp_f32_e32 v207, v203
	v_rcp_f32_e32 v208, v204
	v_rcp_f32_e32 v209, v205
	s_nop 0
	v_div_scale_f32 v210, vcc, v58, v198, v58
	v_fma_f32 v212, -v202, v206, 1.0
	v_fmac_f32_e32 v206, v212, v206
	v_mul_f32_e32 v211, v210, v206
	v_fma_f32 v212, -v202, v211, v210
	v_fmac_f32_e32 v211, v212, v206
	v_fma_f32 v212, -v202, v211, v210
	v_div_fmas_f32 v212, v212, v206, v211
	v_div_fixup_f32 v58, v212, v198, v58
	v_div_scale_f32 v210, vcc, v59, v199, v59
	v_fma_f32 v212, -v203, v207, 1.0
	v_fmac_f32_e32 v207, v212, v207
	v_mul_f32_e32 v211, v210, v207
	v_fma_f32 v212, -v203, v211, v210
	v_fmac_f32_e32 v211, v212, v207
	v_fma_f32 v212, -v203, v211, v210
	v_div_fmas_f32 v212, v212, v207, v211
	v_div_fixup_f32 v59, v212, v199, v59
	v_div_scale_f32 v210, vcc, v60, v200, v60
	v_fma_f32 v212, -v204, v208, 1.0
	v_fmac_f32_e32 v208, v212, v208
	v_mul_f32_e32 v211, v210, v208
	v_fma_f32 v212, -v204, v211, v210
	v_fmac_f32_e32 v211, v212, v208
	v_fma_f32 v212, -v204, v211, v210
	v_div_fmas_f32 v212, v212, v208, v211
	v_div_fixup_f32 v60, v212, v200, v60
	v_div_scale_f32 v210, vcc, v61, v201, v61
	v_fma_f32 v212, -v205, v209, 1.0
	v_fmac_f32_e32 v209, v212, v209
	v_mul_f32_e32 v211, v210, v209
	v_fma_f32 v212, -v205, v211, v210
	v_fmac_f32_e32 v211, v212, v209
	v_fma_f32 v212, -v205, v211, v210
	v_div_fmas_f32 v212, v212, v209, v211
	v_div_fixup_f32 v61, v212, v201, v61
	v_mul_f32_e32 v198, 0xbfb8aa3b, v62
	v_mul_f32_e32 v199, 0xbfb8aa3b, v63
	v_mul_f32_e32 v200, 0xbfb8aa3b, v64
	v_mul_f32_e32 v201, 0xbfb8aa3b, v65
	v_exp_f32_e32 v198, v198
	v_exp_f32_e32 v199, v199
	v_exp_f32_e32 v200, v200
	v_exp_f32_e32 v201, v201
	s_nop 0
	v_add_f32_e32 v198, 1.0, v198
	v_add_f32_e32 v199, 1.0, v199
	v_add_f32_e32 v200, 1.0, v200
	v_add_f32_e32 v201, 1.0, v201
	v_div_scale_f32 v202, s[84:85], v198, v198, v62
	v_div_scale_f32 v203, s[84:85], v199, v199, v63
	v_div_scale_f32 v204, s[84:85], v200, v200, v64
	v_div_scale_f32 v205, s[84:85], v201, v201, v65
	v_rcp_f32_e32 v206, v202
	v_rcp_f32_e32 v207, v203
	v_rcp_f32_e32 v208, v204
	v_rcp_f32_e32 v209, v205
	s_nop 0
	v_div_scale_f32 v210, vcc, v62, v198, v62
	v_fma_f32 v212, -v202, v206, 1.0
	v_fmac_f32_e32 v206, v212, v206
	v_mul_f32_e32 v211, v210, v206
	v_fma_f32 v212, -v202, v211, v210
	v_fmac_f32_e32 v211, v212, v206
	v_fma_f32 v212, -v202, v211, v210
	v_div_fmas_f32 v212, v212, v206, v211
	v_div_fixup_f32 v62, v212, v198, v62
	v_div_scale_f32 v210, vcc, v63, v199, v63
	v_fma_f32 v212, -v203, v207, 1.0
	v_fmac_f32_e32 v207, v212, v207
	v_mul_f32_e32 v211, v210, v207
	v_fma_f32 v212, -v203, v211, v210
	v_fmac_f32_e32 v211, v212, v207
	v_fma_f32 v212, -v203, v211, v210
	v_div_fmas_f32 v212, v212, v207, v211
	v_div_fixup_f32 v63, v212, v199, v63
	v_div_scale_f32 v210, vcc, v64, v200, v64
	v_fma_f32 v212, -v204, v208, 1.0
	v_fmac_f32_e32 v208, v212, v208
	v_mul_f32_e32 v211, v210, v208
	v_fma_f32 v212, -v204, v211, v210
	v_fmac_f32_e32 v211, v212, v208
	v_fma_f32 v212, -v204, v211, v210
	v_div_fmas_f32 v212, v212, v208, v211
	v_div_fixup_f32 v64, v212, v200, v64
	v_div_scale_f32 v210, vcc, v65, v201, v65
	v_fma_f32 v212, -v205, v209, 1.0
	v_fmac_f32_e32 v209, v212, v209
	v_mul_f32_e32 v211, v210, v209
	v_fma_f32 v212, -v205, v211, v210
	v_fmac_f32_e32 v211, v212, v209
	v_fma_f32 v212, -v205, v211, v210
	v_div_fmas_f32 v212, v212, v209, v211
	v_div_fixup_f32 v65, v212, v201, v65
	v_mul_f32_e32 v198, 0xbfb8aa3b, v66
	v_mul_f32_e32 v199, 0xbfb8aa3b, v67
	v_mul_f32_e32 v200, 0xbfb8aa3b, v68
	v_mul_f32_e32 v201, 0xbfb8aa3b, v69
	v_exp_f32_e32 v198, v198
	v_exp_f32_e32 v199, v199
	v_exp_f32_e32 v200, v200
	v_exp_f32_e32 v201, v201
	s_nop 0
	v_add_f32_e32 v198, 1.0, v198
	v_add_f32_e32 v199, 1.0, v199
	v_add_f32_e32 v200, 1.0, v200
	v_add_f32_e32 v201, 1.0, v201
	v_div_scale_f32 v202, s[84:85], v198, v198, v66
	v_div_scale_f32 v203, s[84:85], v199, v199, v67
	v_div_scale_f32 v204, s[84:85], v200, v200, v68
	v_div_scale_f32 v205, s[84:85], v201, v201, v69
	v_rcp_f32_e32 v206, v202
	v_rcp_f32_e32 v207, v203
	v_rcp_f32_e32 v208, v204
	v_rcp_f32_e32 v209, v205
	s_nop 0
	v_div_scale_f32 v210, vcc, v66, v198, v66
	v_fma_f32 v212, -v202, v206, 1.0
	v_fmac_f32_e32 v206, v212, v206
	v_mul_f32_e32 v211, v210, v206
	v_fma_f32 v212, -v202, v211, v210
	v_fmac_f32_e32 v211, v212, v206
	v_fma_f32 v212, -v202, v211, v210
	v_div_fmas_f32 v212, v212, v206, v211
	v_div_fixup_f32 v66, v212, v198, v66
	v_div_scale_f32 v210, vcc, v67, v199, v67
	v_fma_f32 v212, -v203, v207, 1.0
	v_fmac_f32_e32 v207, v212, v207
	v_mul_f32_e32 v211, v210, v207
	v_fma_f32 v212, -v203, v211, v210
	v_fmac_f32_e32 v211, v212, v207
	v_fma_f32 v212, -v203, v211, v210
	v_div_fmas_f32 v212, v212, v207, v211
	v_div_fixup_f32 v67, v212, v199, v67
	v_div_scale_f32 v210, vcc, v68, v200, v68
	v_fma_f32 v212, -v204, v208, 1.0
	v_fmac_f32_e32 v208, v212, v208
	v_mul_f32_e32 v211, v210, v208
	v_fma_f32 v212, -v204, v211, v210
	v_fmac_f32_e32 v211, v212, v208
	v_fma_f32 v212, -v204, v211, v210
	v_div_fmas_f32 v212, v212, v208, v211
	v_div_fixup_f32 v68, v212, v200, v68
	v_div_scale_f32 v210, vcc, v69, v201, v69
	v_fma_f32 v212, -v205, v209, 1.0
	v_fmac_f32_e32 v209, v212, v209
	v_mul_f32_e32 v211, v210, v209
	v_fma_f32 v212, -v205, v211, v210
	v_fmac_f32_e32 v211, v212, v209
	v_fma_f32 v212, -v205, v211, v210
	v_div_fmas_f32 v212, v212, v209, v211
	v_div_fixup_f32 v69, v212, v201, v69
	v_mul_f32_e32 v198, 0xbfb8aa3b, v70
	v_mul_f32_e32 v199, 0xbfb8aa3b, v71
	v_mul_f32_e32 v200, 0xbfb8aa3b, v72
	v_mul_f32_e32 v201, 0xbfb8aa3b, v73
	v_exp_f32_e32 v198, v198
	v_exp_f32_e32 v199, v199
	v_exp_f32_e32 v200, v200
	v_exp_f32_e32 v201, v201
	s_nop 0
	v_add_f32_e32 v198, 1.0, v198
	v_add_f32_e32 v199, 1.0, v199
	v_add_f32_e32 v200, 1.0, v200
	v_add_f32_e32 v201, 1.0, v201
	v_div_scale_f32 v202, s[84:85], v198, v198, v70
	v_div_scale_f32 v203, s[84:85], v199, v199, v71
	v_div_scale_f32 v204, s[84:85], v200, v200, v72
	v_div_scale_f32 v205, s[84:85], v201, v201, v73
	v_rcp_f32_e32 v206, v202
	v_rcp_f32_e32 v207, v203
	v_rcp_f32_e32 v208, v204
	v_rcp_f32_e32 v209, v205
	s_nop 0
	v_div_scale_f32 v210, vcc, v70, v198, v70
	v_fma_f32 v212, -v202, v206, 1.0
	v_fmac_f32_e32 v206, v212, v206
	v_mul_f32_e32 v211, v210, v206
	v_fma_f32 v212, -v202, v211, v210
	v_fmac_f32_e32 v211, v212, v206
	v_fma_f32 v212, -v202, v211, v210
	v_div_fmas_f32 v212, v212, v206, v211
	v_div_fixup_f32 v70, v212, v198, v70
	v_div_scale_f32 v210, vcc, v71, v199, v71
	v_fma_f32 v212, -v203, v207, 1.0
	v_fmac_f32_e32 v207, v212, v207
	v_mul_f32_e32 v211, v210, v207
	v_fma_f32 v212, -v203, v211, v210
	v_fmac_f32_e32 v211, v212, v207
	v_fma_f32 v212, -v203, v211, v210
	v_div_fmas_f32 v212, v212, v207, v211
	v_div_fixup_f32 v71, v212, v199, v71
	v_div_scale_f32 v210, vcc, v72, v200, v72
	v_fma_f32 v212, -v204, v208, 1.0
	v_fmac_f32_e32 v208, v212, v208
	v_mul_f32_e32 v211, v210, v208
	v_fma_f32 v212, -v204, v211, v210
	v_fmac_f32_e32 v211, v212, v208
	v_fma_f32 v212, -v204, v211, v210
	v_div_fmas_f32 v212, v212, v208, v211
	v_div_fixup_f32 v72, v212, v200, v72
	v_div_scale_f32 v210, vcc, v73, v201, v73
	v_fma_f32 v212, -v205, v209, 1.0
	v_fmac_f32_e32 v209, v212, v209
	v_mul_f32_e32 v211, v210, v209
	v_fma_f32 v212, -v205, v211, v210
	v_fmac_f32_e32 v211, v212, v209
	v_fma_f32 v212, -v205, v211, v210
	v_div_fmas_f32 v212, v212, v209, v211
	v_div_fixup_f32 v73, v212, v201, v73
	v_mul_f32_e32 v198, 0xbfb8aa3b, v74
	v_mul_f32_e32 v199, 0xbfb8aa3b, v75
	v_mul_f32_e32 v200, 0xbfb8aa3b, v76
	v_mul_f32_e32 v201, 0xbfb8aa3b, v77
	v_exp_f32_e32 v198, v198
	v_exp_f32_e32 v199, v199
	v_exp_f32_e32 v200, v200
	v_exp_f32_e32 v201, v201
	s_nop 0
	v_add_f32_e32 v198, 1.0, v198
	v_add_f32_e32 v199, 1.0, v199
	v_add_f32_e32 v200, 1.0, v200
	v_add_f32_e32 v201, 1.0, v201
	v_div_scale_f32 v202, s[84:85], v198, v198, v74
	v_div_scale_f32 v203, s[84:85], v199, v199, v75
	v_div_scale_f32 v204, s[84:85], v200, v200, v76
	v_div_scale_f32 v205, s[84:85], v201, v201, v77
	v_rcp_f32_e32 v206, v202
	v_rcp_f32_e32 v207, v203
	v_rcp_f32_e32 v208, v204
	v_rcp_f32_e32 v209, v205
	s_nop 0
	v_div_scale_f32 v210, vcc, v74, v198, v74
	v_fma_f32 v212, -v202, v206, 1.0
	v_fmac_f32_e32 v206, v212, v206
	v_mul_f32_e32 v211, v210, v206
	v_fma_f32 v212, -v202, v211, v210
	v_fmac_f32_e32 v211, v212, v206
	v_fma_f32 v212, -v202, v211, v210
	v_div_fmas_f32 v212, v212, v206, v211
	v_div_fixup_f32 v74, v212, v198, v74
	v_div_scale_f32 v210, vcc, v75, v199, v75
	v_fma_f32 v212, -v203, v207, 1.0
	v_fmac_f32_e32 v207, v212, v207
	v_mul_f32_e32 v211, v210, v207
	v_fma_f32 v212, -v203, v211, v210
	v_fmac_f32_e32 v211, v212, v207
	v_fma_f32 v212, -v203, v211, v210
	v_div_fmas_f32 v212, v212, v207, v211
	v_div_fixup_f32 v75, v212, v199, v75
	v_div_scale_f32 v210, vcc, v76, v200, v76
	v_fma_f32 v212, -v204, v208, 1.0
	v_fmac_f32_e32 v208, v212, v208
	v_mul_f32_e32 v211, v210, v208
	v_fma_f32 v212, -v204, v211, v210
	v_fmac_f32_e32 v211, v212, v208
	v_fma_f32 v212, -v204, v211, v210
	v_div_fmas_f32 v212, v212, v208, v211
	v_div_fixup_f32 v76, v212, v200, v76
	v_div_scale_f32 v210, vcc, v77, v201, v77
	v_fma_f32 v212, -v205, v209, 1.0
	v_fmac_f32_e32 v209, v212, v209
	v_mul_f32_e32 v211, v210, v209
	v_fma_f32 v212, -v205, v211, v210
	v_fmac_f32_e32 v211, v212, v209
	v_fma_f32 v212, -v205, v211, v210
	v_div_fmas_f32 v212, v212, v209, v211
	v_div_fixup_f32 v77, v212, v201, v77
	v_mul_f32_e32 v198, 0xbfb8aa3b, v78
	v_mul_f32_e32 v199, 0xbfb8aa3b, v79
	v_mul_f32_e32 v200, 0xbfb8aa3b, v80
	v_mul_f32_e32 v201, 0xbfb8aa3b, v81
	v_exp_f32_e32 v198, v198
	v_exp_f32_e32 v199, v199
	v_exp_f32_e32 v200, v200
	v_exp_f32_e32 v201, v201
	s_nop 0
	v_add_f32_e32 v198, 1.0, v198
	v_add_f32_e32 v199, 1.0, v199
	v_add_f32_e32 v200, 1.0, v200
	v_add_f32_e32 v201, 1.0, v201
	v_div_scale_f32 v202, s[84:85], v198, v198, v78
	v_div_scale_f32 v203, s[84:85], v199, v199, v79
	v_div_scale_f32 v204, s[84:85], v200, v200, v80
	v_div_scale_f32 v205, s[84:85], v201, v201, v81
	v_rcp_f32_e32 v206, v202
	v_rcp_f32_e32 v207, v203
	v_rcp_f32_e32 v208, v204
	v_rcp_f32_e32 v209, v205
	s_nop 0
	v_div_scale_f32 v210, vcc, v78, v198, v78
	v_fma_f32 v212, -v202, v206, 1.0
	v_fmac_f32_e32 v206, v212, v206
	v_mul_f32_e32 v211, v210, v206
	v_fma_f32 v212, -v202, v211, v210
	v_fmac_f32_e32 v211, v212, v206
	v_fma_f32 v212, -v202, v211, v210
	v_div_fmas_f32 v212, v212, v206, v211
	v_div_fixup_f32 v78, v212, v198, v78
	v_div_scale_f32 v210, vcc, v79, v199, v79
	v_fma_f32 v212, -v203, v207, 1.0
	v_fmac_f32_e32 v207, v212, v207
	v_mul_f32_e32 v211, v210, v207
	v_fma_f32 v212, -v203, v211, v210
	v_fmac_f32_e32 v211, v212, v207
	v_fma_f32 v212, -v203, v211, v210
	v_div_fmas_f32 v212, v212, v207, v211
	v_div_fixup_f32 v79, v212, v199, v79
	v_div_scale_f32 v210, vcc, v80, v200, v80
	v_fma_f32 v212, -v204, v208, 1.0
	v_fmac_f32_e32 v208, v212, v208
	v_mul_f32_e32 v211, v210, v208
	v_fma_f32 v212, -v204, v211, v210
	v_fmac_f32_e32 v211, v212, v208
	v_fma_f32 v212, -v204, v211, v210
	v_div_fmas_f32 v212, v212, v208, v211
	v_div_fixup_f32 v80, v212, v200, v80
	v_div_scale_f32 v210, vcc, v81, v201, v81
	v_fma_f32 v212, -v205, v209, 1.0
	v_fmac_f32_e32 v209, v212, v209
	v_mul_f32_e32 v211, v210, v209
	v_fma_f32 v212, -v205, v211, v210
	v_fmac_f32_e32 v211, v212, v209
	v_fma_f32 v212, -v205, v211, v210
	v_div_fmas_f32 v212, v212, v209, v211
	v_div_fixup_f32 v81, v212, v201, v81
	v_mul_f32_e32 v198, 0xbfb8aa3b, v82
	v_mul_f32_e32 v199, 0xbfb8aa3b, v83
	v_mul_f32_e32 v200, 0xbfb8aa3b, v84
	v_mul_f32_e32 v201, 0xbfb8aa3b, v85
	v_exp_f32_e32 v198, v198
	v_exp_f32_e32 v199, v199
	v_exp_f32_e32 v200, v200
	v_exp_f32_e32 v201, v201
	s_nop 0
	v_add_f32_e32 v198, 1.0, v198
	v_add_f32_e32 v199, 1.0, v199
	v_add_f32_e32 v200, 1.0, v200
	v_add_f32_e32 v201, 1.0, v201
	v_div_scale_f32 v202, s[84:85], v198, v198, v82
	v_div_scale_f32 v203, s[84:85], v199, v199, v83
	v_div_scale_f32 v204, s[84:85], v200, v200, v84
	v_div_scale_f32 v205, s[84:85], v201, v201, v85
	v_rcp_f32_e32 v206, v202
	v_rcp_f32_e32 v207, v203
	v_rcp_f32_e32 v208, v204
	v_rcp_f32_e32 v209, v205
	s_nop 0
	v_div_scale_f32 v210, vcc, v82, v198, v82
	v_fma_f32 v212, -v202, v206, 1.0
	v_fmac_f32_e32 v206, v212, v206
	v_mul_f32_e32 v211, v210, v206
	v_fma_f32 v212, -v202, v211, v210
	v_fmac_f32_e32 v211, v212, v206
	v_fma_f32 v212, -v202, v211, v210
	v_div_fmas_f32 v212, v212, v206, v211
	v_div_fixup_f32 v82, v212, v198, v82
	v_div_scale_f32 v210, vcc, v83, v199, v83
	v_fma_f32 v212, -v203, v207, 1.0
	v_fmac_f32_e32 v207, v212, v207
	v_mul_f32_e32 v211, v210, v207
	v_fma_f32 v212, -v203, v211, v210
	v_fmac_f32_e32 v211, v212, v207
	v_fma_f32 v212, -v203, v211, v210
	v_div_fmas_f32 v212, v212, v207, v211
	v_div_fixup_f32 v83, v212, v199, v83
	v_div_scale_f32 v210, vcc, v84, v200, v84
	v_fma_f32 v212, -v204, v208, 1.0
	v_fmac_f32_e32 v208, v212, v208
	v_mul_f32_e32 v211, v210, v208
	v_fma_f32 v212, -v204, v211, v210
	v_fmac_f32_e32 v211, v212, v208
	v_fma_f32 v212, -v204, v211, v210
	v_div_fmas_f32 v212, v212, v208, v211
	v_div_fixup_f32 v84, v212, v200, v84
	v_div_scale_f32 v210, vcc, v85, v201, v85
	v_fma_f32 v212, -v205, v209, 1.0
	v_fmac_f32_e32 v209, v212, v209
	v_mul_f32_e32 v211, v210, v209
	v_fma_f32 v212, -v205, v211, v210
	v_fmac_f32_e32 v211, v212, v209
	v_fma_f32 v212, -v205, v211, v210
	v_div_fmas_f32 v212, v212, v209, v211
	v_div_fixup_f32 v85, v212, v201, v85
	v_mul_f32_e32 v198, 0xbfb8aa3b, v86
	v_mul_f32_e32 v199, 0xbfb8aa3b, v87
	v_mul_f32_e32 v200, 0xbfb8aa3b, v88
	v_mul_f32_e32 v201, 0xbfb8aa3b, v89
	v_exp_f32_e32 v198, v198
	v_exp_f32_e32 v199, v199
	v_exp_f32_e32 v200, v200
	v_exp_f32_e32 v201, v201
	s_nop 0
	v_add_f32_e32 v198, 1.0, v198
	v_add_f32_e32 v199, 1.0, v199
	v_add_f32_e32 v200, 1.0, v200
	v_add_f32_e32 v201, 1.0, v201
	v_div_scale_f32 v202, s[84:85], v198, v198, v86
	v_div_scale_f32 v203, s[84:85], v199, v199, v87
	v_div_scale_f32 v204, s[84:85], v200, v200, v88
	v_div_scale_f32 v205, s[84:85], v201, v201, v89
	v_rcp_f32_e32 v206, v202
	v_rcp_f32_e32 v207, v203
	v_rcp_f32_e32 v208, v204
	v_rcp_f32_e32 v209, v205
	s_nop 0
	v_div_scale_f32 v210, vcc, v86, v198, v86
	v_fma_f32 v212, -v202, v206, 1.0
	v_fmac_f32_e32 v206, v212, v206
	v_mul_f32_e32 v211, v210, v206
	v_fma_f32 v212, -v202, v211, v210
	v_fmac_f32_e32 v211, v212, v206
	v_fma_f32 v212, -v202, v211, v210
	v_div_fmas_f32 v212, v212, v206, v211
	v_div_fixup_f32 v86, v212, v198, v86
	v_div_scale_f32 v210, vcc, v87, v199, v87
	v_fma_f32 v212, -v203, v207, 1.0
	v_fmac_f32_e32 v207, v212, v207
	v_mul_f32_e32 v211, v210, v207
	v_fma_f32 v212, -v203, v211, v210
	v_fmac_f32_e32 v211, v212, v207
	v_fma_f32 v212, -v203, v211, v210
	v_div_fmas_f32 v212, v212, v207, v211
	v_div_fixup_f32 v87, v212, v199, v87
	v_div_scale_f32 v210, vcc, v88, v200, v88
	v_fma_f32 v212, -v204, v208, 1.0
	v_fmac_f32_e32 v208, v212, v208
	v_mul_f32_e32 v211, v210, v208
	v_fma_f32 v212, -v204, v211, v210
	v_fmac_f32_e32 v211, v212, v208
	v_fma_f32 v212, -v204, v211, v210
	v_div_fmas_f32 v212, v212, v208, v211
	v_div_fixup_f32 v88, v212, v200, v88
	v_div_scale_f32 v210, vcc, v89, v201, v89
	v_fma_f32 v212, -v205, v209, 1.0
	v_fmac_f32_e32 v209, v212, v209
	v_mul_f32_e32 v211, v210, v209
	v_fma_f32 v212, -v205, v211, v210
	v_fmac_f32_e32 v211, v212, v209
	v_fma_f32 v212, -v205, v211, v210
	v_div_fmas_f32 v212, v212, v209, v211
	v_div_fixup_f32 v89, v212, v201, v89
	v_mul_f32_e32 v198, 0xbfb8aa3b, v90
	v_mul_f32_e32 v199, 0xbfb8aa3b, v91
	v_mul_f32_e32 v200, 0xbfb8aa3b, v92
	v_mul_f32_e32 v201, 0xbfb8aa3b, v93
	v_exp_f32_e32 v198, v198
	v_exp_f32_e32 v199, v199
	v_exp_f32_e32 v200, v200
	v_exp_f32_e32 v201, v201
	s_nop 0
	v_add_f32_e32 v198, 1.0, v198
	v_add_f32_e32 v199, 1.0, v199
	v_add_f32_e32 v200, 1.0, v200
	v_add_f32_e32 v201, 1.0, v201
	v_div_scale_f32 v202, s[84:85], v198, v198, v90
	v_div_scale_f32 v203, s[84:85], v199, v199, v91
	v_div_scale_f32 v204, s[84:85], v200, v200, v92
	v_div_scale_f32 v205, s[84:85], v201, v201, v93
	v_rcp_f32_e32 v206, v202
	v_rcp_f32_e32 v207, v203
	v_rcp_f32_e32 v208, v204
	v_rcp_f32_e32 v209, v205
	s_nop 0
	v_div_scale_f32 v210, vcc, v90, v198, v90
	v_fma_f32 v212, -v202, v206, 1.0
	v_fmac_f32_e32 v206, v212, v206
	v_mul_f32_e32 v211, v210, v206
	v_fma_f32 v212, -v202, v211, v210
	v_fmac_f32_e32 v211, v212, v206
	v_fma_f32 v212, -v202, v211, v210
	v_div_fmas_f32 v212, v212, v206, v211
	v_div_fixup_f32 v90, v212, v198, v90
	v_div_scale_f32 v210, vcc, v91, v199, v91
	v_fma_f32 v212, -v203, v207, 1.0
	v_fmac_f32_e32 v207, v212, v207
	v_mul_f32_e32 v211, v210, v207
	v_fma_f32 v212, -v203, v211, v210
	v_fmac_f32_e32 v211, v212, v207
	v_fma_f32 v212, -v203, v211, v210
	v_div_fmas_f32 v212, v212, v207, v211
	v_div_fixup_f32 v91, v212, v199, v91
	v_div_scale_f32 v210, vcc, v92, v200, v92
	v_fma_f32 v212, -v204, v208, 1.0
	v_fmac_f32_e32 v208, v212, v208
	v_mul_f32_e32 v211, v210, v208
	v_fma_f32 v212, -v204, v211, v210
	v_fmac_f32_e32 v211, v212, v208
	v_fma_f32 v212, -v204, v211, v210
	v_div_fmas_f32 v212, v212, v208, v211
	v_div_fixup_f32 v92, v212, v200, v92
	v_div_scale_f32 v210, vcc, v93, v201, v93
	v_fma_f32 v212, -v205, v209, 1.0
	v_fmac_f32_e32 v209, v212, v209
	v_mul_f32_e32 v211, v210, v209
	v_fma_f32 v212, -v205, v211, v210
	v_fmac_f32_e32 v211, v212, v209
	v_fma_f32 v212, -v205, v211, v210
	v_div_fmas_f32 v212, v212, v209, v211
	v_div_fixup_f32 v93, v212, v201, v93
	v_mul_f32_e32 v198, 0xbfb8aa3b, v94
	v_mul_f32_e32 v199, 0xbfb8aa3b, v95
	v_mul_f32_e32 v200, 0xbfb8aa3b, v96
	v_mul_f32_e32 v201, 0xbfb8aa3b, v97
	v_exp_f32_e32 v198, v198
	v_exp_f32_e32 v199, v199
	v_exp_f32_e32 v200, v200
	v_exp_f32_e32 v201, v201
	s_nop 0
	v_add_f32_e32 v198, 1.0, v198
	v_add_f32_e32 v199, 1.0, v199
	v_add_f32_e32 v200, 1.0, v200
	v_add_f32_e32 v201, 1.0, v201
	v_div_scale_f32 v202, s[84:85], v198, v198, v94
	v_div_scale_f32 v203, s[84:85], v199, v199, v95
	v_div_scale_f32 v204, s[84:85], v200, v200, v96
	v_div_scale_f32 v205, s[84:85], v201, v201, v97
	v_rcp_f32_e32 v206, v202
	v_rcp_f32_e32 v207, v203
	v_rcp_f32_e32 v208, v204
	v_rcp_f32_e32 v209, v205
	s_nop 0
	v_div_scale_f32 v210, vcc, v94, v198, v94
	v_fma_f32 v212, -v202, v206, 1.0
	v_fmac_f32_e32 v206, v212, v206
	v_mul_f32_e32 v211, v210, v206
	v_fma_f32 v212, -v202, v211, v210
	v_fmac_f32_e32 v211, v212, v206
	v_fma_f32 v212, -v202, v211, v210
	v_div_fmas_f32 v212, v212, v206, v211
	v_div_fixup_f32 v94, v212, v198, v94
	v_div_scale_f32 v210, vcc, v95, v199, v95
	v_fma_f32 v212, -v203, v207, 1.0
	v_fmac_f32_e32 v207, v212, v207
	v_mul_f32_e32 v211, v210, v207
	v_fma_f32 v212, -v203, v211, v210
	v_fmac_f32_e32 v211, v212, v207
	v_fma_f32 v212, -v203, v211, v210
	v_div_fmas_f32 v212, v212, v207, v211
	v_div_fixup_f32 v95, v212, v199, v95
	v_div_scale_f32 v210, vcc, v96, v200, v96
	v_fma_f32 v212, -v204, v208, 1.0
	v_fmac_f32_e32 v208, v212, v208
	v_mul_f32_e32 v211, v210, v208
	v_fma_f32 v212, -v204, v211, v210
	v_fmac_f32_e32 v211, v212, v208
	v_fma_f32 v212, -v204, v211, v210
	v_div_fmas_f32 v212, v212, v208, v211
	v_div_fixup_f32 v96, v212, v200, v96
	v_div_scale_f32 v210, vcc, v97, v201, v97
	v_fma_f32 v212, -v205, v209, 1.0
	v_fmac_f32_e32 v209, v212, v209
	v_mul_f32_e32 v211, v210, v209
	v_fma_f32 v212, -v205, v211, v210
	v_fmac_f32_e32 v211, v212, v209
	v_fma_f32 v212, -v205, v211, v210
	v_div_fmas_f32 v212, v212, v209, v211
	v_div_fixup_f32 v97, v212, v201, v97
	s_branch G1E_ph17_ST
G1E_ph17_U:
	s_load_dwordx2 s[82:83], s[0:1], 0x108
G1E_ph17_ST:
	v_and_b32_e32 v223, 31, v0
	v_mul_u32_u24_e32 v220, 0x110, v223
	v_bfe_u32 v223, v0, 5, 1
	v_lshl_add_u32 v220, v223, 4, v220
	v_bfe_u32 v224, v0, 6, 2
	v_mul_u32_u24_e32 v223, 0x2200, v224
	v_add_u32_e32 v220, v220, v223
	v_bfe_u32 v222, v0, 4, 2
	v_mul_u32_u24_e32 v221, 0x110, v222
	v_add_u32_e32 v221, v221, v223
	v_and_b32_e32 v223, 15, v0
	v_lshl_add_u32 v221, v223, 4, v221
	s_and_b32 s84, s35, 63
	s_mulk_i32 s84, 0xc0
	s_lshr_b32 s85, s35, 6
	s_and_b32 s85, s85, 7
	s_lshl_b32 s85, s85, 8
	v_lshrrev_b32_e32 v224, 1, v224
	v_mul_u32_u24_e32 v224, 0x60, v224
	v_add3_u32 v222, v222, v224, s84
	v_lshlrev_b32_e32 v222, 11, v222
	v_lshl_add_u32 v222, v223, 3, v222
	v_bfe_u32 v223, v0, 6, 1
	v_lshl_add_u32 v222, v223, 7, v222
	v_add_u32_e32 v222, s85, v222
	ds_write_b128 v220, v[82:85]
	ds_write_b128 v220, v[86:89] offset:32
	ds_write_b128 v220, v[90:93] offset:64
	ds_write_b128 v220, v[94:97] offset:96
	ds_write_b128 v220, v[66:69] offset:128
	ds_write_b128 v220, v[70:73] offset:160
	ds_write_b128 v220, v[74:77] offset:192
	ds_write_b128 v220, v[78:81] offset:224
	v_mov_b32_e32 v230, v222
	v_add_u32_e32 v231, 0x2000, v222
	v_add_u32_e32 v232, 0x4000, v222
	v_add_u32_e32 v233, 0x6000, v222
	v_add_u32_e32 v234, 0x8000, v222
	v_add_u32_e32 v235, 0xa000, v222
	v_add_u32_e32 v236, 0xc000, v222
	v_add_u32_e32 v237, 0xe000, v222
	s_waitcnt lgkmcnt(0)
	ds_read_b128 v[82:85], v221
	ds_read_b128 v[86:89], v221 offset:1088
	ds_read_b128 v[90:93], v221 offset:2176
	ds_read_b128 v[94:97], v221 offset:3264
	ds_read_b128 v[66:69], v221 offset:4352
	ds_read_b128 v[70:73], v221 offset:5440
	ds_read_b128 v[74:77], v221 offset:6528
	ds_read_b128 v[78:81], v221 offset:7616
	s_waitcnt lgkmcnt(7)
	v_cvt_pk_bf16_f32 v82, v82, v83
	v_cvt_pk_bf16_f32 v83, v84, v85
	global_store_dwordx2 v230, v[82:83], s[82:83]
	s_waitcnt lgkmcnt(6)
	v_cvt_pk_bf16_f32 v86, v86, v87
	v_cvt_pk_bf16_f32 v87, v88, v89
	global_store_dwordx2 v231, v[86:87], s[82:83]
	s_waitcnt lgkmcnt(5)
	v_cvt_pk_bf16_f32 v90, v90, v91
	v_cvt_pk_bf16_f32 v91, v92, v93
	global_store_dwordx2 v232, v[90:91], s[82:83]
	s_waitcnt lgkmcnt(4)
	v_cvt_pk_bf16_f32 v94, v94, v95
	v_cvt_pk_bf16_f32 v95, v96, v97
	global_store_dwordx2 v233, v[94:95], s[82:83]
	s_waitcnt lgkmcnt(3)
	v_cvt_pk_bf16_f32 v66, v66, v67
	v_cvt_pk_bf16_f32 v67, v68, v69
	global_store_dwordx2 v234, v[66:67], s[82:83]
	s_waitcnt lgkmcnt(2)
	v_cvt_pk_bf16_f32 v70, v70, v71
	v_cvt_pk_bf16_f32 v71, v72, v73
	global_store_dwordx2 v235, v[70:71], s[82:83]
	s_waitcnt lgkmcnt(1)
	v_cvt_pk_bf16_f32 v74, v74, v75
	v_cvt_pk_bf16_f32 v75, v76, v77
	global_store_dwordx2 v236, v[74:75], s[82:83]
	s_waitcnt lgkmcnt(0)
	v_cvt_pk_bf16_f32 v78, v78, v79
	v_cvt_pk_bf16_f32 v79, v80, v81
	global_store_dwordx2 v237, v[78:79], s[82:83]
	ds_write_b128 v220, v[50:53]
	ds_write_b128 v220, v[54:57] offset:32
	ds_write_b128 v220, v[58:61] offset:64
	ds_write_b128 v220, v[62:65] offset:96
	ds_write_b128 v220, v[34:37] offset:128
	ds_write_b128 v220, v[38:41] offset:160
	ds_write_b128 v220, v[42:45] offset:192
	ds_write_b128 v220, v[46:49] offset:224
	v_add_u32_e32 v230, 0x10000, v222
	v_add_u32_e32 v231, 0x12000, v222
	v_add_u32_e32 v232, 0x14000, v222
	v_add_u32_e32 v233, 0x16000, v222
	v_add_u32_e32 v234, 0x18000, v222
	v_add_u32_e32 v235, 0x1a000, v222
	v_add_u32_e32 v236, 0x1c000, v222
	v_add_u32_e32 v237, 0x1e000, v222
	s_waitcnt lgkmcnt(0)
	ds_read_b128 v[50:53], v221
	ds_read_b128 v[54:57], v221 offset:1088
	ds_read_b128 v[58:61], v221 offset:2176
	ds_read_b128 v[62:65], v221 offset:3264
	ds_read_b128 v[34:37], v221 offset:4352
	ds_read_b128 v[38:41], v221 offset:5440
	ds_read_b128 v[42:45], v221 offset:6528
	ds_read_b128 v[46:49], v221 offset:7616
	s_waitcnt lgkmcnt(7)
	v_cvt_pk_bf16_f32 v50, v50, v51
	v_cvt_pk_bf16_f32 v51, v52, v53
	global_store_dwordx2 v230, v[50:51], s[82:83]
	s_waitcnt lgkmcnt(6)
	v_cvt_pk_bf16_f32 v54, v54, v55
	v_cvt_pk_bf16_f32 v55, v56, v57
	global_store_dwordx2 v231, v[54:55], s[82:83]
	s_waitcnt lgkmcnt(5)
	v_cvt_pk_bf16_f32 v58, v58, v59
	v_cvt_pk_bf16_f32 v59, v60, v61
	global_store_dwordx2 v232, v[58:59], s[82:83]
	s_waitcnt lgkmcnt(4)
	v_cvt_pk_bf16_f32 v62, v62, v63
	v_cvt_pk_bf16_f32 v63, v64, v65
	global_store_dwordx2 v233, v[62:63], s[82:83]
	s_waitcnt lgkmcnt(3)
	v_cvt_pk_bf16_f32 v34, v34, v35
	v_cvt_pk_bf16_f32 v35, v36, v37
	global_store_dwordx2 v234, v[34:35], s[82:83]
	s_waitcnt lgkmcnt(2)
	v_cvt_pk_bf16_f32 v38, v38, v39
	v_cvt_pk_bf16_f32 v39, v40, v41
	global_store_dwordx2 v235, v[38:39], s[82:83]
	s_waitcnt lgkmcnt(1)
	v_cvt_pk_bf16_f32 v42, v42, v43
	v_cvt_pk_bf16_f32 v43, v44, v45
	global_store_dwordx2 v236, v[42:43], s[82:83]
	s_waitcnt lgkmcnt(0)
	v_cvt_pk_bf16_f32 v46, v46, v47
	v_cvt_pk_bf16_f32 v47, v48, v49
	global_store_dwordx2 v237, v[46:47], s[82:83]
	ds_write_b128 v220, v[18:21]
	ds_write_b128 v220, v[22:25] offset:32
	ds_write_b128 v220, v[26:29] offset:64
	ds_write_b128 v220, v[30:33] offset:96
	ds_write_b128 v220, v[2:5] offset:128
	ds_write_b128 v220, v[6:9] offset:160
	ds_write_b128 v220, v[10:13] offset:192
	ds_write_b128 v220, v[14:17] offset:224
	v_add_u32_e32 v230, 0x20000, v222
	v_add_u32_e32 v231, 0x22000, v222
	v_add_u32_e32 v232, 0x24000, v222
	v_add_u32_e32 v233, 0x26000, v222
	v_add_u32_e32 v234, 0x28000, v222
	v_add_u32_e32 v235, 0x2a000, v222
	v_add_u32_e32 v236, 0x2c000, v222
	v_add_u32_e32 v237, 0x2e000, v222
	s_waitcnt lgkmcnt(0)
	ds_read_b128 v[18:21], v221
	ds_read_b128 v[22:25], v221 offset:1088
	ds_read_b128 v[26:29], v221 offset:2176
	ds_read_b128 v[30:33], v221 offset:3264
	ds_read_b128 v[2:5], v221 offset:4352
	ds_read_b128 v[6:9], v221 offset:5440
	ds_read_b128 v[10:13], v221 offset:6528
	ds_read_b128 v[14:17], v221 offset:7616
	s_waitcnt lgkmcnt(7)
	v_cvt_pk_bf16_f32 v18, v18, v19
	v_cvt_pk_bf16_f32 v19, v20, v21
	global_store_dwordx2 v230, v[18:19], s[82:83]
	s_waitcnt lgkmcnt(6)
	v_cvt_pk_bf16_f32 v22, v22, v23
	v_cvt_pk_bf16_f32 v23, v24, v25
	global_store_dwordx2 v231, v[22:23], s[82:83]
	s_waitcnt lgkmcnt(5)
	v_cvt_pk_bf16_f32 v26, v26, v27
	v_cvt_pk_bf16_f32 v27, v28, v29
	global_store_dwordx2 v232, v[26:27], s[82:83]
	s_waitcnt lgkmcnt(4)
	v_cvt_pk_bf16_f32 v30, v30, v31
	v_cvt_pk_bf16_f32 v31, v32, v33
	global_store_dwordx2 v233, v[30:31], s[82:83]
	s_waitcnt lgkmcnt(3)
	v_cvt_pk_bf16_f32 v2, v2, v3
	v_cvt_pk_bf16_f32 v3, v4, v5
	global_store_dwordx2 v234, v[2:3], s[82:83]
	s_waitcnt lgkmcnt(2)
	v_cvt_pk_bf16_f32 v6, v6, v7
	v_cvt_pk_bf16_f32 v7, v8, v9
	global_store_dwordx2 v235, v[6:7], s[82:83]
	s_waitcnt lgkmcnt(1)
	v_cvt_pk_bf16_f32 v10, v10, v11
	v_cvt_pk_bf16_f32 v11, v12, v13
	global_store_dwordx2 v236, v[10:11], s[82:83]
	s_waitcnt lgkmcnt(0)
	v_cvt_pk_bf16_f32 v14, v14, v15
	v_cvt_pk_bf16_f32 v15, v16, v17
	global_store_dwordx2 v237, v[14:15], s[82:83]
	s_barrier
	s_mov_b64 s[4:5], exec
	s_branch .LBB0_1991
